# GEMM main loops: s_setprio flips around the MFMA segments removed (load segments no longer carry VALU work)
# speedup vs baseline: 1.0704x; 1.0022x over previous
; #define LDA(dst, b, h) for (int m = 0; m < 4; ++m) for (int k = 0; k < 2; ++k) \
;     dst[m][k] = *reinterpret_cast<const bf16x8*>((char*)SA(b, h) + a_thr + (m * 2 + k) * 1024)
; #define LDB(dst, b, h) for (int n = 0; n < 2; ++n) for (int k = 0; k < 2; ++k) \
;     dst[n][k] = *reinterpret_cast<const bf16x8*>((char*)SB(b, h) + b_thr + (n * 2 + k) * 1024)
; #define MMA(ai, bj, At, Btf) do { __builtin_amdgcn_s_setprio(1); \
;     for (int m = 0; m < 4; ++m) for (int n = 0; n < 2; ++n) for (int k = 0; k < 2; ++k) \
;       acc[ai][bj][m][n] = __builtin_amdgcn_mfma_f32_16x16x32_bf16(Btf[n][k], At[m][k], acc[ai][bj][m][n], 0, 0, 0); \
;     __builtin_amdgcn_s_setprio(0); } while (0)
; #define WAIT_V(n) asm volatile("s_waitcnt vmcnt(" #n ")" ::: "memory")
; #define WAIT_L(n) asm volatile("s_waitcnt lgkmcnt(" #n ")" ::: "memory")
; #define BAR __builtin_amdgcn_s_barrier()
; #define SCHED __builtin_amdgcn_sched_barrier(0)
; template <bool OVL, bool PANEL = false, class Epi>
; __device__ __forceinline__ void gemm_phase(const bf16_t* __restrict__ A, long lda, const bf16_t* __restrict__ Bt, long ldb, int nM, int nN, int K,
;                                            const Epi& epi, bf16_t* shm, int w0) {
;     ...
;     for (int t = 0; t < nt - 2; t += 2) {
;       LDB(B0, 0, 0); SCHED; LDA(At, 0, 0); STAGE(SA(1, 1), A, lda, aoff, brow + HALF, t + 1);
;       WAIT_L(8); BAR; WAIT_L(0); MMA(0, 0, At, B0); BAR; SCHED;
;       LDB(B1, 0, 1); STAGE(SB(0, 0), Bt, ldb, boff, bcol, t + 2);
;       BAR; WAIT_L(0); MMA(0, 1, At, B1); BAR;
;       LDA(At, 0, 1); STAGE(SA(0, 0), A, lda, aoff, brow, t + 2);
;       BAR; WAIT_L(0); MMA(1, 0, At, B0); BAR; SCHED;
;       STAGE(SB(0, 1), Bt, ldb, boff, bcol + HALF, t + 2);
;       WAIT_V(6); BAR; MMA(1, 1, At, B1); BAR;
.LBB0_125:
	ds_read_b128 v[138:141], v218
	ds_read_b128 v[142:145], v218 offset:1024
	ds_read_b128 v[146:149], v218 offset:2048
	ds_read_b128 v[150:153], v218 offset:3072
	s_add_u32 s8, s4, s6
	s_addc_u32 s9, s5, s7
	ds_read_b128 v[154:157], v213
	ds_read_b128 v[158:161], v213 offset:1024
	ds_read_b128 v[162:165], v213 offset:2048
	ds_read_b128 v[166:169], v213 offset:3072
	ds_read_b128 v[170:173], v213 offset:4096
	ds_read_b128 v[174:177], v213 offset:5120
	ds_read_b128 v[178:181], v213 offset:6144
	ds_read_b128 v[182:185], v213 offset:7168
	s_mov_b32 m0, s25
	s_add_u32 s98, s8, s14
	s_addc_u32 s99, s9, s15
	global_load_lds_dwordx4 v203, s[98:99]
	s_mov_b32 m0, s32
	s_add_u32 s98, s8, s16
	s_addc_u32 s99, s9, s17
	global_load_lds_dwordx4 v203, s[98:99]
	s_waitcnt lgkmcnt(8)
	s_waitcnt vmcnt(10)
	s_barrier
	s_waitcnt lgkmcnt(0)
	s_waitcnt lgkmcnt(0)
	v_mfma_f32_16x16x32_bf16 v[126:129], v[138:141], v[154:157], v[126:129]
	v_mfma_f32_16x16x32_bf16 v[122:125], v[146:149], v[154:157], v[122:125]
	v_mfma_f32_16x16x32_bf16 v[118:121], v[138:141], v[162:165], v[118:121]
	v_mfma_f32_16x16x32_bf16 v[114:117], v[146:149], v[162:165], v[114:117]
	v_mfma_f32_16x16x32_bf16 v[110:113], v[138:141], v[170:173], v[110:113]
	v_mfma_f32_16x16x32_bf16 v[106:109], v[146:149], v[170:173], v[106:109]
	v_mfma_f32_16x16x32_bf16 v[102:105], v[138:141], v[178:181], v[102:105]
	v_mfma_f32_16x16x32_bf16 v[98:101], v[146:149], v[178:181], v[98:101]
	v_mfma_f32_16x16x32_bf16 v[126:129], v[142:145], v[158:161], v[126:129]
	v_mfma_f32_16x16x32_bf16 v[122:125], v[150:153], v[158:161], v[122:125]
	v_mfma_f32_16x16x32_bf16 v[118:121], v[142:145], v[166:169], v[118:121]
	v_mfma_f32_16x16x32_bf16 v[114:117], v[150:153], v[166:169], v[114:117]
	v_mfma_f32_16x16x32_bf16 v[110:113], v[142:145], v[174:177], v[110:113]
	v_mfma_f32_16x16x32_bf16 v[106:109], v[150:153], v[174:177], v[106:109]
	v_mfma_f32_16x16x32_bf16 v[102:105], v[142:145], v[182:185], v[102:105]
	v_mfma_f32_16x16x32_bf16 v[98:101], v[150:153], v[182:185], v[98:101]
	s_barrier
	s_add_u32 vcc_lo, s0, s6
	ds_read_b128 v[186:189], v219
	ds_read_b128 v[190:193], v219 offset:1024
	ds_read_b128 v[194:197], v219 offset:2048
	ds_read_b128 v[198:201], v219 offset:3072
	s_addc_u32 vcc_hi, s1, s7
	s_mov_b32 m0, s44
	s_add_u32 s98, vcc_lo, s34
	s_addc_u32 s99, vcc_hi, s35
	global_load_lds_dwordx4 v203, s[98:99]
	s_mov_b32 m0, s45
	s_add_u32 s98, vcc_lo, s18
	s_addc_u32 s99, vcc_hi, s19
	global_load_lds_dwordx4 v203, s[98:99]
	s_waitcnt vmcnt(10)
	s_barrier
	s_waitcnt lgkmcnt(0)
	s_waitcnt lgkmcnt(0)
	v_mfma_f32_16x16x32_bf16 v[94:97], v[186:189], v[154:157], v[94:97]
	v_mfma_f32_16x16x32_bf16 v[90:93], v[194:197], v[154:157], v[90:93]
	v_mfma_f32_16x16x32_bf16 v[86:89], v[186:189], v[162:165], v[86:89]
	v_mfma_f32_16x16x32_bf16 v[82:85], v[194:197], v[162:165], v[82:85]
	v_mfma_f32_16x16x32_bf16 v[78:81], v[186:189], v[170:173], v[78:81]
	v_mfma_f32_16x16x32_bf16 v[74:77], v[194:197], v[170:173], v[74:77]
	v_mfma_f32_16x16x32_bf16 v[70:73], v[186:189], v[178:181], v[70:73]
	v_mfma_f32_16x16x32_bf16 v[66:69], v[194:197], v[178:181], v[66:69]
	v_mfma_f32_16x16x32_bf16 v[94:97], v[190:193], v[158:161], v[94:97]
	v_mfma_f32_16x16x32_bf16 v[90:93], v[198:201], v[158:161], v[90:93]
	v_mfma_f32_16x16x32_bf16 v[86:89], v[190:193], v[166:169], v[86:89]
	v_mfma_f32_16x16x32_bf16 v[82:85], v[198:201], v[166:169], v[82:85]
	v_mfma_f32_16x16x32_bf16 v[78:81], v[190:193], v[174:177], v[78:81]
	v_mfma_f32_16x16x32_bf16 v[74:77], v[198:201], v[174:177], v[74:77]
	v_mfma_f32_16x16x32_bf16 v[70:73], v[190:193], v[182:185], v[70:73]
	v_mfma_f32_16x16x32_bf16 v[66:69], v[198:201], v[182:185], v[66:69]
	s_barrier
	ds_read_b128 v[154:157], v213 offset:16384
	ds_read_b128 v[158:161], v213 offset:17408
	ds_read_b128 v[162:165], v213 offset:18432
	ds_read_b128 v[166:169], v213 offset:19456
	ds_read_b128 v[170:173], v213 offset:20480
	ds_read_b128 v[174:177], v213 offset:21504
	ds_read_b128 v[178:181], v213 offset:22528
	ds_read_b128 v[182:185], v213 offset:23552
	s_mov_b32 m0, s46
	s_add_u32 s98, s8, s34
	s_addc_u32 s99, s9, s35
	global_load_lds_dwordx4 v203, s[98:99]
	s_mov_b32 m0, s47
	s_add_u32 s98, s8, s18
	s_addc_u32 s99, s9, s19
	global_load_lds_dwordx4 v203, s[98:99]
	s_barrier
	s_waitcnt lgkmcnt(0)
	s_waitcnt lgkmcnt(0)
	v_mfma_f32_16x16x32_bf16 v[62:65], v[138:141], v[154:157], v[62:65]
	v_mfma_f32_16x16x32_bf16 v[58:61], v[146:149], v[154:157], v[58:61]
	v_mfma_f32_16x16x32_bf16 v[54:57], v[138:141], v[162:165], v[54:57]
	v_mfma_f32_16x16x32_bf16 v[50:53], v[146:149], v[162:165], v[50:53]
	v_mfma_f32_16x16x32_bf16 v[46:49], v[138:141], v[170:173], v[46:49]
	v_mfma_f32_16x16x32_bf16 v[42:45], v[146:149], v[170:173], v[42:45]
	v_mfma_f32_16x16x32_bf16 v[38:41], v[138:141], v[178:181], v[38:41]
	v_mfma_f32_16x16x32_bf16 v[34:37], v[146:149], v[178:181], v[34:37]
	v_mfma_f32_16x16x32_bf16 v[62:65], v[142:145], v[158:161], v[62:65]
	v_mfma_f32_16x16x32_bf16 v[58:61], v[150:153], v[158:161], v[58:61]
	v_mfma_f32_16x16x32_bf16 v[54:57], v[142:145], v[166:169], v[54:57]
	v_mfma_f32_16x16x32_bf16 v[50:53], v[150:153], v[166:169], v[50:53]
	v_mfma_f32_16x16x32_bf16 v[46:49], v[142:145], v[174:177], v[46:49]
	v_mfma_f32_16x16x32_bf16 v[42:45], v[150:153], v[174:177], v[42:45]
	v_mfma_f32_16x16x32_bf16 v[38:41], v[142:145], v[182:185], v[38:41]
	v_mfma_f32_16x16x32_bf16 v[34:37], v[150:153], v[182:185], v[34:37]
	s_barrier
	s_mov_b32 m0, s48
	s_add_u32 s98, vcc_lo, s30
	s_addc_u32 s99, vcc_hi, s31
	global_load_lds_dwordx4 v203, s[98:99]
	s_mov_b32 m0, s49
	s_add_u32 s98, vcc_lo, s40
	s_addc_u32 s99, vcc_hi, s41
	global_load_lds_dwordx4 v203, s[98:99]
	s_waitcnt vmcnt(10)
	s_barrier
; #define LDA(dst, b, h) for (int m = 0; m < 4; ++m) for (int k = 0; k < 2; ++k) \
;     dst[m][k] = *reinterpret_cast<const bf16x8*>((char*)SA(b, h) + a_thr + (m * 2 + k) * 1024)
; #define LDB(dst, b, h) for (int n = 0; n < 2; ++n) for (int k = 0; k < 2; ++k) \
;     dst[n][k] = *reinterpret_cast<const bf16x8*>((char*)SB(b, h) + b_thr + (n * 2 + k) * 1024)
; #define MMA(ai, bj, At, Btf) do { __builtin_amdgcn_s_setprio(1); \
;     for (int m = 0; m < 4; ++m) for (int n = 0; n < 2; ++n) for (int k = 0; k < 2; ++k) \
;       acc[ai][bj][m][n] = __builtin_amdgcn_mfma_f32_16x16x32_bf16(Btf[n][k], At[m][k], acc[ai][bj][m][n], 0, 0, 0); \
;     __builtin_amdgcn_s_setprio(0); } while (0)
; #define WAIT_V(n) asm volatile("s_waitcnt vmcnt(" #n ")" ::: "memory")
; #define WAIT_L(n) asm volatile("s_waitcnt lgkmcnt(" #n ")" ::: "memory")
; #define BAR __builtin_amdgcn_s_barrier()
; #define SCHED __builtin_amdgcn_sched_barrier(0)
; template <bool OVL, bool PANEL = false, class Epi>
; __device__ __forceinline__ void gemm_phase(const bf16_t* __restrict__ A, long lda, const bf16_t* __restrict__ Bt, long ldb, int nM, int nN, int K,
;                                            const Epi& epi, bf16_t* shm, int w0) {
;     ...
;       WAIT_V(6); BAR; MMA(1, 1, At, B1); BAR;
;       LDB(B0, 1, 0); SCHED; LDA(At, 1, 0); STAGE(SA(0, 1), A, lda, aoff, brow + HALF, t + 2);
;       WAIT_L(8); BAR; WAIT_L(0); MMA(0, 0, At, B0); BAR; SCHED;
;       LDB(B1, 1, 1); STAGE(SB(1, 0), Bt, ldb, boff, bcol, t + 3);
;       BAR; WAIT_L(0); MMA(0, 1, At, B1); BAR;
;       LDA(At, 1, 1); STAGE(SA(1, 0), A, lda, aoff, brow, t + 3);
	v_mfma_f32_16x16x32_bf16 v[30:33], v[186:189], v[154:157], v[30:33]
	v_mfma_f32_16x16x32_bf16 v[26:29], v[194:197], v[154:157], v[26:29]
	v_mfma_f32_16x16x32_bf16 v[22:25], v[186:189], v[162:165], v[22:25]
	v_mfma_f32_16x16x32_bf16 v[18:21], v[194:197], v[162:165], v[18:21]
	v_mfma_f32_16x16x32_bf16 v[14:17], v[186:189], v[170:173], v[14:17]
	v_mfma_f32_16x16x32_bf16 v[10:13], v[194:197], v[170:173], v[10:13]
	v_mfma_f32_16x16x32_bf16 v[6:9], v[186:189], v[178:181], v[6:9]
	v_mfma_f32_16x16x32_bf16 v[2:5], v[194:197], v[178:181], v[2:5]
	v_mfma_f32_16x16x32_bf16 v[30:33], v[190:193], v[158:161], v[30:33]
	v_mfma_f32_16x16x32_bf16 v[26:29], v[198:201], v[158:161], v[26:29]
	v_mfma_f32_16x16x32_bf16 v[22:25], v[190:193], v[166:169], v[22:25]
	v_mfma_f32_16x16x32_bf16 v[18:21], v[198:201], v[166:169], v[18:21]
	v_mfma_f32_16x16x32_bf16 v[14:17], v[190:193], v[174:177], v[14:17]
	v_mfma_f32_16x16x32_bf16 v[10:13], v[198:201], v[174:177], v[10:13]
	v_mfma_f32_16x16x32_bf16 v[6:9], v[190:193], v[182:185], v[6:9]
	v_mfma_f32_16x16x32_bf16 v[2:5], v[198:201], v[182:185], v[2:5]
	s_barrier
	ds_read_b128 v[138:141], v220
	ds_read_b128 v[142:145], v220 offset:1024
	ds_read_b128 v[146:149], v220 offset:2048
	ds_read_b128 v[150:153], v220 offset:3072
	ds_read_b128 v[154:157], v213 offset:32768
	ds_read_b128 v[158:161], v213 offset:33792
	ds_read_b128 v[162:165], v213 offset:34816
	ds_read_b128 v[166:169], v213 offset:35840
	ds_read_b128 v[170:173], v213 offset:36864
	ds_read_b128 v[174:177], v213 offset:37888
	ds_read_b128 v[178:181], v213 offset:38912
	ds_read_b128 v[182:185], v213 offset:39936
	s_mov_b32 m0, s50
	s_add_u32 s98, s8, s30
	s_addc_u32 s99, s9, s31
	global_load_lds_dwordx4 v203, s[98:99]
	s_mov_b32 m0, s51
	s_add_u32 s98, s8, s40
	s_addc_u32 s99, s9, s41
	global_load_lds_dwordx4 v203, s[98:99]
	s_waitcnt lgkmcnt(8)
	s_waitcnt vmcnt(10)
	s_barrier
	s_waitcnt lgkmcnt(0)
	s_waitcnt lgkmcnt(0)
	v_mfma_f32_16x16x32_bf16 v[126:129], v[138:141], v[154:157], v[126:129]
	v_mfma_f32_16x16x32_bf16 v[122:125], v[146:149], v[154:157], v[122:125]
	v_mfma_f32_16x16x32_bf16 v[118:121], v[138:141], v[162:165], v[118:121]
	v_mfma_f32_16x16x32_bf16 v[114:117], v[146:149], v[162:165], v[114:117]
	v_mfma_f32_16x16x32_bf16 v[110:113], v[138:141], v[170:173], v[110:113]
	v_mfma_f32_16x16x32_bf16 v[106:109], v[146:149], v[170:173], v[106:109]
	v_mfma_f32_16x16x32_bf16 v[102:105], v[138:141], v[178:181], v[102:105]
	v_mfma_f32_16x16x32_bf16 v[98:101], v[146:149], v[178:181], v[98:101]
	v_mfma_f32_16x16x32_bf16 v[126:129], v[142:145], v[158:161], v[126:129]
	v_mfma_f32_16x16x32_bf16 v[122:125], v[150:153], v[158:161], v[122:125]
	v_mfma_f32_16x16x32_bf16 v[118:121], v[142:145], v[166:169], v[118:121]
	v_mfma_f32_16x16x32_bf16 v[114:117], v[150:153], v[166:169], v[114:117]
	v_mfma_f32_16x16x32_bf16 v[110:113], v[142:145], v[174:177], v[110:113]
	v_mfma_f32_16x16x32_bf16 v[106:109], v[150:153], v[174:177], v[106:109]
	v_mfma_f32_16x16x32_bf16 v[102:105], v[142:145], v[182:185], v[102:105]
	v_mfma_f32_16x16x32_bf16 v[98:101], v[150:153], v[182:185], v[98:101]
	s_barrier
	ds_read_b128 v[186:189], v221
	ds_read_b128 v[190:193], v221 offset:1024
	ds_read_b128 v[194:197], v221 offset:2048
	ds_read_b128 v[198:201], v221 offset:3072
	s_mov_b32 m0, s52
	s_add_u32 s98, vcc_lo, s94
	s_addc_u32 s99, vcc_hi, s95
	global_load_lds_dwordx4 v203, s[98:99]
	s_mov_b32 m0, s53
	s_add_u32 s98, vcc_lo, s42
	s_addc_u32 s99, vcc_hi, s43
	global_load_lds_dwordx4 v203, s[98:99]
	s_waitcnt vmcnt(10)
	s_barrier
	s_waitcnt lgkmcnt(0)
	s_waitcnt lgkmcnt(0)
	v_mfma_f32_16x16x32_bf16 v[94:97], v[186:189], v[154:157], v[94:97]
	v_mfma_f32_16x16x32_bf16 v[90:93], v[194:197], v[154:157], v[90:93]
	v_mfma_f32_16x16x32_bf16 v[86:89], v[186:189], v[162:165], v[86:89]
	v_mfma_f32_16x16x32_bf16 v[82:85], v[194:197], v[162:165], v[82:85]
	v_mfma_f32_16x16x32_bf16 v[78:81], v[186:189], v[170:173], v[78:81]
	v_mfma_f32_16x16x32_bf16 v[74:77], v[194:197], v[170:173], v[74:77]
	v_mfma_f32_16x16x32_bf16 v[70:73], v[186:189], v[178:181], v[70:73]
	v_mfma_f32_16x16x32_bf16 v[66:69], v[194:197], v[178:181], v[66:69]
	v_mfma_f32_16x16x32_bf16 v[94:97], v[190:193], v[158:161], v[94:97]
	v_mfma_f32_16x16x32_bf16 v[90:93], v[198:201], v[158:161], v[90:93]
	v_mfma_f32_16x16x32_bf16 v[86:89], v[190:193], v[166:169], v[86:89]
	v_mfma_f32_16x16x32_bf16 v[82:85], v[198:201], v[166:169], v[82:85]
	v_mfma_f32_16x16x32_bf16 v[78:81], v[190:193], v[174:177], v[78:81]
	v_mfma_f32_16x16x32_bf16 v[74:77], v[198:201], v[174:177], v[74:77]
	v_mfma_f32_16x16x32_bf16 v[70:73], v[190:193], v[182:185], v[70:73]
	v_mfma_f32_16x16x32_bf16 v[66:69], v[198:201], v[182:185], v[66:69]
	s_barrier
	ds_read_b128 v[154:157], v213 offset:49152
	ds_read_b128 v[158:161], v213 offset:50176
	ds_read_b128 v[162:165], v213 offset:51200
	ds_read_b128 v[166:169], v213 offset:52224
	ds_read_b128 v[170:173], v213 offset:53248
	ds_read_b128 v[174:177], v213 offset:54272
	ds_read_b128 v[178:181], v213 offset:55296
	ds_read_b128 v[182:185], v213 offset:56320
	s_mov_b32 m0, s54
	s_add_u32 s98, s8, s94
	s_addc_u32 s99, s9, s95
	global_load_lds_dwordx4 v203, s[98:99]
	s_mov_b32 m0, s55
	s_add_u32 s98, s8, s42
	s_addc_u32 s99, s9, s43
	global_load_lds_dwordx4 v203, s[98:99]
	s_barrier
; #define LDA(dst, b, h) for (int m = 0; m < 4; ++m) for (int k = 0; k < 2; ++k) \
;     dst[m][k] = *reinterpret_cast<const bf16x8*>((char*)SA(b, h) + a_thr + (m * 2 + k) * 1024)
; #define LDB(dst, b, h) for (int n = 0; n < 2; ++n) for (int k = 0; k < 2; ++k) \
;     dst[n][k] = *reinterpret_cast<const bf16x8*>((char*)SB(b, h) + b_thr + (n * 2 + k) * 1024)
; #define MMA(ai, bj, At, Btf) do { __builtin_amdgcn_s_setprio(1); \
;     for (int m = 0; m < 4; ++m) for (int n = 0; n < 2; ++n) for (int k = 0; k < 2; ++k) \
;       acc[ai][bj][m][n] = __builtin_amdgcn_mfma_f32_16x16x32_bf16(Btf[n][k], At[m][k], acc[ai][bj][m][n], 0, 0, 0); \
;     __builtin_amdgcn_s_setprio(0); } while (0)
; #define WAIT_V(n) asm volatile("s_waitcnt vmcnt(" #n ")" ::: "memory")
; #define WAIT_L(n) asm volatile("s_waitcnt lgkmcnt(" #n ")" ::: "memory")
; #define BAR __builtin_amdgcn_s_barrier()
; #define SCHED __builtin_amdgcn_sched_barrier(0)
; template <bool OVL, bool PANEL = false, class Epi>
; __device__ __forceinline__ void gemm_phase(const bf16_t* __restrict__ A, long lda, const bf16_t* __restrict__ Bt, long ldb, int nM, int nN, int K,
;                                            const Epi& epi, bf16_t* shm, int w0) {
;     ...
;       BAR; WAIT_L(0); MMA(1, 0, At, B0); BAR; SCHED;
;       STAGE(SB(1, 1), Bt, ldb, boff, bcol + HALF, t + 3);
;       WAIT_V(6); BAR; MMA(1, 1, At, B1); BAR;
;     }
;     { LDB(B0, 0, 0); LDA(At, 0, 0); STAGE(SA(1, 1), A, lda, aoff, brow + HALF, nt - 1);
;       BAR; WAIT_L(0); MMA(0, 0, At, B0); BAR;
;       LDB(B1, 0, 1); BAR; WAIT_L(0); MMA(0, 1, At, B1); BAR;
	s_waitcnt lgkmcnt(0)
	s_waitcnt lgkmcnt(0)
	v_mfma_f32_16x16x32_bf16 v[62:65], v[138:141], v[154:157], v[62:65]
	v_mfma_f32_16x16x32_bf16 v[58:61], v[146:149], v[154:157], v[58:61]
	v_mfma_f32_16x16x32_bf16 v[54:57], v[138:141], v[162:165], v[54:57]
	v_mfma_f32_16x16x32_bf16 v[50:53], v[146:149], v[162:165], v[50:53]
	v_mfma_f32_16x16x32_bf16 v[46:49], v[138:141], v[170:173], v[46:49]
	v_mfma_f32_16x16x32_bf16 v[42:45], v[146:149], v[170:173], v[42:45]
	v_mfma_f32_16x16x32_bf16 v[38:41], v[138:141], v[178:181], v[38:41]
	v_mfma_f32_16x16x32_bf16 v[34:37], v[146:149], v[178:181], v[34:37]
	v_mfma_f32_16x16x32_bf16 v[62:65], v[142:145], v[158:161], v[62:65]
	v_mfma_f32_16x16x32_bf16 v[58:61], v[150:153], v[158:161], v[58:61]
	v_mfma_f32_16x16x32_bf16 v[54:57], v[142:145], v[166:169], v[54:57]
	v_mfma_f32_16x16x32_bf16 v[50:53], v[150:153], v[166:169], v[50:53]
	v_mfma_f32_16x16x32_bf16 v[46:49], v[142:145], v[174:177], v[46:49]
	v_mfma_f32_16x16x32_bf16 v[42:45], v[150:153], v[174:177], v[42:45]
	v_mfma_f32_16x16x32_bf16 v[38:41], v[142:145], v[182:185], v[38:41]
	v_mfma_f32_16x16x32_bf16 v[34:37], v[150:153], v[182:185], v[34:37]
	s_barrier
	s_mov_b64 s[8:9], 0xb0180
	s_mov_b64 s[8:9], 0x108180
	s_mov_b32 m0, s60
	s_add_u32 s98, vcc_lo, 0xb0180
	s_addc_u32 s99, vcc_hi, 0
	global_load_lds_dwordx4 v203, s[98:99]
	s_mov_b32 m0, s61
	s_add_u32 s98, vcc_lo, 0x108180
	s_addc_u32 s99, vcc_hi, 0
	global_load_lds_dwordx4 v203, s[98:99]
	s_waitcnt vmcnt(10)
	s_barrier
	v_mfma_f32_16x16x32_bf16 v[30:33], v[186:189], v[154:157], v[30:33]
	v_mfma_f32_16x16x32_bf16 v[26:29], v[194:197], v[154:157], v[26:29]
	v_mfma_f32_16x16x32_bf16 v[22:25], v[186:189], v[162:165], v[22:25]
	v_mfma_f32_16x16x32_bf16 v[18:21], v[194:197], v[162:165], v[18:21]
	v_mfma_f32_16x16x32_bf16 v[14:17], v[186:189], v[170:173], v[14:17]
	v_mfma_f32_16x16x32_bf16 v[10:13], v[194:197], v[170:173], v[10:13]
	v_mfma_f32_16x16x32_bf16 v[6:9], v[186:189], v[178:181], v[6:9]
	v_mfma_f32_16x16x32_bf16 v[2:5], v[194:197], v[178:181], v[2:5]
	v_mfma_f32_16x16x32_bf16 v[30:33], v[190:193], v[158:161], v[30:33]
	v_mfma_f32_16x16x32_bf16 v[26:29], v[198:201], v[158:161], v[26:29]
	v_mfma_f32_16x16x32_bf16 v[22:25], v[190:193], v[166:169], v[22:25]
	v_mfma_f32_16x16x32_bf16 v[18:21], v[198:201], v[166:169], v[18:21]
	v_mfma_f32_16x16x32_bf16 v[14:17], v[190:193], v[174:177], v[14:17]
	v_mfma_f32_16x16x32_bf16 v[10:13], v[198:201], v[174:177], v[10:13]
	v_mfma_f32_16x16x32_bf16 v[6:9], v[190:193], v[182:185], v[6:9]
	v_mfma_f32_16x16x32_bf16 v[2:5], v[198:201], v[182:185], v[2:5]
	s_add_i32 s2, s2, 2
	s_add_u32 s6, s6, 0x100
	s_addc_u32 s7, s7, 0
	s_cmp_gt_u32 s2, 39
	s_barrier
	s_cbranch_scc0 .LBB0_125
	s_waitcnt vmcnt(6)
	s_or_b32 s0, s28, 0x80
	s_mul_hi_i32 s1, s0, 0x1600
	s_mulk_i32 s0, 0x1600
	v_readlane_b32 s2, v250, 49
	v_add_u32_e32 v227, 16, v212
	s_add_u32 s0, s2, s0
	v_readlane_b32 s2, v250, 50
	v_add_u32_e32 v0, 0x10000, v227
	s_addc_u32 s1, s2, s1
	v_readfirstlane_b32 s2, v136
	ds_read_b128 v[130:133], v0
	ds_read_b128 v[138:141], v0 offset:1024
	ds_read_b128 v[142:145], v0 offset:2048
	ds_read_b128 v[146:149], v0 offset:3072
	ds_read_b128 v[150:153], v213
	ds_read_b128 v[154:157], v213 offset:1024
	ds_read_b128 v[158:161], v213 offset:2048
	ds_read_b128 v[162:165], v213 offset:3072
	ds_read_b128 v[166:169], v213 offset:4096
	ds_read_b128 v[170:173], v213 offset:5120
	ds_read_b128 v[174:177], v213 offset:6144
	ds_read_b128 v[178:181], v213 offset:7168
	v_mov_b32_e32 v0, v203
	s_mov_b32 m0, s2
	s_nop 0
	v_lshl_add_u64 v[134:135], s[0:1], 0, v[0:1]
	global_load_lds_dwordx4 v0, s[0:1]
	v_readfirstlane_b32 s0, v137
	v_lshl_add_u64 v[134:135], v[134:135], 0, s[26:27]
	s_mov_b32 m0, s0
	s_nop 0
	global_load_lds_dwordx4 v[134:135], off
	s_barrier
	s_waitcnt lgkmcnt(0)
	s_setprio 1
	s_waitcnt lgkmcnt(0)
	v_mfma_f32_16x16x32_bf16 v[126:129], v[130:133], v[150:153], v[126:129]
	v_mfma_f32_16x16x32_bf16 v[122:125], v[142:145], v[150:153], v[122:125]
	v_mfma_f32_16x16x32_bf16 v[118:121], v[130:133], v[158:161], v[118:121]
	v_mfma_f32_16x16x32_bf16 v[114:117], v[142:145], v[158:161], v[114:117]
	v_mfma_f32_16x16x32_bf16 v[110:113], v[130:133], v[166:169], v[110:113]
	v_mfma_f32_16x16x32_bf16 v[106:109], v[142:145], v[166:169], v[106:109]
	v_mfma_f32_16x16x32_bf16 v[102:105], v[130:133], v[174:177], v[102:105]
	v_mfma_f32_16x16x32_bf16 v[98:101], v[142:145], v[174:177], v[98:101]
	v_mfma_f32_16x16x32_bf16 v[126:129], v[138:141], v[154:157], v[126:129]
	v_mfma_f32_16x16x32_bf16 v[122:125], v[146:149], v[154:157], v[122:125]
	v_mfma_f32_16x16x32_bf16 v[118:121], v[138:141], v[162:165], v[118:121]
	v_mfma_f32_16x16x32_bf16 v[114:117], v[146:149], v[162:165], v[114:117]
	v_mfma_f32_16x16x32_bf16 v[110:113], v[138:141], v[170:173], v[110:113]
	v_mfma_f32_16x16x32_bf16 v[106:109], v[146:149], v[170:173], v[106:109]
	v_mfma_f32_16x16x32_bf16 v[102:105], v[138:141], v[178:181], v[102:105]
	v_mfma_f32_16x16x32_bf16 v[98:101], v[146:149], v[178:181], v[98:101]
	s_setprio 0
	v_add_u32_e32 v0, 0x14000, v227
	s_barrier
	ds_read_b128 v[134:137], v0
	ds_read_b128 v[182:185], v0 offset:1024
	ds_read_b128 v[186:189], v0 offset:2048
	ds_read_b128 v[190:193], v0 offset:3072
	s_barrier
; #define LDA(dst, b, h) for (int m = 0; m < 4; ++m) for (int k = 0; k < 2; ++k) \
;     dst[m][k] = *reinterpret_cast<const bf16x8*>((char*)SA(b, h) + a_thr + (m * 2 + k) * 1024)
; #define LDB(dst, b, h) for (int n = 0; n < 2; ++n) for (int k = 0; k < 2; ++k) \
;     dst[n][k] = *reinterpret_cast<const bf16x8*>((char*)SB(b, h) + b_thr + (n * 2 + k) * 1024)
; #define MMA(ai, bj, At, Btf) do { __builtin_amdgcn_s_setprio(1); \
;     for (int m = 0; m < 4; ++m) for (int n = 0; n < 2; ++n) for (int k = 0; k < 2; ++k) \
;       acc[ai][bj][m][n] = __builtin_amdgcn_mfma_f32_16x16x32_bf16(Btf[n][k], At[m][k], acc[ai][bj][m][n], 0, 0, 0); \
;     __builtin_amdgcn_s_setprio(0); } while (0)
; #define WAIT_V(n) asm volatile("s_waitcnt vmcnt(" #n ")" ::: "memory")
; #define WAIT_L(n) asm volatile("s_waitcnt lgkmcnt(" #n ")" ::: "memory")
; #define BAR __builtin_amdgcn_s_barrier()
; template <bool OVL, bool PANEL = false, class Epi>
; __device__ __forceinline__ void gemm_phase(const bf16_t* __restrict__ A, long lda, const bf16_t* __restrict__ Bt, long ldb, int nM, int nN, int K,
;                                            const Epi& epi, bf16_t* shm, int w0) {
;     ...
;       LDB(B1, 0, 1); BAR; WAIT_L(0); MMA(0, 1, At, B1); BAR;
;       LDA(At, 0, 1); WAIT_V(4); BAR; WAIT_L(0); MMA(1, 0, At, B0); MMA(1, 1, At, B1); BAR; }
;     { LDB(B0, 1, 0); LDA(At, 1, 0); WAIT_V(2); BAR; WAIT_L(0); MMA(0, 0, At, B0); BAR;
	s_waitcnt lgkmcnt(0)
	s_setprio 1
	s_waitcnt lgkmcnt(0)
	v_mfma_f32_16x16x32_bf16 v[94:97], v[134:137], v[150:153], v[94:97]
	v_mfma_f32_16x16x32_bf16 v[90:93], v[186:189], v[150:153], v[90:93]
	v_mfma_f32_16x16x32_bf16 v[86:89], v[134:137], v[158:161], v[86:89]
	v_mfma_f32_16x16x32_bf16 v[82:85], v[186:189], v[158:161], v[82:85]
	v_mfma_f32_16x16x32_bf16 v[78:81], v[134:137], v[166:169], v[78:81]
	v_mfma_f32_16x16x32_bf16 v[66:69], v[186:189], v[174:177], v[66:69]
	v_mfma_f32_16x16x32_bf16 v[94:97], v[182:185], v[154:157], v[94:97]
	v_mfma_f32_16x16x32_bf16 v[90:93], v[190:193], v[154:157], v[90:93]
	v_mfma_f32_16x16x32_bf16 v[86:89], v[182:185], v[162:165], v[86:89]
	v_mfma_f32_16x16x32_bf16 v[82:85], v[190:193], v[162:165], v[82:85]
	v_mfma_f32_16x16x32_bf16 v[78:81], v[182:185], v[170:173], v[78:81]
	v_mfma_f32_16x16x32_bf16 v[74:77], v[186:189], v[166:169], v[74:77]
	v_mfma_f32_16x16x32_bf16 v[70:73], v[134:137], v[174:177], v[70:73]
	v_mfma_f32_16x16x32_bf16 v[66:69], v[190:193], v[178:181], v[66:69]
	v_mfma_f32_16x16x32_bf16 v[150:153], v[190:193], v[170:173], v[74:77]
	v_mfma_f32_16x16x32_bf16 v[154:157], v[182:185], v[178:181], v[70:73]
	s_setprio 0
	s_barrier
	s_nop 2
	ds_read_b128 v[70:73], v213 offset:16384
	ds_read_b128 v[74:77], v213 offset:17408
	ds_read_b128 v[158:161], v213 offset:18432
	ds_read_b128 v[162:165], v213 offset:19456
	ds_read_b128 v[166:169], v213 offset:20480
	ds_read_b128 v[170:173], v213 offset:21504
	ds_read_b128 v[174:177], v213 offset:22528
	ds_read_b128 v[178:181], v213 offset:23552
	s_waitcnt vmcnt(4)
	s_barrier
	s_waitcnt lgkmcnt(0)
	s_setprio 1
	s_waitcnt lgkmcnt(0)
	v_mfma_f32_16x16x32_bf16 v[58:61], v[142:145], v[70:73], v[58:61]
	v_mfma_f32_16x16x32_bf16 v[54:57], v[130:133], v[158:161], v[54:57]
	v_mfma_f32_16x16x32_bf16 v[62:65], v[130:133], v[70:73], v[62:65]
	v_mfma_f32_16x16x32_bf16 v[58:61], v[146:149], v[74:77], v[58:61]
	v_mfma_f32_16x16x32_bf16 v[54:57], v[138:141], v[162:165], v[54:57]
	v_mfma_f32_16x16x32_bf16 v[50:53], v[142:145], v[158:161], v[50:53]
	v_mfma_f32_16x16x32_bf16 v[46:49], v[130:133], v[166:169], v[46:49]
	v_mfma_f32_16x16x32_bf16 v[42:45], v[142:145], v[166:169], v[42:45]
	v_mfma_f32_16x16x32_bf16 v[38:41], v[130:133], v[174:177], v[38:41]
	v_mfma_f32_16x16x32_bf16 v[34:37], v[142:145], v[174:177], v[34:37]
	v_mfma_f32_16x16x32_bf16 v[194:197], v[138:141], v[74:77], v[62:65]
	v_mfma_f32_16x16x32_bf16 v[198:201], v[146:149], v[162:165], v[50:53]
	v_mfma_f32_16x16x32_bf16 v[214:217], v[138:141], v[170:173], v[46:49]
	v_mfma_f32_16x16x32_bf16 v[218:221], v[146:149], v[170:173], v[42:45]
	v_mfma_f32_16x16x32_bf16 v[130:133], v[138:141], v[178:181], v[38:41]
	v_mfma_f32_16x16x32_bf16 v[138:141], v[146:149], v[178:181], v[34:37]
	s_setprio 0
	s_setprio 1
	v_mfma_f32_16x16x32_bf16 v[30:33], v[134:137], v[70:73], v[30:33]
	v_mfma_f32_16x16x32_bf16 v[26:29], v[186:189], v[70:73], v[26:29]
	v_mfma_f32_16x16x32_bf16 v[22:25], v[134:137], v[158:161], v[22:25]
	v_mfma_f32_16x16x32_bf16 v[18:21], v[186:189], v[158:161], v[18:21]
	v_mfma_f32_16x16x32_bf16 v[14:17], v[134:137], v[166:169], v[14:17]
	v_mfma_f32_16x16x32_bf16 v[10:13], v[186:189], v[166:169], v[10:13]
	v_mfma_f32_16x16x32_bf16 v[6:9], v[134:137], v[174:177], v[6:9]
	v_mfma_f32_16x16x32_bf16 v[2:5], v[186:189], v[174:177], v[2:5]
	v_mfma_f32_16x16x32_bf16 v[142:145], v[182:185], v[74:77], v[30:33]
	v_mfma_f32_16x16x32_bf16 v[146:149], v[190:193], v[74:77], v[26:29]
	v_mfma_f32_16x16x32_bf16 v[222:225], v[182:185], v[162:165], v[22:25]
	v_mfma_f32_16x16x32_bf16 v[158:161], v[190:193], v[162:165], v[18:21]
	v_mfma_f32_16x16x32_bf16 v[162:165], v[182:185], v[170:173], v[14:17]
	v_mfma_f32_16x16x32_bf16 v[166:169], v[190:193], v[170:173], v[10:13]
	v_mfma_f32_16x16x32_bf16 v[134:137], v[182:185], v[178:181], v[6:9]
	v_mfma_f32_16x16x32_bf16 v[170:173], v[190:193], v[178:181], v[2:5]
	s_setprio 0
	v_add_u32_e32 v0, 0x18000, v227
	s_barrier
	ds_read_b128 v[34:37], v0
	ds_read_b128 v[174:177], v0 offset:1024
	ds_read_b128 v[178:181], v0 offset:2048
	ds_read_b128 v[182:185], v0 offset:3072
	ds_read_b128 v[18:21], v213 offset:32768
	ds_read_b128 v[22:25], v213 offset:33792
	ds_read_b128 v[26:29], v213 offset:34816
	ds_read_b128 v[50:53], v213 offset:35840
	ds_read_b128 v[186:189], v213 offset:36864
	ds_read_b128 v[190:193], v213 offset:37888
	ds_read_b128 v[228:231], v213 offset:38912
	ds_read_b128 v[232:235], v213 offset:39936
	s_waitcnt vmcnt(2)
	s_barrier
; #define LDA(dst, b, h) for (int m = 0; m < 4; ++m) for (int k = 0; k < 2; ++k) \
;     dst[m][k] = *reinterpret_cast<const bf16x8*>((char*)SA(b, h) + a_thr + (m * 2 + k) * 1024)
; #define LDB(dst, b, h) for (int n = 0; n < 2; ++n) for (int k = 0; k < 2; ++k) \
;     dst[n][k] = *reinterpret_cast<const bf16x8*>((char*)SB(b, h) + b_thr + (n * 2 + k) * 1024)
; #define MMA(ai, bj, At, Btf) do { __builtin_amdgcn_s_setprio(1); \
;     for (int m = 0; m < 4; ++m) for (int n = 0; n < 2; ++n) for (int k = 0; k < 2; ++k) \
;       acc[ai][bj][m][n] = __builtin_amdgcn_mfma_f32_16x16x32_bf16(Btf[n][k], At[m][k], acc[ai][bj][m][n], 0, 0, 0); \
;     __builtin_amdgcn_s_setprio(0); } while (0)
; #define WAIT_V(n) asm volatile("s_waitcnt vmcnt(" #n ")" ::: "memory")
; #define WAIT_L(n) asm volatile("s_waitcnt lgkmcnt(" #n ")" ::: "memory")
; #define BAR __builtin_amdgcn_s_barrier()
; template <bool OVL, bool PANEL = false, class Epi>
; __device__ __forceinline__ void gemm_phase(const bf16_t* __restrict__ A, long lda, const bf16_t* __restrict__ Bt, long ldb, int nM, int nN, int K,
;                                            const Epi& epi, bf16_t* shm, int w0) {
;     ...
;     { LDB(B0, 1, 0); LDA(At, 1, 0); WAIT_V(2); BAR; WAIT_L(0); MMA(0, 0, At, B0); BAR;
;       LDB(B1, 1, 1); WAIT_V(0); BAR; WAIT_L(0); MMA(0, 1, At, B1); BAR;
;       LDA(At, 1, 1); BAR; WAIT_L(0); MMA(1, 0, At, B0); MMA(1, 1, At, B1); BAR; }
;     if (wr == 0) BAR;
	s_waitcnt lgkmcnt(0)
	s_setprio 1
	s_waitcnt lgkmcnt(0)
	v_mfma_f32_16x16x32_bf16 v[6:9], v[178:181], v[18:21], v[122:125]
	v_mfma_f32_16x16x32_bf16 v[10:13], v[178:181], v[26:29], v[114:117]
	v_mfma_f32_16x16x32_bf16 v[14:17], v[178:181], v[186:189], v[106:109]
	v_mfma_f32_16x16x32_bf16 v[2:5], v[34:37], v[18:21], v[126:129]
	v_mfma_f32_16x16x32_bf16 v[30:33], v[182:185], v[22:25], v[6:9]
	v_mfma_f32_16x16x32_bf16 v[6:9], v[34:37], v[26:29], v[118:121]
	v_mfma_f32_16x16x32_bf16 v[38:41], v[182:185], v[50:53], v[10:13]
	v_mfma_f32_16x16x32_bf16 v[10:13], v[34:37], v[186:189], v[110:113]
	v_mfma_f32_16x16x32_bf16 v[42:45], v[182:185], v[190:193], v[14:17]
	v_mfma_f32_16x16x32_bf16 v[14:17], v[34:37], v[228:231], v[102:105]
	v_mfma_f32_16x16x32_bf16 v[46:49], v[178:181], v[228:231], v[98:101]
	v_mfma_f32_16x16x32_bf16 v[2:5], v[174:177], v[22:25], v[2:5]
	v_mfma_f32_16x16x32_bf16 v[6:9], v[174:177], v[50:53], v[6:9]
	v_mfma_f32_16x16x32_bf16 v[10:13], v[174:177], v[190:193], v[10:13]
	v_mfma_f32_16x16x32_bf16 v[14:17], v[174:177], v[232:235], v[14:17]
	v_mfma_f32_16x16x32_bf16 v[46:49], v[182:185], v[232:235], v[46:49]
	s_setprio 0
	v_add_u32_e32 v0, 0x1c000, v227
	s_barrier
	ds_read_b128 v[102:105], v0
	ds_read_b128 v[236:239], v0 offset:1024
	ds_read_b128 v[240:243], v0 offset:2048
	ds_read_b128 v[244:247], v0 offset:3072
	s_waitcnt vmcnt(0)
	s_barrier
	s_waitcnt lgkmcnt(0)
	s_setprio 1
	s_waitcnt lgkmcnt(0)
	v_mfma_f32_16x16x32_bf16 v[62:65], v[102:105], v[18:21], v[94:97]
	v_mfma_f32_16x16x32_bf16 v[18:21], v[240:243], v[18:21], v[90:93]
	v_mfma_f32_16x16x32_bf16 v[98:101], v[244:247], v[22:25], v[18:21]
	v_mfma_f32_16x16x32_bf16 v[18:21], v[102:105], v[26:29], v[86:89]
	v_mfma_f32_16x16x32_bf16 v[70:73], v[236:239], v[50:53], v[18:21]
	v_mfma_f32_16x16x32_bf16 v[18:21], v[240:243], v[26:29], v[82:85]
	v_mfma_f32_16x16x32_bf16 v[106:109], v[244:247], v[50:53], v[18:21]
	v_mfma_f32_16x16x32_bf16 v[18:21], v[102:105], v[186:189], v[78:81]
	v_mfma_f32_16x16x32_bf16 v[74:77], v[236:239], v[190:193], v[18:21]
	v_mfma_f32_16x16x32_bf16 v[18:21], v[240:243], v[186:189], v[150:153]
	v_mfma_f32_16x16x32_bf16 v[110:113], v[244:247], v[190:193], v[18:21]
	v_mfma_f32_16x16x32_bf16 v[18:21], v[102:105], v[228:231], v[154:157]
	v_mfma_f32_16x16x32_bf16 v[78:81], v[236:239], v[232:235], v[18:21]
	v_mfma_f32_16x16x32_bf16 v[18:21], v[240:243], v[228:231], v[66:69]
	v_mfma_f32_16x16x32_bf16 v[62:65], v[236:239], v[22:25], v[62:65]
	v_mfma_f32_16x16x32_bf16 v[114:117], v[244:247], v[232:235], v[18:21]
	s_setprio 0
	s_barrier
	ds_read_b128 v[86:89], v213 offset:49152
	ds_read_b128 v[90:93], v213 offset:50176
	ds_read_b128 v[94:97], v213 offset:51200
	ds_read_b128 v[118:121], v213 offset:52224
	ds_read_b128 v[150:153], v213 offset:53248
	ds_read_b128 v[154:157], v213 offset:54272
	ds_read_b128 v[186:189], v213 offset:55296
	ds_read_b128 v[190:193], v213 offset:56320
	s_barrier
	s_waitcnt lgkmcnt(0)
	s_setprio 1
	s_waitcnt lgkmcnt(0)
	v_mfma_f32_16x16x32_bf16 v[22:25], v[178:181], v[86:89], v[58:61]
	v_mfma_f32_16x16x32_bf16 v[26:29], v[178:181], v[94:97], v[198:201]
	v_mfma_f32_16x16x32_bf16 v[18:21], v[34:37], v[86:89], v[194:197]
	v_mfma_f32_16x16x32_bf16 v[50:53], v[182:185], v[90:93], v[22:25]
	v_mfma_f32_16x16x32_bf16 v[22:25], v[34:37], v[94:97], v[54:57]
	v_mfma_f32_16x16x32_bf16 v[54:57], v[182:185], v[118:121], v[26:29]
	v_mfma_f32_16x16x32_bf16 v[26:29], v[34:37], v[150:153], v[214:217]
	v_mfma_f32_16x16x32_bf16 v[58:61], v[178:181], v[150:153], v[218:221]
	v_mfma_f32_16x16x32_bf16 v[34:37], v[34:37], v[186:189], v[130:133]
	v_mfma_f32_16x16x32_bf16 v[66:69], v[178:181], v[186:189], v[138:141]
	v_mfma_f32_16x16x32_bf16 v[18:21], v[174:177], v[90:93], v[18:21]
	v_mfma_f32_16x16x32_bf16 v[22:25], v[174:177], v[118:121], v[22:25]
	v_mfma_f32_16x16x32_bf16 v[26:29], v[174:177], v[154:157], v[26:29]
	v_mfma_f32_16x16x32_bf16 v[58:61], v[182:185], v[154:157], v[58:61]
	v_mfma_f32_16x16x32_bf16 v[34:37], v[174:177], v[190:193], v[34:37]
	v_mfma_f32_16x16x32_bf16 v[66:69], v[182:185], v[190:193], v[66:69]
	s_setprio 0
	s_setprio 1
	v_mfma_f32_16x16x32_bf16 v[82:85], v[102:105], v[86:89], v[142:145]
	v_mfma_f32_16x16x32_bf16 v[86:89], v[240:243], v[86:89], v[146:149]
	v_mfma_f32_16x16x32_bf16 v[82:85], v[236:239], v[90:93], v[82:85]
	v_mfma_f32_16x16x32_bf16 v[122:125], v[244:247], v[90:93], v[86:89]
	v_mfma_f32_16x16x32_bf16 v[86:89], v[102:105], v[94:97], v[222:225]
	v_mfma_f32_16x16x32_bf16 v[90:93], v[240:243], v[94:97], v[158:161]
	v_mfma_f32_16x16x32_bf16 v[94:97], v[240:243], v[150:153], v[166:169]
	v_mfma_f32_16x16x32_bf16 v[86:89], v[236:239], v[118:121], v[86:89]
	v_mfma_f32_16x16x32_bf16 v[126:129], v[244:247], v[118:121], v[90:93]
	v_mfma_f32_16x16x32_bf16 v[118:121], v[244:247], v[154:157], v[94:97]
	v_mfma_f32_16x16x32_bf16 v[94:97], v[102:105], v[186:189], v[134:137]
	v_mfma_f32_16x16x32_bf16 v[90:93], v[102:105], v[150:153], v[162:165]
	v_mfma_f32_16x16x32_bf16 v[102:105], v[236:239], v[190:193], v[94:97]
	v_mfma_f32_16x16x32_bf16 v[94:97], v[240:243], v[186:189], v[170:173]
	v_mfma_f32_16x16x32_bf16 v[90:93], v[236:239], v[154:157], v[90:93]
	v_mfma_f32_16x16x32_bf16 v[94:97], v[244:247], v[190:193], v[94:97]
	s_setprio 0
	s_barrier
	s_and_saveexec_b64 s[0:1], s[58:59]
	s_cbranch_execz .LBB0_128
	s_barrier

; #define LDA(dst, b, h) for (int m = 0; m < 4; ++m) for (int k = 0; k < 2; ++k) \
;     dst[m][k] = *reinterpret_cast<const bf16x8*>((char*)SA(b, h) + a_thr + (m * 2 + k) * 1024)
; #define LDB(dst, b, h) for (int n = 0; n < 2; ++n) for (int k = 0; k < 2; ++k) \
;     dst[n][k] = *reinterpret_cast<const bf16x8*>((char*)SB(b, h) + b_thr + (n * 2 + k) * 1024)
; #define MMA(ai, bj, At, Btf) do { __builtin_amdgcn_s_setprio(1); \
;     for (int m = 0; m < 4; ++m) for (int n = 0; n < 2; ++n) for (int k = 0; k < 2; ++k) \
;       acc[ai][bj][m][n] = __builtin_amdgcn_mfma_f32_16x16x32_bf16(Btf[n][k], At[m][k], acc[ai][bj][m][n], 0, 0, 0); \
;     __builtin_amdgcn_s_setprio(0); } while (0)
; #define WAIT_V(n) asm volatile("s_waitcnt vmcnt(" #n ")" ::: "memory")
; #define WAIT_L(n) asm volatile("s_waitcnt lgkmcnt(" #n ")" ::: "memory")
; #define BAR __builtin_amdgcn_s_barrier()
; #define SCHED __builtin_amdgcn_sched_barrier(0)
; template <bool OVL, bool PANEL = false, class Epi>
; __device__ __forceinline__ void gemm_phase(const bf16_t* __restrict__ A, long lda, const bf16_t* __restrict__ Bt, long ldb, int nM, int nN, int K,
;                                            const Epi& epi, bf16_t* shm, int w0) {
;     ...
;     for (int t = 0; t < nt - 2; t += 2) {
;       LDB(B0, 0, 0); SCHED; LDA(At, 0, 0); STAGE(SA(1, 1), A, lda, aoff, brow + HALF, t + 1);
;       WAIT_L(8); BAR; WAIT_L(0); MMA(0, 0, At, B0); BAR; SCHED;
;       LDB(B1, 0, 1); STAGE(SB(0, 0), Bt, ldb, boff, bcol, t + 2);
;       BAR; WAIT_L(0); MMA(0, 1, At, B1); BAR;
;       LDA(At, 0, 1); STAGE(SA(0, 0), A, lda, aoff, brow, t + 2);
;       BAR; WAIT_L(0); MMA(1, 0, At, B0); BAR; SCHED;
;       STAGE(SB(0, 1), Bt, ldb, boff, bcol + HALF, t + 2);
;       WAIT_V(6); BAR; MMA(1, 1, At, B1); BAR;
.LBB0_386:
	ds_read_b128 v[150:153], v218
	ds_read_b128 v[154:157], v218 offset:1024
	ds_read_b128 v[158:161], v218 offset:2048
	ds_read_b128 v[162:165], v218 offset:3072
	s_add_u32 s42, s10, vcc_lo
	s_addc_u32 s43, s11, vcc_hi
	ds_read_b128 v[166:169], v141
	ds_read_b128 v[170:173], v141 offset:1024
	ds_read_b128 v[174:177], v141 offset:2048
	ds_read_b128 v[178:181], v141 offset:3072
	ds_read_b128 v[182:185], v141 offset:4096
	ds_read_b128 v[186:189], v141 offset:5120
	ds_read_b128 v[190:193], v141 offset:6144
	ds_read_b128 v[194:197], v141 offset:7168
	s_mov_b32 m0, s16
	s_add_u32 s98, s42, s28
	s_addc_u32 s99, s43, s29
	global_load_lds_dwordx4 v131, s[98:99]
	s_mov_b32 m0, s32
	s_add_u32 s98, s42, s36
	s_addc_u32 s99, s43, s37
	global_load_lds_dwordx4 v131, s[98:99]
	s_waitcnt lgkmcnt(8)
	s_waitcnt vmcnt(10)
	s_barrier
	s_waitcnt lgkmcnt(0)
	s_waitcnt lgkmcnt(0)
	v_mfma_f32_16x16x32_bf16 v[126:129], v[150:153], v[166:169], v[126:129]
	v_mfma_f32_16x16x32_bf16 v[122:125], v[158:161], v[166:169], v[122:125]
	v_mfma_f32_16x16x32_bf16 v[118:121], v[150:153], v[174:177], v[118:121]
	v_mfma_f32_16x16x32_bf16 v[114:117], v[158:161], v[174:177], v[114:117]
	v_mfma_f32_16x16x32_bf16 v[110:113], v[150:153], v[182:185], v[110:113]
	v_mfma_f32_16x16x32_bf16 v[106:109], v[158:161], v[182:185], v[106:109]
	v_mfma_f32_16x16x32_bf16 v[102:105], v[150:153], v[190:193], v[102:105]
	v_mfma_f32_16x16x32_bf16 v[98:101], v[158:161], v[190:193], v[98:101]
	v_mfma_f32_16x16x32_bf16 v[126:129], v[154:157], v[170:173], v[126:129]
	v_mfma_f32_16x16x32_bf16 v[122:125], v[162:165], v[170:173], v[122:125]
	v_mfma_f32_16x16x32_bf16 v[118:121], v[154:157], v[178:181], v[118:121]
	v_mfma_f32_16x16x32_bf16 v[114:117], v[162:165], v[178:181], v[114:117]
	v_mfma_f32_16x16x32_bf16 v[110:113], v[154:157], v[186:189], v[110:113]
	v_mfma_f32_16x16x32_bf16 v[106:109], v[162:165], v[186:189], v[106:109]
	v_mfma_f32_16x16x32_bf16 v[102:105], v[154:157], v[194:197], v[102:105]
	v_mfma_f32_16x16x32_bf16 v[98:101], v[162:165], v[194:197], v[98:101]
	s_barrier
	s_add_u32 s66, s8, vcc_lo
	ds_read_b128 v[198:201], v219
	ds_read_b128 v[202:205], v219 offset:1024
	ds_read_b128 v[206:209], v219 offset:2048
	ds_read_b128 v[210:213], v219 offset:3072
	s_addc_u32 s67, s9, vcc_hi
	s_mov_b32 m0, s46
	s_add_u32 s98, s66, s34
	s_addc_u32 s99, s67, s35
	global_load_lds_dwordx4 v131, s[98:99]
	s_mov_b32 m0, s47
	s_add_u32 s98, s66, s64
	s_addc_u32 s99, s67, s65
	global_load_lds_dwordx4 v131, s[98:99]
	s_waitcnt vmcnt(10)
	s_barrier
	s_waitcnt lgkmcnt(0)
	s_waitcnt lgkmcnt(0)
	v_mfma_f32_16x16x32_bf16 v[94:97], v[198:201], v[166:169], v[94:97]
	v_mfma_f32_16x16x32_bf16 v[90:93], v[206:209], v[166:169], v[90:93]
	v_mfma_f32_16x16x32_bf16 v[86:89], v[198:201], v[174:177], v[86:89]
	v_mfma_f32_16x16x32_bf16 v[82:85], v[206:209], v[174:177], v[82:85]
	v_mfma_f32_16x16x32_bf16 v[78:81], v[198:201], v[182:185], v[78:81]
	v_mfma_f32_16x16x32_bf16 v[74:77], v[206:209], v[182:185], v[74:77]
	v_mfma_f32_16x16x32_bf16 v[70:73], v[198:201], v[190:193], v[70:73]
	v_mfma_f32_16x16x32_bf16 v[66:69], v[206:209], v[190:193], v[66:69]
	v_mfma_f32_16x16x32_bf16 v[94:97], v[202:205], v[170:173], v[94:97]
	v_mfma_f32_16x16x32_bf16 v[90:93], v[210:213], v[170:173], v[90:93]
	v_mfma_f32_16x16x32_bf16 v[86:89], v[202:205], v[178:181], v[86:89]
	v_mfma_f32_16x16x32_bf16 v[82:85], v[210:213], v[178:181], v[82:85]
	v_mfma_f32_16x16x32_bf16 v[78:81], v[202:205], v[186:189], v[78:81]
	v_mfma_f32_16x16x32_bf16 v[74:77], v[210:213], v[186:189], v[74:77]
	v_mfma_f32_16x16x32_bf16 v[70:73], v[202:205], v[194:197], v[70:73]
	v_mfma_f32_16x16x32_bf16 v[66:69], v[210:213], v[194:197], v[66:69]
	s_barrier
	ds_read_b128 v[166:169], v141 offset:16384
	ds_read_b128 v[170:173], v141 offset:17408
	ds_read_b128 v[174:177], v141 offset:18432
	ds_read_b128 v[178:181], v141 offset:19456
	ds_read_b128 v[182:185], v141 offset:20480
	ds_read_b128 v[186:189], v141 offset:21504
	ds_read_b128 v[190:193], v141 offset:22528
	ds_read_b128 v[194:197], v141 offset:23552
	s_mov_b32 m0, s48
	s_add_u32 s98, s42, s34
	s_addc_u32 s99, s43, s35
	global_load_lds_dwordx4 v131, s[98:99]
	s_mov_b32 m0, s49
	s_add_u32 s98, s42, s64
	s_addc_u32 s99, s43, s65
	global_load_lds_dwordx4 v131, s[98:99]
	s_barrier
	s_waitcnt lgkmcnt(0)
	s_waitcnt lgkmcnt(0)
	v_mfma_f32_16x16x32_bf16 v[62:65], v[150:153], v[166:169], v[62:65]
	v_mfma_f32_16x16x32_bf16 v[58:61], v[158:161], v[166:169], v[58:61]
	v_mfma_f32_16x16x32_bf16 v[54:57], v[150:153], v[174:177], v[54:57]
	v_mfma_f32_16x16x32_bf16 v[50:53], v[158:161], v[174:177], v[50:53]
	v_mfma_f32_16x16x32_bf16 v[46:49], v[150:153], v[182:185], v[46:49]
	v_mfma_f32_16x16x32_bf16 v[42:45], v[158:161], v[182:185], v[42:45]
	v_mfma_f32_16x16x32_bf16 v[38:41], v[150:153], v[190:193], v[38:41]
	v_mfma_f32_16x16x32_bf16 v[34:37], v[158:161], v[190:193], v[34:37]
	v_mfma_f32_16x16x32_bf16 v[62:65], v[154:157], v[170:173], v[62:65]
	v_mfma_f32_16x16x32_bf16 v[58:61], v[162:165], v[170:173], v[58:61]
	v_mfma_f32_16x16x32_bf16 v[54:57], v[154:157], v[178:181], v[54:57]
	v_mfma_f32_16x16x32_bf16 v[50:53], v[162:165], v[178:181], v[50:53]
	v_mfma_f32_16x16x32_bf16 v[46:49], v[154:157], v[186:189], v[46:49]
	v_mfma_f32_16x16x32_bf16 v[42:45], v[162:165], v[186:189], v[42:45]
	v_mfma_f32_16x16x32_bf16 v[38:41], v[154:157], v[194:197], v[38:41]
	v_mfma_f32_16x16x32_bf16 v[34:37], v[162:165], v[194:197], v[34:37]
	s_barrier
	s_mov_b32 m0, s50
	s_add_u32 s98, s66, s68
	s_addc_u32 s99, s67, s69
	global_load_lds_dwordx4 v131, s[98:99]
	s_mov_b32 m0, s51
	s_add_u32 s98, s66, s70
	s_addc_u32 s99, s67, s71
	global_load_lds_dwordx4 v131, s[98:99]
	s_waitcnt vmcnt(10)
	s_barrier
; #define LDA(dst, b, h) for (int m = 0; m < 4; ++m) for (int k = 0; k < 2; ++k) \
;     dst[m][k] = *reinterpret_cast<const bf16x8*>((char*)SA(b, h) + a_thr + (m * 2 + k) * 1024)
; #define LDB(dst, b, h) for (int n = 0; n < 2; ++n) for (int k = 0; k < 2; ++k) \
;     dst[n][k] = *reinterpret_cast<const bf16x8*>((char*)SB(b, h) + b_thr + (n * 2 + k) * 1024)
; #define MMA(ai, bj, At, Btf) do { __builtin_amdgcn_s_setprio(1); \
;     for (int m = 0; m < 4; ++m) for (int n = 0; n < 2; ++n) for (int k = 0; k < 2; ++k) \
;       acc[ai][bj][m][n] = __builtin_amdgcn_mfma_f32_16x16x32_bf16(Btf[n][k], At[m][k], acc[ai][bj][m][n], 0, 0, 0); \
;     __builtin_amdgcn_s_setprio(0); } while (0)
; #define WAIT_V(n) asm volatile("s_waitcnt vmcnt(" #n ")" ::: "memory")
; #define WAIT_L(n) asm volatile("s_waitcnt lgkmcnt(" #n ")" ::: "memory")
; #define BAR __builtin_amdgcn_s_barrier()
; #define SCHED __builtin_amdgcn_sched_barrier(0)
; template <bool OVL, bool PANEL = false, class Epi>
; __device__ __forceinline__ void gemm_phase(const bf16_t* __restrict__ A, long lda, const bf16_t* __restrict__ Bt, long ldb, int nM, int nN, int K,
;                                            const Epi& epi, bf16_t* shm, int w0) {
;     ...
;       WAIT_V(6); BAR; MMA(1, 1, At, B1); BAR;
;       LDB(B0, 1, 0); SCHED; LDA(At, 1, 0); STAGE(SA(0, 1), A, lda, aoff, brow + HALF, t + 2);
;       WAIT_L(8); BAR; WAIT_L(0); MMA(0, 0, At, B0); BAR; SCHED;
;       LDB(B1, 1, 1); STAGE(SB(1, 0), Bt, ldb, boff, bcol, t + 3);
;       BAR; WAIT_L(0); MMA(0, 1, At, B1); BAR;
;       LDA(At, 1, 1); STAGE(SA(1, 0), A, lda, aoff, brow, t + 3);
	v_mfma_f32_16x16x32_bf16 v[30:33], v[198:201], v[166:169], v[30:33]
	v_mfma_f32_16x16x32_bf16 v[26:29], v[206:209], v[166:169], v[26:29]
	v_mfma_f32_16x16x32_bf16 v[22:25], v[198:201], v[174:177], v[22:25]
	v_mfma_f32_16x16x32_bf16 v[18:21], v[206:209], v[174:177], v[18:21]
	v_mfma_f32_16x16x32_bf16 v[14:17], v[198:201], v[182:185], v[14:17]
	v_mfma_f32_16x16x32_bf16 v[10:13], v[206:209], v[182:185], v[10:13]
	v_mfma_f32_16x16x32_bf16 v[6:9], v[198:201], v[190:193], v[6:9]
	v_mfma_f32_16x16x32_bf16 v[2:5], v[206:209], v[190:193], v[2:5]
	v_mfma_f32_16x16x32_bf16 v[30:33], v[202:205], v[170:173], v[30:33]
	v_mfma_f32_16x16x32_bf16 v[26:29], v[210:213], v[170:173], v[26:29]
	v_mfma_f32_16x16x32_bf16 v[22:25], v[202:205], v[178:181], v[22:25]
	v_mfma_f32_16x16x32_bf16 v[18:21], v[210:213], v[178:181], v[18:21]
	v_mfma_f32_16x16x32_bf16 v[14:17], v[202:205], v[186:189], v[14:17]
	v_mfma_f32_16x16x32_bf16 v[10:13], v[210:213], v[186:189], v[10:13]
	v_mfma_f32_16x16x32_bf16 v[6:9], v[202:205], v[194:197], v[6:9]
	v_mfma_f32_16x16x32_bf16 v[2:5], v[210:213], v[194:197], v[2:5]
	s_barrier
	ds_read_b128 v[150:153], v220
	ds_read_b128 v[154:157], v220 offset:1024
	ds_read_b128 v[158:161], v220 offset:2048
	ds_read_b128 v[162:165], v220 offset:3072
	ds_read_b128 v[166:169], v141 offset:32768
	ds_read_b128 v[170:173], v141 offset:33792
	ds_read_b128 v[174:177], v141 offset:34816
	ds_read_b128 v[178:181], v141 offset:35840
	ds_read_b128 v[182:185], v141 offset:36864
	ds_read_b128 v[186:189], v141 offset:37888
	ds_read_b128 v[190:193], v141 offset:38912
	ds_read_b128 v[194:197], v141 offset:39936
	s_mov_b32 m0, s52
	s_add_u32 s98, s42, s68
	s_addc_u32 s99, s43, s69
	global_load_lds_dwordx4 v131, s[98:99]
	s_mov_b32 m0, s53
	s_add_u32 s98, s42, s70
	s_addc_u32 s99, s43, s71
	global_load_lds_dwordx4 v131, s[98:99]
	s_waitcnt lgkmcnt(8)
	s_waitcnt vmcnt(10)
	s_barrier
	s_waitcnt lgkmcnt(0)
	s_waitcnt lgkmcnt(0)
	v_mfma_f32_16x16x32_bf16 v[126:129], v[150:153], v[166:169], v[126:129]
	v_mfma_f32_16x16x32_bf16 v[122:125], v[158:161], v[166:169], v[122:125]
	v_mfma_f32_16x16x32_bf16 v[118:121], v[150:153], v[174:177], v[118:121]
	v_mfma_f32_16x16x32_bf16 v[114:117], v[158:161], v[174:177], v[114:117]
	v_mfma_f32_16x16x32_bf16 v[110:113], v[150:153], v[182:185], v[110:113]
	v_mfma_f32_16x16x32_bf16 v[106:109], v[158:161], v[182:185], v[106:109]
	v_mfma_f32_16x16x32_bf16 v[102:105], v[150:153], v[190:193], v[102:105]
	v_mfma_f32_16x16x32_bf16 v[98:101], v[158:161], v[190:193], v[98:101]
	v_mfma_f32_16x16x32_bf16 v[126:129], v[154:157], v[170:173], v[126:129]
	v_mfma_f32_16x16x32_bf16 v[122:125], v[162:165], v[170:173], v[122:125]
	v_mfma_f32_16x16x32_bf16 v[118:121], v[154:157], v[178:181], v[118:121]
	v_mfma_f32_16x16x32_bf16 v[114:117], v[162:165], v[178:181], v[114:117]
	v_mfma_f32_16x16x32_bf16 v[110:113], v[154:157], v[186:189], v[110:113]
	v_mfma_f32_16x16x32_bf16 v[106:109], v[162:165], v[186:189], v[106:109]
	v_mfma_f32_16x16x32_bf16 v[102:105], v[154:157], v[194:197], v[102:105]
	v_mfma_f32_16x16x32_bf16 v[98:101], v[162:165], v[194:197], v[98:101]
	s_barrier
	ds_read_b128 v[198:201], v221
	ds_read_b128 v[202:205], v221 offset:1024
	ds_read_b128 v[206:209], v221 offset:2048
	ds_read_b128 v[210:213], v221 offset:3072
	s_mov_b32 m0, s54
	s_add_u32 s98, s66, s94
	s_addc_u32 s99, s67, s95
	global_load_lds_dwordx4 v131, s[98:99]
	s_mov_b32 m0, s55
	s_add_u32 s98, s66, s72
	s_addc_u32 s99, s67, s73
	global_load_lds_dwordx4 v131, s[98:99]
	s_waitcnt vmcnt(10)
	s_barrier
	s_waitcnt lgkmcnt(0)
	s_waitcnt lgkmcnt(0)
	v_mfma_f32_16x16x32_bf16 v[94:97], v[198:201], v[166:169], v[94:97]
	v_mfma_f32_16x16x32_bf16 v[90:93], v[206:209], v[166:169], v[90:93]
	v_mfma_f32_16x16x32_bf16 v[86:89], v[198:201], v[174:177], v[86:89]
	v_mfma_f32_16x16x32_bf16 v[82:85], v[206:209], v[174:177], v[82:85]
	v_mfma_f32_16x16x32_bf16 v[78:81], v[198:201], v[182:185], v[78:81]
	v_mfma_f32_16x16x32_bf16 v[74:77], v[206:209], v[182:185], v[74:77]
	v_mfma_f32_16x16x32_bf16 v[70:73], v[198:201], v[190:193], v[70:73]
	v_mfma_f32_16x16x32_bf16 v[66:69], v[206:209], v[190:193], v[66:69]
	v_mfma_f32_16x16x32_bf16 v[94:97], v[202:205], v[170:173], v[94:97]
	v_mfma_f32_16x16x32_bf16 v[90:93], v[210:213], v[170:173], v[90:93]
	v_mfma_f32_16x16x32_bf16 v[86:89], v[202:205], v[178:181], v[86:89]
	v_mfma_f32_16x16x32_bf16 v[82:85], v[210:213], v[178:181], v[82:85]
	v_mfma_f32_16x16x32_bf16 v[78:81], v[202:205], v[186:189], v[78:81]
	v_mfma_f32_16x16x32_bf16 v[74:77], v[210:213], v[186:189], v[74:77]
	v_mfma_f32_16x16x32_bf16 v[70:73], v[202:205], v[194:197], v[70:73]
	v_mfma_f32_16x16x32_bf16 v[66:69], v[210:213], v[194:197], v[66:69]
	s_barrier
	ds_read_b128 v[166:169], v141 offset:49152
	ds_read_b128 v[170:173], v141 offset:50176
	ds_read_b128 v[174:177], v141 offset:51200
	ds_read_b128 v[178:181], v141 offset:52224
	ds_read_b128 v[182:185], v141 offset:53248
	ds_read_b128 v[186:189], v141 offset:54272
	ds_read_b128 v[190:193], v141 offset:55296
	ds_read_b128 v[194:197], v141 offset:56320
	s_mov_b32 m0, s56
	s_add_u32 s98, s42, s94
	s_addc_u32 s99, s43, s95
	global_load_lds_dwordx4 v131, s[98:99]
	s_mov_b32 m0, s57
	s_add_u32 s98, s42, s72
	s_addc_u32 s99, s43, s73
	global_load_lds_dwordx4 v131, s[98:99]
	s_barrier
; #define LDA(dst, b, h) for (int m = 0; m < 4; ++m) for (int k = 0; k < 2; ++k) \
;     dst[m][k] = *reinterpret_cast<const bf16x8*>((char*)SA(b, h) + a_thr + (m * 2 + k) * 1024)
; #define LDB(dst, b, h) for (int n = 0; n < 2; ++n) for (int k = 0; k < 2; ++k) \
;     dst[n][k] = *reinterpret_cast<const bf16x8*>((char*)SB(b, h) + b_thr + (n * 2 + k) * 1024)
; #define MMA(ai, bj, At, Btf) do { __builtin_amdgcn_s_setprio(1); \
;     for (int m = 0; m < 4; ++m) for (int n = 0; n < 2; ++n) for (int k = 0; k < 2; ++k) \
;       acc[ai][bj][m][n] = __builtin_amdgcn_mfma_f32_16x16x32_bf16(Btf[n][k], At[m][k], acc[ai][bj][m][n], 0, 0, 0); \
;     __builtin_amdgcn_s_setprio(0); } while (0)
; #define WAIT_V(n) asm volatile("s_waitcnt vmcnt(" #n ")" ::: "memory")
; #define WAIT_L(n) asm volatile("s_waitcnt lgkmcnt(" #n ")" ::: "memory")
; #define BAR __builtin_amdgcn_s_barrier()
; #define SCHED __builtin_amdgcn_sched_barrier(0)
; template <bool OVL, bool PANEL = false, class Epi>
; __device__ __forceinline__ void gemm_phase(const bf16_t* __restrict__ A, long lda, const bf16_t* __restrict__ Bt, long ldb, int nM, int nN, int K,
;                                            const Epi& epi, bf16_t* shm, int w0) {
;     ...
;       BAR; WAIT_L(0); MMA(1, 0, At, B0); BAR; SCHED;
;       STAGE(SB(1, 1), Bt, ldb, boff, bcol + HALF, t + 3);
;       WAIT_V(6); BAR; MMA(1, 1, At, B1); BAR;
;     }
;     { LDB(B0, 0, 0); LDA(At, 0, 0); STAGE(SA(1, 1), A, lda, aoff, brow + HALF, nt - 1);
;       BAR; WAIT_L(0); MMA(0, 0, At, B0); BAR;
;       LDB(B1, 0, 1); BAR; WAIT_L(0); MMA(0, 1, At, B1); BAR;
	s_waitcnt lgkmcnt(0)
	s_waitcnt lgkmcnt(0)
	v_mfma_f32_16x16x32_bf16 v[62:65], v[150:153], v[166:169], v[62:65]
	v_mfma_f32_16x16x32_bf16 v[58:61], v[158:161], v[166:169], v[58:61]
	v_mfma_f32_16x16x32_bf16 v[54:57], v[150:153], v[174:177], v[54:57]
	v_mfma_f32_16x16x32_bf16 v[50:53], v[158:161], v[174:177], v[50:53]
	v_mfma_f32_16x16x32_bf16 v[46:49], v[150:153], v[182:185], v[46:49]
	v_mfma_f32_16x16x32_bf16 v[42:45], v[158:161], v[182:185], v[42:45]
	v_mfma_f32_16x16x32_bf16 v[38:41], v[150:153], v[190:193], v[38:41]
	v_mfma_f32_16x16x32_bf16 v[34:37], v[158:161], v[190:193], v[34:37]
	v_mfma_f32_16x16x32_bf16 v[62:65], v[154:157], v[170:173], v[62:65]
	v_mfma_f32_16x16x32_bf16 v[58:61], v[162:165], v[170:173], v[58:61]
	v_mfma_f32_16x16x32_bf16 v[54:57], v[154:157], v[178:181], v[54:57]
	v_mfma_f32_16x16x32_bf16 v[50:53], v[162:165], v[178:181], v[50:53]
	v_mfma_f32_16x16x32_bf16 v[46:49], v[154:157], v[186:189], v[46:49]
	v_mfma_f32_16x16x32_bf16 v[42:45], v[162:165], v[186:189], v[42:45]
	v_mfma_f32_16x16x32_bf16 v[38:41], v[154:157], v[194:197], v[38:41]
	v_mfma_f32_16x16x32_bf16 v[34:37], v[162:165], v[194:197], v[34:37]
	s_barrier
	s_mov_b32 m0, s58
	s_add_u32 s98, s66, s30
	s_addc_u32 s99, s67, s31
	global_load_lds_dwordx4 v131, s[98:99]
	s_mov_b32 m0, s59
	s_add_u32 s98, s66, s44
	s_addc_u32 s99, s67, s45
	global_load_lds_dwordx4 v131, s[98:99]
	s_waitcnt vmcnt(10)
	s_barrier
	v_mfma_f32_16x16x32_bf16 v[30:33], v[198:201], v[166:169], v[30:33]
	v_mfma_f32_16x16x32_bf16 v[26:29], v[206:209], v[166:169], v[26:29]
	v_mfma_f32_16x16x32_bf16 v[22:25], v[198:201], v[174:177], v[22:25]
	v_mfma_f32_16x16x32_bf16 v[18:21], v[206:209], v[174:177], v[18:21]
	v_mfma_f32_16x16x32_bf16 v[14:17], v[198:201], v[182:185], v[14:17]
	v_mfma_f32_16x16x32_bf16 v[10:13], v[206:209], v[182:185], v[10:13]
	v_mfma_f32_16x16x32_bf16 v[6:9], v[198:201], v[190:193], v[6:9]
	v_mfma_f32_16x16x32_bf16 v[2:5], v[206:209], v[190:193], v[2:5]
	v_mfma_f32_16x16x32_bf16 v[30:33], v[202:205], v[170:173], v[30:33]
	v_mfma_f32_16x16x32_bf16 v[26:29], v[210:213], v[170:173], v[26:29]
	v_mfma_f32_16x16x32_bf16 v[22:25], v[202:205], v[178:181], v[22:25]
	v_mfma_f32_16x16x32_bf16 v[18:21], v[210:213], v[178:181], v[18:21]
	v_mfma_f32_16x16x32_bf16 v[14:17], v[202:205], v[186:189], v[14:17]
	v_mfma_f32_16x16x32_bf16 v[10:13], v[210:213], v[186:189], v[10:13]
	v_mfma_f32_16x16x32_bf16 v[6:9], v[202:205], v[194:197], v[6:9]
	v_mfma_f32_16x16x32_bf16 v[2:5], v[210:213], v[194:197], v[2:5]
	s_add_i32 s18, s18, 2
	s_add_u32 vcc_lo, vcc_lo, 0x100
	s_addc_u32 vcc_hi, vcc_hi, 0
	s_cmp_lt_u32 s18, 12
	s_barrier
	s_cbranch_scc1 .LBB0_386
	s_waitcnt vmcnt(6)
	s_or_b32 s8, s2, 0x80
	s_mov_b32 s9, s3
	v_readlane_b32 s44, v252, 20
	s_lshl_b64 s[8:9], s[8:9], 11
	v_readlane_b32 s50, v252, 26
	v_add_u32_e32 v214, 16, v140
	v_readlane_b32 s51, v252, 27
	s_add_u32 s8, s50, s8
	v_add_u32_e32 v0, 0x10000, v214
	s_addc_u32 s9, s51, s9
	ds_read_b128 v[142:145], v0
	ds_read_b128 v[150:153], v0 offset:1024
	ds_read_b128 v[154:157], v0 offset:2048
	ds_read_b128 v[158:161], v0 offset:3072
	ds_read_b128 v[162:165], v141
	ds_read_b128 v[166:169], v141 offset:1024
	ds_read_b128 v[170:173], v141 offset:2048
	ds_read_b128 v[174:177], v141 offset:3072
	ds_read_b128 v[178:181], v141 offset:4096
	ds_read_b128 v[182:185], v141 offset:5120
	ds_read_b128 v[186:189], v141 offset:6144
	ds_read_b128 v[190:193], v141 offset:7168
	v_mov_b32_e32 v0, v131
	v_readlane_b32 s45, v252, 21
	v_lshl_add_u64 v[146:147], s[8:9], 0, v[0:1]
	s_mov_b64 s[8:9], 0x780
	v_lshl_add_u64 v[194:195], v[146:147], 0, s[8:9]
	v_readfirstlane_b32 s8, v148
	s_mov_b32 m0, s8
	s_mov_b64 s[8:9], 0x20780
	v_lshl_add_u64 v[146:147], v[146:147], 0, s[8:9]
	v_readfirstlane_b32 s8, v149
	global_load_lds_dwordx4 v[194:195], off
	s_mov_b32 m0, s8
	v_readlane_b32 s46, v252, 22
	global_load_lds_dwordx4 v[146:147], off
	s_barrier
	s_waitcnt lgkmcnt(0)
	v_readlane_b32 s47, v252, 23
	v_readlane_b32 s48, v252, 24
	v_readlane_b32 s49, v252, 25
	v_readlane_b32 s52, v252, 28
	v_readlane_b32 s53, v252, 29
	v_readlane_b32 s54, v252, 30
	v_readlane_b32 s55, v252, 31
	v_readlane_b32 s56, v252, 32
	v_readlane_b32 s57, v252, 33
	v_readlane_b32 s58, v252, 34
	v_readlane_b32 s59, v252, 35
	s_setprio 1
	s_waitcnt lgkmcnt(0)
	v_mfma_f32_16x16x32_bf16 v[126:129], v[142:145], v[162:165], v[126:129]
	v_mfma_f32_16x16x32_bf16 v[122:125], v[154:157], v[162:165], v[122:125]
	v_mfma_f32_16x16x32_bf16 v[118:121], v[142:145], v[170:173], v[118:121]
	v_mfma_f32_16x16x32_bf16 v[114:117], v[154:157], v[170:173], v[114:117]
	v_mfma_f32_16x16x32_bf16 v[110:113], v[142:145], v[178:181], v[110:113]
	v_mfma_f32_16x16x32_bf16 v[106:109], v[154:157], v[178:181], v[106:109]
	v_mfma_f32_16x16x32_bf16 v[98:101], v[154:157], v[186:189], v[98:101]
	v_mfma_f32_16x16x32_bf16 v[126:129], v[150:153], v[166:169], v[126:129]
	v_mfma_f32_16x16x32_bf16 v[122:125], v[158:161], v[166:169], v[122:125]
	v_mfma_f32_16x16x32_bf16 v[118:121], v[150:153], v[174:177], v[118:121]
	v_mfma_f32_16x16x32_bf16 v[114:117], v[158:161], v[174:177], v[114:117]
	v_mfma_f32_16x16x32_bf16 v[110:113], v[150:153], v[182:185], v[110:113]
	v_mfma_f32_16x16x32_bf16 v[106:109], v[158:161], v[182:185], v[106:109]
	v_mfma_f32_16x16x32_bf16 v[102:105], v[142:145], v[186:189], v[102:105]
	v_mfma_f32_16x16x32_bf16 v[98:101], v[158:161], v[190:193], v[98:101]
	v_mfma_f32_16x16x32_bf16 v[146:149], v[150:153], v[190:193], v[102:105]
	s_setprio 0
	v_add_u32_e32 v0, 0x14000, v214
	s_barrier
	s_nop 2
	ds_read_b128 v[102:105], v0
	ds_read_b128 v[194:197], v0 offset:1024
	ds_read_b128 v[198:201], v0 offset:2048
	ds_read_b128 v[202:205], v0 offset:3072
	s_barrier
; #define LDA(dst, b, h) for (int m = 0; m < 4; ++m) for (int k = 0; k < 2; ++k) \
;     dst[m][k] = *reinterpret_cast<const bf16x8*>((char*)SA(b, h) + a_thr + (m * 2 + k) * 1024)
; #define LDB(dst, b, h) for (int n = 0; n < 2; ++n) for (int k = 0; k < 2; ++k) \
;     dst[n][k] = *reinterpret_cast<const bf16x8*>((char*)SB(b, h) + b_thr + (n * 2 + k) * 1024)
; #define MMA(ai, bj, At, Btf) do { __builtin_amdgcn_s_setprio(1); \
;     for (int m = 0; m < 4; ++m) for (int n = 0; n < 2; ++n) for (int k = 0; k < 2; ++k) \
;       acc[ai][bj][m][n] = __builtin_amdgcn_mfma_f32_16x16x32_bf16(Btf[n][k], At[m][k], acc[ai][bj][m][n], 0, 0, 0); \
;     __builtin_amdgcn_s_setprio(0); } while (0)
; #define WAIT_V(n) asm volatile("s_waitcnt vmcnt(" #n ")" ::: "memory")
; #define WAIT_L(n) asm volatile("s_waitcnt lgkmcnt(" #n ")" ::: "memory")
; #define BAR __builtin_amdgcn_s_barrier()
; template <bool OVL, bool PANEL = false, class Epi>
; __device__ __forceinline__ void gemm_phase(const bf16_t* __restrict__ A, long lda, const bf16_t* __restrict__ Bt, long ldb, int nM, int nN, int K,
;                                            const Epi& epi, bf16_t* shm, int w0) {
;     ...
;       LDB(B1, 0, 1); BAR; WAIT_L(0); MMA(0, 1, At, B1); BAR;
;       LDA(At, 0, 1); WAIT_V(4); BAR; WAIT_L(0); MMA(1, 0, At, B0); MMA(1, 1, At, B1); BAR; }
;     { LDB(B0, 1, 0); LDA(At, 1, 0); WAIT_V(2); BAR; WAIT_L(0); MMA(0, 0, At, B0); BAR;
	s_waitcnt lgkmcnt(0)
	s_setprio 1
	s_waitcnt lgkmcnt(0)
	v_mfma_f32_16x16x32_bf16 v[94:97], v[102:105], v[162:165], v[94:97]
	v_mfma_f32_16x16x32_bf16 v[86:89], v[102:105], v[170:173], v[86:89]
	v_mfma_f32_16x16x32_bf16 v[78:81], v[102:105], v[178:181], v[78:81]
	v_mfma_f32_16x16x32_bf16 v[74:77], v[198:201], v[178:181], v[74:77]
	v_mfma_f32_16x16x32_bf16 v[94:97], v[194:197], v[166:169], v[94:97]
	v_mfma_f32_16x16x32_bf16 v[90:93], v[198:201], v[162:165], v[90:93]
	v_mfma_f32_16x16x32_bf16 v[86:89], v[194:197], v[174:177], v[86:89]
	v_mfma_f32_16x16x32_bf16 v[82:85], v[198:201], v[170:173], v[82:85]
	v_mfma_f32_16x16x32_bf16 v[78:81], v[194:197], v[182:185], v[78:81]
	v_mfma_f32_16x16x32_bf16 v[74:77], v[202:205], v[182:185], v[74:77]
	v_mfma_f32_16x16x32_bf16 v[70:73], v[102:105], v[186:189], v[70:73]
	v_mfma_f32_16x16x32_bf16 v[66:69], v[198:201], v[186:189], v[66:69]
	v_mfma_f32_16x16x32_bf16 v[162:165], v[202:205], v[166:169], v[90:93]
	v_mfma_f32_16x16x32_bf16 v[166:169], v[202:205], v[174:177], v[82:85]
	v_mfma_f32_16x16x32_bf16 v[170:173], v[194:197], v[190:193], v[70:73]
	v_mfma_f32_16x16x32_bf16 v[174:177], v[202:205], v[190:193], v[66:69]
	s_setprio 0
	s_barrier
	s_nop 1
	ds_read_b128 v[66:69], v141 offset:16384
	ds_read_b128 v[70:73], v141 offset:17408
	ds_read_b128 v[82:85], v141 offset:18432
	ds_read_b128 v[90:93], v141 offset:19456
	ds_read_b128 v[178:181], v141 offset:20480
	ds_read_b128 v[182:185], v141 offset:21504
	ds_read_b128 v[186:189], v141 offset:22528
	ds_read_b128 v[190:193], v141 offset:23552
	s_waitcnt vmcnt(4)
	s_barrier
	s_waitcnt lgkmcnt(0)
	s_setprio 1
	s_waitcnt lgkmcnt(0)
	v_mfma_f32_16x16x32_bf16 v[62:65], v[142:145], v[66:69], v[62:65]
	v_mfma_f32_16x16x32_bf16 v[54:57], v[142:145], v[82:85], v[54:57]
	v_mfma_f32_16x16x32_bf16 v[46:49], v[142:145], v[178:181], v[46:49]
	v_mfma_f32_16x16x32_bf16 v[42:45], v[154:157], v[178:181], v[42:45]
	v_mfma_f32_16x16x32_bf16 v[38:41], v[142:145], v[186:189], v[38:41]
	v_mfma_f32_16x16x32_bf16 v[34:37], v[154:157], v[186:189], v[34:37]
	v_mfma_f32_16x16x32_bf16 v[62:65], v[150:153], v[70:73], v[62:65]
	v_mfma_f32_16x16x32_bf16 v[58:61], v[154:157], v[66:69], v[58:61]
	v_mfma_f32_16x16x32_bf16 v[54:57], v[150:153], v[90:93], v[54:57]
	v_mfma_f32_16x16x32_bf16 v[50:53], v[154:157], v[82:85], v[50:53]
	v_mfma_f32_16x16x32_bf16 v[46:49], v[150:153], v[182:185], v[46:49]
	v_mfma_f32_16x16x32_bf16 v[42:45], v[158:161], v[182:185], v[42:45]
	v_mfma_f32_16x16x32_bf16 v[38:41], v[150:153], v[190:193], v[38:41]
	v_mfma_f32_16x16x32_bf16 v[34:37], v[158:161], v[190:193], v[34:37]
	v_mfma_f32_16x16x32_bf16 v[206:209], v[158:161], v[70:73], v[58:61]
	v_mfma_f32_16x16x32_bf16 v[210:213], v[158:161], v[90:93], v[50:53]
	s_setprio 0
	s_setprio 1
	v_mfma_f32_16x16x32_bf16 v[30:33], v[102:105], v[66:69], v[30:33]
	v_mfma_f32_16x16x32_bf16 v[26:29], v[198:201], v[66:69], v[26:29]
	v_mfma_f32_16x16x32_bf16 v[22:25], v[102:105], v[82:85], v[22:25]
	v_mfma_f32_16x16x32_bf16 v[18:21], v[198:201], v[82:85], v[18:21]
	v_mfma_f32_16x16x32_bf16 v[14:17], v[102:105], v[178:181], v[14:17]
	v_mfma_f32_16x16x32_bf16 v[10:13], v[198:201], v[178:181], v[10:13]
	v_mfma_f32_16x16x32_bf16 v[6:9], v[102:105], v[186:189], v[6:9]
	v_mfma_f32_16x16x32_bf16 v[2:5], v[198:201], v[186:189], v[2:5]
	v_mfma_f32_16x16x32_bf16 v[30:33], v[194:197], v[70:73], v[30:33]
	v_mfma_f32_16x16x32_bf16 v[26:29], v[202:205], v[70:73], v[26:29]
	v_mfma_f32_16x16x32_bf16 v[22:25], v[194:197], v[90:93], v[22:25]
	v_mfma_f32_16x16x32_bf16 v[18:21], v[202:205], v[90:93], v[18:21]
	v_mfma_f32_16x16x32_bf16 v[14:17], v[194:197], v[182:185], v[14:17]
	v_mfma_f32_16x16x32_bf16 v[10:13], v[202:205], v[182:185], v[10:13]
	v_mfma_f32_16x16x32_bf16 v[6:9], v[194:197], v[190:193], v[6:9]
	v_mfma_f32_16x16x32_bf16 v[2:5], v[202:205], v[190:193], v[2:5]
	s_setprio 0
	v_add_u32_e32 v0, 0x18000, v214
	s_barrier
	ds_read_b128 v[142:145], v0
	ds_read_b128 v[150:153], v0 offset:1024
	ds_read_b128 v[154:157], v0 offset:2048
	ds_read_b128 v[158:161], v0 offset:3072
	ds_read_b128 v[50:53], v141 offset:32768
	ds_read_b128 v[58:61], v141 offset:33792
	ds_read_b128 v[66:69], v141 offset:34816
	ds_read_b128 v[70:73], v141 offset:35840
	ds_read_b128 v[178:181], v141 offset:36864
	ds_read_b128 v[182:185], v141 offset:37888
	ds_read_b128 v[186:189], v141 offset:38912
	ds_read_b128 v[190:193], v141 offset:39936
	s_waitcnt vmcnt(2)
	s_barrier
; #define LDA(dst, b, h) for (int m = 0; m < 4; ++m) for (int k = 0; k < 2; ++k) \
;     dst[m][k] = *reinterpret_cast<const bf16x8*>((char*)SA(b, h) + a_thr + (m * 2 + k) * 1024)
; #define LDB(dst, b, h) for (int n = 0; n < 2; ++n) for (int k = 0; k < 2; ++k) \
;     dst[n][k] = *reinterpret_cast<const bf16x8*>((char*)SB(b, h) + b_thr + (n * 2 + k) * 1024)
; #define MMA(ai, bj, At, Btf) do { __builtin_amdgcn_s_setprio(1); \
;     for (int m = 0; m < 4; ++m) for (int n = 0; n < 2; ++n) for (int k = 0; k < 2; ++k) \
;       acc[ai][bj][m][n] = __builtin_amdgcn_mfma_f32_16x16x32_bf16(Btf[n][k], At[m][k], acc[ai][bj][m][n], 0, 0, 0); \
;     __builtin_amdgcn_s_setprio(0); } while (0)
; #define WAIT_V(n) asm volatile("s_waitcnt vmcnt(" #n ")" ::: "memory")
; #define WAIT_L(n) asm volatile("s_waitcnt lgkmcnt(" #n ")" ::: "memory")
; #define BAR __builtin_amdgcn_s_barrier()
; template <bool OVL, bool PANEL = false, class Epi>
; __device__ __forceinline__ void gemm_phase(const bf16_t* __restrict__ A, long lda, const bf16_t* __restrict__ Bt, long ldb, int nM, int nN, int K,
;                                            const Epi& epi, bf16_t* shm, int w0) {
;     ...
;     { LDB(B0, 1, 0); LDA(At, 1, 0); WAIT_V(2); BAR; WAIT_L(0); MMA(0, 0, At, B0); BAR;
;       LDB(B1, 1, 1); WAIT_V(0); BAR; WAIT_L(0); MMA(0, 1, At, B1); BAR;
;       LDA(At, 1, 1); BAR; WAIT_L(0); MMA(1, 0, At, B0); MMA(1, 1, At, B1); BAR; }
;     if (wr == 0) BAR;
	s_waitcnt lgkmcnt(0)
	s_setprio 1
	s_waitcnt lgkmcnt(0)
	v_mfma_f32_16x16x32_bf16 v[82:85], v[142:145], v[50:53], v[126:129]
	v_mfma_f32_16x16x32_bf16 v[126:129], v[150:153], v[58:61], v[82:85]
	v_mfma_f32_16x16x32_bf16 v[82:85], v[154:157], v[50:53], v[122:125]
	v_mfma_f32_16x16x32_bf16 v[122:125], v[158:161], v[58:61], v[82:85]
	v_mfma_f32_16x16x32_bf16 v[82:85], v[142:145], v[66:69], v[118:121]
	v_mfma_f32_16x16x32_bf16 v[118:121], v[150:153], v[70:73], v[82:85]
	v_mfma_f32_16x16x32_bf16 v[82:85], v[154:157], v[66:69], v[114:117]
	v_mfma_f32_16x16x32_bf16 v[114:117], v[158:161], v[70:73], v[82:85]
	v_mfma_f32_16x16x32_bf16 v[82:85], v[142:145], v[178:181], v[110:113]
	v_mfma_f32_16x16x32_bf16 v[110:113], v[150:153], v[182:185], v[82:85]
	v_mfma_f32_16x16x32_bf16 v[82:85], v[154:157], v[178:181], v[106:109]
	v_mfma_f32_16x16x32_bf16 v[102:105], v[158:161], v[182:185], v[82:85]
	v_mfma_f32_16x16x32_bf16 v[82:85], v[142:145], v[186:189], v[146:149]
	v_mfma_f32_16x16x32_bf16 v[90:93], v[150:153], v[190:193], v[82:85]
	v_mfma_f32_16x16x32_bf16 v[82:85], v[154:157], v[186:189], v[98:101]
	v_mfma_f32_16x16x32_bf16 v[82:85], v[158:161], v[190:193], v[82:85]
	s_setprio 0
	v_add_u32_e32 v0, 0x1c000, v214
	s_barrier
	ds_read_b128 v[146:149], v0
	ds_read_b128 v[194:197], v0 offset:1024
	ds_read_b128 v[198:201], v0 offset:2048
	ds_read_b128 v[202:205], v0 offset:3072
	s_waitcnt vmcnt(0)
	s_barrier
	s_waitcnt lgkmcnt(0)
	s_setprio 1
	s_waitcnt lgkmcnt(0)
	v_mfma_f32_16x16x32_bf16 v[94:97], v[146:149], v[50:53], v[94:97]
	v_mfma_f32_16x16x32_bf16 v[50:53], v[198:201], v[50:53], v[162:165]
	v_mfma_f32_16x16x32_bf16 v[98:101], v[202:205], v[58:61], v[50:53]
	v_mfma_f32_16x16x32_bf16 v[50:53], v[146:149], v[66:69], v[86:89]
	v_mfma_f32_16x16x32_bf16 v[106:109], v[194:197], v[58:61], v[94:97]
	v_mfma_f32_16x16x32_bf16 v[94:97], v[194:197], v[70:73], v[50:53]
	v_mfma_f32_16x16x32_bf16 v[50:53], v[198:201], v[66:69], v[166:169]
	v_mfma_f32_16x16x32_bf16 v[86:89], v[202:205], v[70:73], v[50:53]
	v_mfma_f32_16x16x32_bf16 v[50:53], v[146:149], v[178:181], v[78:81]
	v_mfma_f32_16x16x32_bf16 v[70:73], v[194:197], v[182:185], v[50:53]
	v_mfma_f32_16x16x32_bf16 v[50:53], v[198:201], v[178:181], v[74:77]
	v_mfma_f32_16x16x32_bf16 v[66:69], v[202:205], v[182:185], v[50:53]
	v_mfma_f32_16x16x32_bf16 v[50:53], v[146:149], v[186:189], v[170:173]
	v_mfma_f32_16x16x32_bf16 v[58:61], v[194:197], v[190:193], v[50:53]
	v_mfma_f32_16x16x32_bf16 v[50:53], v[198:201], v[186:189], v[174:177]
	v_mfma_f32_16x16x32_bf16 v[50:53], v[202:205], v[190:193], v[50:53]
	s_setprio 0
	s_barrier
	ds_read_b128 v[162:165], v141 offset:49152
	ds_read_b128 v[166:169], v141 offset:50176
	ds_read_b128 v[170:173], v141 offset:51200
	ds_read_b128 v[174:177], v141 offset:52224
	ds_read_b128 v[178:181], v141 offset:53248
	ds_read_b128 v[182:185], v141 offset:54272
	ds_read_b128 v[186:189], v141 offset:55296
	ds_read_b128 v[190:193], v141 offset:56320
	s_barrier
	s_waitcnt lgkmcnt(0)
	s_setprio 1
	s_waitcnt lgkmcnt(0)
	v_mfma_f32_16x16x32_bf16 v[62:65], v[142:145], v[162:165], v[62:65]
	v_mfma_f32_16x16x32_bf16 v[78:81], v[150:153], v[166:169], v[62:65]
	v_mfma_f32_16x16x32_bf16 v[62:65], v[154:157], v[162:165], v[206:209]
	v_mfma_f32_16x16x32_bf16 v[54:57], v[142:145], v[170:173], v[54:57]
	v_mfma_f32_16x16x32_bf16 v[74:77], v[158:161], v[166:169], v[62:65]
	v_mfma_f32_16x16x32_bf16 v[62:65], v[150:153], v[174:177], v[54:57]
	v_mfma_f32_16x16x32_bf16 v[54:57], v[154:157], v[170:173], v[210:213]
	v_mfma_f32_16x16x32_bf16 v[46:49], v[142:145], v[178:181], v[46:49]
	v_mfma_f32_16x16x32_bf16 v[42:45], v[154:157], v[178:181], v[42:45]
	v_mfma_f32_16x16x32_bf16 v[38:41], v[142:145], v[186:189], v[38:41]
	v_mfma_f32_16x16x32_bf16 v[34:37], v[154:157], v[186:189], v[34:37]
	v_mfma_f32_16x16x32_bf16 v[54:57], v[158:161], v[174:177], v[54:57]
	v_mfma_f32_16x16x32_bf16 v[46:49], v[150:153], v[182:185], v[46:49]
	v_mfma_f32_16x16x32_bf16 v[42:45], v[158:161], v[182:185], v[42:45]
	v_mfma_f32_16x16x32_bf16 v[38:41], v[150:153], v[190:193], v[38:41]
	v_mfma_f32_16x16x32_bf16 v[34:37], v[158:161], v[190:193], v[34:37]
	s_setprio 0
	s_setprio 1
	v_mfma_f32_16x16x32_bf16 v[30:33], v[146:149], v[162:165], v[30:33]
	v_mfma_f32_16x16x32_bf16 v[26:29], v[198:201], v[162:165], v[26:29]
	v_mfma_f32_16x16x32_bf16 v[22:25], v[146:149], v[170:173], v[22:25]
	v_mfma_f32_16x16x32_bf16 v[18:21], v[198:201], v[170:173], v[18:21]
	v_mfma_f32_16x16x32_bf16 v[14:17], v[146:149], v[178:181], v[14:17]
	v_mfma_f32_16x16x32_bf16 v[10:13], v[198:201], v[178:181], v[10:13]
	v_mfma_f32_16x16x32_bf16 v[6:9], v[146:149], v[186:189], v[6:9]
	v_mfma_f32_16x16x32_bf16 v[2:5], v[198:201], v[186:189], v[2:5]
	v_mfma_f32_16x16x32_bf16 v[30:33], v[194:197], v[166:169], v[30:33]
	v_mfma_f32_16x16x32_bf16 v[26:29], v[202:205], v[166:169], v[26:29]
	v_mfma_f32_16x16x32_bf16 v[22:25], v[194:197], v[174:177], v[22:25]
	v_mfma_f32_16x16x32_bf16 v[18:21], v[202:205], v[174:177], v[18:21]
	v_mfma_f32_16x16x32_bf16 v[14:17], v[194:197], v[182:185], v[14:17]
	v_mfma_f32_16x16x32_bf16 v[10:13], v[202:205], v[182:185], v[10:13]
	v_mfma_f32_16x16x32_bf16 v[6:9], v[194:197], v[190:193], v[6:9]
	v_mfma_f32_16x16x32_bf16 v[2:5], v[202:205], v[190:193], v[2:5]
	s_setprio 0
	s_barrier
	s_and_saveexec_b64 s[8:9], s[78:79]
	s_cbranch_execz .LBB0_389
	s_barrier

; #define LDA(dst, b, h) for (int m = 0; m < 4; ++m) for (int k = 0; k < 2; ++k) \
;     dst[m][k] = *reinterpret_cast<const bf16x8*>((char*)SA(b, h) + a_thr + (m * 2 + k) * 1024)
; #define LDB(dst, b, h) for (int n = 0; n < 2; ++n) for (int k = 0; k < 2; ++k) \
;     dst[n][k] = *reinterpret_cast<const bf16x8*>((char*)SB(b, h) + b_thr + (n * 2 + k) * 1024)
; #define MMA(ai, bj, At, Btf) do { __builtin_amdgcn_s_setprio(1); \
;     for (int m = 0; m < 4; ++m) for (int n = 0; n < 2; ++n) for (int k = 0; k < 2; ++k) \
;       acc[ai][bj][m][n] = __builtin_amdgcn_mfma_f32_16x16x32_bf16(Btf[n][k], At[m][k], acc[ai][bj][m][n], 0, 0, 0); \
;     __builtin_amdgcn_s_setprio(0); } while (0)
; #define WAIT_V(n) asm volatile("s_waitcnt vmcnt(" #n ")" ::: "memory")
; #define WAIT_L(n) asm volatile("s_waitcnt lgkmcnt(" #n ")" ::: "memory")
; #define BAR __builtin_amdgcn_s_barrier()
; #define SCHED __builtin_amdgcn_sched_barrier(0)
; template <bool OVL, bool PANEL = false, class Epi>
; __device__ __forceinline__ void gemm_phase(const bf16_t* __restrict__ A, long lda, const bf16_t* __restrict__ Bt, long ldb, int nM, int nN, int K,
;                                            const Epi& epi, bf16_t* shm, int w0) {
;     ...
;     for (int t = 0; t < nt - 2; t += 2) {
;       LDB(B0, 0, 0); SCHED; LDA(At, 0, 0); STAGE(SA(1, 1), A, lda, aoff, brow + HALF, t + 1);
;       WAIT_L(8); BAR; WAIT_L(0); MMA(0, 0, At, B0); BAR; SCHED;
;       LDB(B1, 0, 1); STAGE(SB(0, 0), Bt, ldb, boff, bcol, t + 2);
;       BAR; WAIT_L(0); MMA(0, 1, At, B1); BAR;
;       LDA(At, 0, 1); STAGE(SA(0, 0), A, lda, aoff, brow, t + 2);
;       BAR; WAIT_L(0); MMA(1, 0, At, B0); BAR; SCHED;
;       STAGE(SB(0, 1), Bt, ldb, boff, bcol + HALF, t + 2);
;       WAIT_V(6); BAR; MMA(1, 1, At, B1); BAR;
.LBB0_410:
	ds_read_b128 v[152:155], v220
	ds_read_b128 v[156:159], v220 offset:1024
	ds_read_b128 v[160:163], v220 offset:2048
	ds_read_b128 v[164:167], v220 offset:3072
	s_add_u32 s12, s8, s10
	s_addc_u32 s13, s9, s11
	ds_read_b128 v[168:171], v143
	ds_read_b128 v[172:175], v143 offset:1024
	ds_read_b128 v[176:179], v143 offset:2048
	ds_read_b128 v[180:183], v143 offset:3072
	ds_read_b128 v[184:187], v143 offset:4096
	ds_read_b128 v[188:191], v143 offset:5120
	ds_read_b128 v[192:195], v143 offset:6144
	ds_read_b128 v[196:199], v143 offset:7168
	s_mov_b32 m0, s16
	s_add_u32 s98, s12, s24
	s_addc_u32 s99, s13, s25
	global_load_lds_dwordx4 v131, s[98:99]
	s_mov_b32 m0, s23
	s_add_u32 s98, s12, s36
	s_addc_u32 s99, s13, s37
	global_load_lds_dwordx4 v131, s[98:99]
	s_waitcnt lgkmcnt(8)
	s_waitcnt vmcnt(10)
	s_barrier
	s_waitcnt lgkmcnt(0)
	s_waitcnt lgkmcnt(0)
	v_mfma_f32_16x16x32_bf16 v[126:129], v[152:155], v[168:171], v[126:129]
	v_mfma_f32_16x16x32_bf16 v[122:125], v[160:163], v[168:171], v[122:125]
	v_mfma_f32_16x16x32_bf16 v[118:121], v[152:155], v[176:179], v[118:121]
	v_mfma_f32_16x16x32_bf16 v[114:117], v[160:163], v[176:179], v[114:117]
	v_mfma_f32_16x16x32_bf16 v[110:113], v[152:155], v[184:187], v[110:113]
	v_mfma_f32_16x16x32_bf16 v[106:109], v[160:163], v[184:187], v[106:109]
	v_mfma_f32_16x16x32_bf16 v[102:105], v[152:155], v[192:195], v[102:105]
	v_mfma_f32_16x16x32_bf16 v[98:101], v[160:163], v[192:195], v[98:101]
	v_mfma_f32_16x16x32_bf16 v[126:129], v[156:159], v[172:175], v[126:129]
	v_mfma_f32_16x16x32_bf16 v[122:125], v[164:167], v[172:175], v[122:125]
	v_mfma_f32_16x16x32_bf16 v[118:121], v[156:159], v[180:183], v[118:121]
	v_mfma_f32_16x16x32_bf16 v[114:117], v[164:167], v[180:183], v[114:117]
	v_mfma_f32_16x16x32_bf16 v[110:113], v[156:159], v[188:191], v[110:113]
	v_mfma_f32_16x16x32_bf16 v[106:109], v[164:167], v[188:191], v[106:109]
	v_mfma_f32_16x16x32_bf16 v[102:105], v[156:159], v[196:199], v[102:105]
	v_mfma_f32_16x16x32_bf16 v[98:101], v[164:167], v[196:199], v[98:101]
	s_barrier
	s_add_u32 s14, s0, s10
	ds_read_b128 v[200:203], v221
	ds_read_b128 v[204:207], v221 offset:1024
	ds_read_b128 v[208:211], v221 offset:2048
	ds_read_b128 v[212:215], v221 offset:3072
	s_addc_u32 s15, s1, s11
	s_mov_b32 m0, s30
	s_add_u32 s98, s14, s34
	s_addc_u32 s99, s15, s35
	global_load_lds_dwordx4 v131, s[98:99]
	s_mov_b32 m0, s31
	s_add_u32 s98, s14, s64
	s_addc_u32 s99, s15, s65
	global_load_lds_dwordx4 v131, s[98:99]
	s_waitcnt vmcnt(10)
	s_barrier
	s_waitcnt lgkmcnt(0)
	s_waitcnt lgkmcnt(0)
	v_mfma_f32_16x16x32_bf16 v[94:97], v[200:203], v[168:171], v[94:97]
	v_mfma_f32_16x16x32_bf16 v[90:93], v[208:211], v[168:171], v[90:93]
	v_mfma_f32_16x16x32_bf16 v[86:89], v[200:203], v[176:179], v[86:89]
	v_mfma_f32_16x16x32_bf16 v[82:85], v[208:211], v[176:179], v[82:85]
	v_mfma_f32_16x16x32_bf16 v[78:81], v[200:203], v[184:187], v[78:81]
	v_mfma_f32_16x16x32_bf16 v[74:77], v[208:211], v[184:187], v[74:77]
	v_mfma_f32_16x16x32_bf16 v[70:73], v[200:203], v[192:195], v[70:73]
	v_mfma_f32_16x16x32_bf16 v[66:69], v[208:211], v[192:195], v[66:69]
	v_mfma_f32_16x16x32_bf16 v[94:97], v[204:207], v[172:175], v[94:97]
	v_mfma_f32_16x16x32_bf16 v[90:93], v[212:215], v[172:175], v[90:93]
	v_mfma_f32_16x16x32_bf16 v[86:89], v[204:207], v[180:183], v[86:89]
	v_mfma_f32_16x16x32_bf16 v[82:85], v[212:215], v[180:183], v[82:85]
	v_mfma_f32_16x16x32_bf16 v[78:81], v[204:207], v[188:191], v[78:81]
	v_mfma_f32_16x16x32_bf16 v[74:77], v[212:215], v[188:191], v[74:77]
	v_mfma_f32_16x16x32_bf16 v[70:73], v[204:207], v[196:199], v[70:73]
	v_mfma_f32_16x16x32_bf16 v[66:69], v[212:215], v[196:199], v[66:69]
	s_barrier
	ds_read_b128 v[168:171], v143 offset:16384
	ds_read_b128 v[172:175], v143 offset:17408
	ds_read_b128 v[176:179], v143 offset:18432
	ds_read_b128 v[180:183], v143 offset:19456
	ds_read_b128 v[184:187], v143 offset:20480
	ds_read_b128 v[188:191], v143 offset:21504
	ds_read_b128 v[192:195], v143 offset:22528
	ds_read_b128 v[196:199], v143 offset:23552
	s_mov_b32 m0, s32
	s_add_u32 s98, s12, s34
	s_addc_u32 s99, s13, s35
	global_load_lds_dwordx4 v131, s[98:99]
	s_mov_b32 m0, s40
	s_add_u32 s98, s12, s64
	s_addc_u32 s99, s13, s65
	global_load_lds_dwordx4 v131, s[98:99]
	s_barrier
	s_waitcnt lgkmcnt(0)
	s_waitcnt lgkmcnt(0)
	v_mfma_f32_16x16x32_bf16 v[62:65], v[152:155], v[168:171], v[62:65]
	v_mfma_f32_16x16x32_bf16 v[58:61], v[160:163], v[168:171], v[58:61]
	v_mfma_f32_16x16x32_bf16 v[54:57], v[152:155], v[176:179], v[54:57]
	v_mfma_f32_16x16x32_bf16 v[50:53], v[160:163], v[176:179], v[50:53]
	v_mfma_f32_16x16x32_bf16 v[46:49], v[152:155], v[184:187], v[46:49]
	v_mfma_f32_16x16x32_bf16 v[42:45], v[160:163], v[184:187], v[42:45]
	v_mfma_f32_16x16x32_bf16 v[38:41], v[152:155], v[192:195], v[38:41]
	v_mfma_f32_16x16x32_bf16 v[34:37], v[160:163], v[192:195], v[34:37]
	v_mfma_f32_16x16x32_bf16 v[62:65], v[156:159], v[172:175], v[62:65]
	v_mfma_f32_16x16x32_bf16 v[58:61], v[164:167], v[172:175], v[58:61]
	v_mfma_f32_16x16x32_bf16 v[54:57], v[156:159], v[180:183], v[54:57]
	v_mfma_f32_16x16x32_bf16 v[50:53], v[164:167], v[180:183], v[50:53]
	v_mfma_f32_16x16x32_bf16 v[46:49], v[156:159], v[188:191], v[46:49]
	v_mfma_f32_16x16x32_bf16 v[42:45], v[164:167], v[188:191], v[42:45]
	v_mfma_f32_16x16x32_bf16 v[38:41], v[156:159], v[196:199], v[38:41]
	v_mfma_f32_16x16x32_bf16 v[34:37], v[164:167], v[196:199], v[34:37]
	s_barrier
	s_mov_b32 m0, s41
	s_add_u32 s98, s14, s68
	s_addc_u32 s99, s15, s69
	global_load_lds_dwordx4 v131, s[98:99]
	s_mov_b32 m0, s42
	s_add_u32 s98, s14, s70
	s_addc_u32 s99, s15, s71
	global_load_lds_dwordx4 v131, s[98:99]
	s_waitcnt vmcnt(10)
	s_barrier
; #define LDA(dst, b, h) for (int m = 0; m < 4; ++m) for (int k = 0; k < 2; ++k) \
;     dst[m][k] = *reinterpret_cast<const bf16x8*>((char*)SA(b, h) + a_thr + (m * 2 + k) * 1024)
; #define LDB(dst, b, h) for (int n = 0; n < 2; ++n) for (int k = 0; k < 2; ++k) \
;     dst[n][k] = *reinterpret_cast<const bf16x8*>((char*)SB(b, h) + b_thr + (n * 2 + k) * 1024)
; #define MMA(ai, bj, At, Btf) do { __builtin_amdgcn_s_setprio(1); \
;     for (int m = 0; m < 4; ++m) for (int n = 0; n < 2; ++n) for (int k = 0; k < 2; ++k) \
;       acc[ai][bj][m][n] = __builtin_amdgcn_mfma_f32_16x16x32_bf16(Btf[n][k], At[m][k], acc[ai][bj][m][n], 0, 0, 0); \
;     __builtin_amdgcn_s_setprio(0); } while (0)
; #define WAIT_V(n) asm volatile("s_waitcnt vmcnt(" #n ")" ::: "memory")
; #define WAIT_L(n) asm volatile("s_waitcnt lgkmcnt(" #n ")" ::: "memory")
; #define BAR __builtin_amdgcn_s_barrier()
; #define SCHED __builtin_amdgcn_sched_barrier(0)
; template <bool OVL, bool PANEL = false, class Epi>
; __device__ __forceinline__ void gemm_phase(const bf16_t* __restrict__ A, long lda, const bf16_t* __restrict__ Bt, long ldb, int nM, int nN, int K,
;                                            const Epi& epi, bf16_t* shm, int w0) {
;     ...
;       WAIT_V(6); BAR; MMA(1, 1, At, B1); BAR;
;       LDB(B0, 1, 0); SCHED; LDA(At, 1, 0); STAGE(SA(0, 1), A, lda, aoff, brow + HALF, t + 2);
;       WAIT_L(8); BAR; WAIT_L(0); MMA(0, 0, At, B0); BAR; SCHED;
;       LDB(B1, 1, 1); STAGE(SB(1, 0), Bt, ldb, boff, bcol, t + 3);
;       BAR; WAIT_L(0); MMA(0, 1, At, B1); BAR;
;       LDA(At, 1, 1); STAGE(SA(1, 0), A, lda, aoff, brow, t + 3);
	v_mfma_f32_16x16x32_bf16 v[30:33], v[200:203], v[168:171], v[30:33]
	v_mfma_f32_16x16x32_bf16 v[26:29], v[208:211], v[168:171], v[26:29]
	v_mfma_f32_16x16x32_bf16 v[22:25], v[200:203], v[176:179], v[22:25]
	v_mfma_f32_16x16x32_bf16 v[18:21], v[208:211], v[176:179], v[18:21]
	v_mfma_f32_16x16x32_bf16 v[14:17], v[200:203], v[184:187], v[14:17]
	v_mfma_f32_16x16x32_bf16 v[10:13], v[208:211], v[184:187], v[10:13]
	v_mfma_f32_16x16x32_bf16 v[6:9], v[200:203], v[192:195], v[6:9]
	v_mfma_f32_16x16x32_bf16 v[2:5], v[208:211], v[192:195], v[2:5]
	v_mfma_f32_16x16x32_bf16 v[30:33], v[204:207], v[172:175], v[30:33]
	v_mfma_f32_16x16x32_bf16 v[26:29], v[212:215], v[172:175], v[26:29]
	v_mfma_f32_16x16x32_bf16 v[22:25], v[204:207], v[180:183], v[22:25]
	v_mfma_f32_16x16x32_bf16 v[18:21], v[212:215], v[180:183], v[18:21]
	v_mfma_f32_16x16x32_bf16 v[14:17], v[204:207], v[188:191], v[14:17]
	v_mfma_f32_16x16x32_bf16 v[10:13], v[212:215], v[188:191], v[10:13]
	v_mfma_f32_16x16x32_bf16 v[6:9], v[204:207], v[196:199], v[6:9]
	v_mfma_f32_16x16x32_bf16 v[2:5], v[212:215], v[196:199], v[2:5]
	s_barrier
	ds_read_b128 v[152:155], v222
	ds_read_b128 v[156:159], v222 offset:1024
	ds_read_b128 v[160:163], v222 offset:2048
	ds_read_b128 v[164:167], v222 offset:3072
	ds_read_b128 v[168:171], v143 offset:32768
	ds_read_b128 v[172:175], v143 offset:33792
	ds_read_b128 v[176:179], v143 offset:34816
	ds_read_b128 v[180:183], v143 offset:35840
	ds_read_b128 v[184:187], v143 offset:36864
	ds_read_b128 v[188:191], v143 offset:37888
	ds_read_b128 v[192:195], v143 offset:38912
	ds_read_b128 v[196:199], v143 offset:39936
	s_mov_b32 m0, s43
	s_add_u32 s98, s12, s68
	s_addc_u32 s99, s13, s69
	global_load_lds_dwordx4 v131, s[98:99]
	s_mov_b32 m0, s44
	s_add_u32 s98, s12, s70
	s_addc_u32 s99, s13, s71
	global_load_lds_dwordx4 v131, s[98:99]
	s_waitcnt lgkmcnt(8)
	s_waitcnt vmcnt(10)
	s_barrier
	s_waitcnt lgkmcnt(0)
	s_waitcnt lgkmcnt(0)
	v_mfma_f32_16x16x32_bf16 v[126:129], v[152:155], v[168:171], v[126:129]
	v_mfma_f32_16x16x32_bf16 v[122:125], v[160:163], v[168:171], v[122:125]
	v_mfma_f32_16x16x32_bf16 v[118:121], v[152:155], v[176:179], v[118:121]
	v_mfma_f32_16x16x32_bf16 v[114:117], v[160:163], v[176:179], v[114:117]
	v_mfma_f32_16x16x32_bf16 v[110:113], v[152:155], v[184:187], v[110:113]
	v_mfma_f32_16x16x32_bf16 v[106:109], v[160:163], v[184:187], v[106:109]
	v_mfma_f32_16x16x32_bf16 v[102:105], v[152:155], v[192:195], v[102:105]
	v_mfma_f32_16x16x32_bf16 v[98:101], v[160:163], v[192:195], v[98:101]
	v_mfma_f32_16x16x32_bf16 v[126:129], v[156:159], v[172:175], v[126:129]
	v_mfma_f32_16x16x32_bf16 v[122:125], v[164:167], v[172:175], v[122:125]
	v_mfma_f32_16x16x32_bf16 v[118:121], v[156:159], v[180:183], v[118:121]
	v_mfma_f32_16x16x32_bf16 v[114:117], v[164:167], v[180:183], v[114:117]
	v_mfma_f32_16x16x32_bf16 v[110:113], v[156:159], v[188:191], v[110:113]
	v_mfma_f32_16x16x32_bf16 v[106:109], v[164:167], v[188:191], v[106:109]
	v_mfma_f32_16x16x32_bf16 v[102:105], v[156:159], v[196:199], v[102:105]
	v_mfma_f32_16x16x32_bf16 v[98:101], v[164:167], v[196:199], v[98:101]
	s_barrier
	ds_read_b128 v[200:203], v223
	ds_read_b128 v[204:207], v223 offset:1024
	ds_read_b128 v[208:211], v223 offset:2048
	ds_read_b128 v[212:215], v223 offset:3072
	s_mov_b32 m0, s45
	s_add_u32 s98, s14, s94
	s_addc_u32 s99, s15, s95
	global_load_lds_dwordx4 v131, s[98:99]
	s_mov_b32 m0, s46
	s_add_u32 s98, s14, s72
	s_addc_u32 s99, s15, s73
	global_load_lds_dwordx4 v131, s[98:99]
	s_waitcnt vmcnt(10)
	s_barrier
	s_waitcnt lgkmcnt(0)
	s_waitcnt lgkmcnt(0)
	v_mfma_f32_16x16x32_bf16 v[94:97], v[200:203], v[168:171], v[94:97]
	v_mfma_f32_16x16x32_bf16 v[90:93], v[208:211], v[168:171], v[90:93]
	v_mfma_f32_16x16x32_bf16 v[86:89], v[200:203], v[176:179], v[86:89]
	v_mfma_f32_16x16x32_bf16 v[82:85], v[208:211], v[176:179], v[82:85]
	v_mfma_f32_16x16x32_bf16 v[78:81], v[200:203], v[184:187], v[78:81]
	v_mfma_f32_16x16x32_bf16 v[74:77], v[208:211], v[184:187], v[74:77]
	v_mfma_f32_16x16x32_bf16 v[70:73], v[200:203], v[192:195], v[70:73]
	v_mfma_f32_16x16x32_bf16 v[66:69], v[208:211], v[192:195], v[66:69]
	v_mfma_f32_16x16x32_bf16 v[94:97], v[204:207], v[172:175], v[94:97]
	v_mfma_f32_16x16x32_bf16 v[90:93], v[212:215], v[172:175], v[90:93]
	v_mfma_f32_16x16x32_bf16 v[86:89], v[204:207], v[180:183], v[86:89]
	v_mfma_f32_16x16x32_bf16 v[82:85], v[212:215], v[180:183], v[82:85]
	v_mfma_f32_16x16x32_bf16 v[78:81], v[204:207], v[188:191], v[78:81]
	v_mfma_f32_16x16x32_bf16 v[74:77], v[212:215], v[188:191], v[74:77]
	v_mfma_f32_16x16x32_bf16 v[70:73], v[204:207], v[196:199], v[70:73]
	v_mfma_f32_16x16x32_bf16 v[66:69], v[212:215], v[196:199], v[66:69]
	s_barrier
	ds_read_b128 v[168:171], v143 offset:49152
	ds_read_b128 v[172:175], v143 offset:50176
	ds_read_b128 v[176:179], v143 offset:51200
	ds_read_b128 v[180:183], v143 offset:52224
	ds_read_b128 v[184:187], v143 offset:53248
	ds_read_b128 v[188:191], v143 offset:54272
	ds_read_b128 v[192:195], v143 offset:55296
	ds_read_b128 v[196:199], v143 offset:56320
	s_mov_b32 m0, s47
	s_add_u32 s98, s12, s94
	s_addc_u32 s99, s13, s95
	global_load_lds_dwordx4 v131, s[98:99]
	s_mov_b32 m0, s48
	s_add_u32 s98, s12, s72
	s_addc_u32 s99, s13, s73
	global_load_lds_dwordx4 v131, s[98:99]
	s_barrier
; #define LDA(dst, b, h) for (int m = 0; m < 4; ++m) for (int k = 0; k < 2; ++k) \
;     dst[m][k] = *reinterpret_cast<const bf16x8*>((char*)SA(b, h) + a_thr + (m * 2 + k) * 1024)
; #define LDB(dst, b, h) for (int n = 0; n < 2; ++n) for (int k = 0; k < 2; ++k) \
;     dst[n][k] = *reinterpret_cast<const bf16x8*>((char*)SB(b, h) + b_thr + (n * 2 + k) * 1024)
; #define MMA(ai, bj, At, Btf) do { __builtin_amdgcn_s_setprio(1); \
;     for (int m = 0; m < 4; ++m) for (int n = 0; n < 2; ++n) for (int k = 0; k < 2; ++k) \
;       acc[ai][bj][m][n] = __builtin_amdgcn_mfma_f32_16x16x32_bf16(Btf[n][k], At[m][k], acc[ai][bj][m][n], 0, 0, 0); \
;     __builtin_amdgcn_s_setprio(0); } while (0)
; #define WAIT_V(n) asm volatile("s_waitcnt vmcnt(" #n ")" ::: "memory")
; #define WAIT_L(n) asm volatile("s_waitcnt lgkmcnt(" #n ")" ::: "memory")
; #define BAR __builtin_amdgcn_s_barrier()
; #define SCHED __builtin_amdgcn_sched_barrier(0)
; template <bool OVL, bool PANEL = false, class Epi>
; __device__ __forceinline__ void gemm_phase(const bf16_t* __restrict__ A, long lda, const bf16_t* __restrict__ Bt, long ldb, int nM, int nN, int K,
;                                            const Epi& epi, bf16_t* shm, int w0) {
;     ...
;       BAR; WAIT_L(0); MMA(1, 0, At, B0); BAR; SCHED;
;       STAGE(SB(1, 1), Bt, ldb, boff, bcol + HALF, t + 3);
;       WAIT_V(6); BAR; MMA(1, 1, At, B1); BAR;
;     }
;     { LDB(B0, 0, 0); LDA(At, 0, 0); STAGE(SA(1, 1), A, lda, aoff, brow + HALF, nt - 1);
;       BAR; WAIT_L(0); MMA(0, 0, At, B0); BAR;
;       LDB(B1, 0, 1); BAR; WAIT_L(0); MMA(0, 1, At, B1); BAR;
	s_waitcnt lgkmcnt(0)
	s_waitcnt lgkmcnt(0)
	v_mfma_f32_16x16x32_bf16 v[62:65], v[152:155], v[168:171], v[62:65]
	v_mfma_f32_16x16x32_bf16 v[58:61], v[160:163], v[168:171], v[58:61]
	v_mfma_f32_16x16x32_bf16 v[54:57], v[152:155], v[176:179], v[54:57]
	v_mfma_f32_16x16x32_bf16 v[50:53], v[160:163], v[176:179], v[50:53]
	v_mfma_f32_16x16x32_bf16 v[46:49], v[152:155], v[184:187], v[46:49]
	v_mfma_f32_16x16x32_bf16 v[42:45], v[160:163], v[184:187], v[42:45]
	v_mfma_f32_16x16x32_bf16 v[38:41], v[152:155], v[192:195], v[38:41]
	v_mfma_f32_16x16x32_bf16 v[34:37], v[160:163], v[192:195], v[34:37]
	v_mfma_f32_16x16x32_bf16 v[62:65], v[156:159], v[172:175], v[62:65]
	v_mfma_f32_16x16x32_bf16 v[58:61], v[164:167], v[172:175], v[58:61]
	v_mfma_f32_16x16x32_bf16 v[54:57], v[156:159], v[180:183], v[54:57]
	v_mfma_f32_16x16x32_bf16 v[50:53], v[164:167], v[180:183], v[50:53]
	v_mfma_f32_16x16x32_bf16 v[46:49], v[156:159], v[188:191], v[46:49]
	v_mfma_f32_16x16x32_bf16 v[42:45], v[164:167], v[188:191], v[42:45]
	v_mfma_f32_16x16x32_bf16 v[38:41], v[156:159], v[196:199], v[38:41]
	v_mfma_f32_16x16x32_bf16 v[34:37], v[164:167], v[196:199], v[34:37]
	s_barrier
	s_mov_b32 m0, s49
	s_add_u32 s98, s14, s26
	s_addc_u32 s99, s15, s27
	global_load_lds_dwordx4 v131, s[98:99]
	s_mov_b32 m0, s50
	s_add_u32 s98, s14, s28
	s_addc_u32 s99, s15, s29
	global_load_lds_dwordx4 v131, s[98:99]
	s_waitcnt vmcnt(10)
	s_barrier
	v_mfma_f32_16x16x32_bf16 v[30:33], v[200:203], v[168:171], v[30:33]
	v_mfma_f32_16x16x32_bf16 v[26:29], v[208:211], v[168:171], v[26:29]
	v_mfma_f32_16x16x32_bf16 v[22:25], v[200:203], v[176:179], v[22:25]
	v_mfma_f32_16x16x32_bf16 v[18:21], v[208:211], v[176:179], v[18:21]
	v_mfma_f32_16x16x32_bf16 v[14:17], v[200:203], v[184:187], v[14:17]
	v_mfma_f32_16x16x32_bf16 v[10:13], v[208:211], v[184:187], v[10:13]
	v_mfma_f32_16x16x32_bf16 v[6:9], v[200:203], v[192:195], v[6:9]
	v_mfma_f32_16x16x32_bf16 v[2:5], v[208:211], v[192:195], v[2:5]
	v_mfma_f32_16x16x32_bf16 v[30:33], v[204:207], v[172:175], v[30:33]
	v_mfma_f32_16x16x32_bf16 v[26:29], v[212:215], v[172:175], v[26:29]
	v_mfma_f32_16x16x32_bf16 v[22:25], v[204:207], v[180:183], v[22:25]
	v_mfma_f32_16x16x32_bf16 v[18:21], v[212:215], v[180:183], v[18:21]
	v_mfma_f32_16x16x32_bf16 v[14:17], v[204:207], v[188:191], v[14:17]
	v_mfma_f32_16x16x32_bf16 v[10:13], v[212:215], v[188:191], v[10:13]
	v_mfma_f32_16x16x32_bf16 v[6:9], v[204:207], v[196:199], v[6:9]
	v_mfma_f32_16x16x32_bf16 v[2:5], v[212:215], v[196:199], v[2:5]
	s_add_i32 s21, s21, 2
	s_add_u32 s10, s10, 0x100
	s_addc_u32 s11, s11, 0
	s_cmp_lt_u32 s21, 12
	s_barrier
	s_cbranch_scc1 .LBB0_410
	s_waitcnt vmcnt(6)
	v_add_u32_e32 v212, 16, v140
	v_add_u32_e32 v0, 0x10000, v212
	ds_read_b128 v[144:147], v0
	ds_read_b128 v[152:155], v0 offset:1024
	ds_read_b128 v[156:159], v0 offset:2048
	ds_read_b128 v[160:163], v0 offset:3072
	ds_read_b128 v[164:167], v143
	ds_read_b128 v[168:171], v143 offset:1024
	ds_read_b128 v[172:175], v143 offset:2048
	ds_read_b128 v[176:179], v143 offset:3072
	ds_read_b128 v[180:183], v143 offset:4096
	ds_read_b128 v[184:187], v143 offset:5120
	ds_read_b128 v[188:191], v143 offset:6144
	ds_read_b128 v[192:195], v143 offset:7168
	v_mov_b32_e32 v0, v131
	s_mov_b64 s[0:1], 0x40780
	v_lshl_add_u64 v[148:149], s[8:9], 0, v[0:1]
	v_lshl_add_u64 v[196:197], v[148:149], 0, s[0:1]
	v_readfirstlane_b32 s0, v150
	s_mov_b32 m0, s0
	s_mov_b64 s[0:1], 0x60780
	v_lshl_add_u64 v[148:149], v[148:149], 0, s[0:1]
	v_readfirstlane_b32 s0, v151
	global_load_lds_dwordx4 v[196:197], off
	s_mov_b32 m0, s0
	s_nop 0
	global_load_lds_dwordx4 v[148:149], off
	s_barrier
	s_waitcnt lgkmcnt(0)
	s_setprio 1
	s_waitcnt lgkmcnt(0)
	v_mfma_f32_16x16x32_bf16 v[126:129], v[144:147], v[164:167], v[126:129]
	v_mfma_f32_16x16x32_bf16 v[122:125], v[156:159], v[164:167], v[122:125]
	v_mfma_f32_16x16x32_bf16 v[118:121], v[144:147], v[172:175], v[118:121]
	v_mfma_f32_16x16x32_bf16 v[114:117], v[156:159], v[172:175], v[114:117]
	v_mfma_f32_16x16x32_bf16 v[110:113], v[144:147], v[180:183], v[110:113]
	v_mfma_f32_16x16x32_bf16 v[106:109], v[156:159], v[180:183], v[106:109]
	v_mfma_f32_16x16x32_bf16 v[102:105], v[144:147], v[188:191], v[102:105]
	v_mfma_f32_16x16x32_bf16 v[126:129], v[152:155], v[168:171], v[126:129]
	v_mfma_f32_16x16x32_bf16 v[122:125], v[160:163], v[168:171], v[122:125]
	v_mfma_f32_16x16x32_bf16 v[118:121], v[152:155], v[176:179], v[118:121]
	v_mfma_f32_16x16x32_bf16 v[114:117], v[160:163], v[176:179], v[114:117]
	v_mfma_f32_16x16x32_bf16 v[110:113], v[152:155], v[184:187], v[110:113]
	v_mfma_f32_16x16x32_bf16 v[106:109], v[160:163], v[184:187], v[106:109]
	v_mfma_f32_16x16x32_bf16 v[102:105], v[152:155], v[192:195], v[102:105]
	v_mfma_f32_16x16x32_bf16 v[98:101], v[156:159], v[188:191], v[98:101]
	v_mfma_f32_16x16x32_bf16 v[148:151], v[160:163], v[192:195], v[98:101]
	s_setprio 0
	v_add_u32_e32 v0, 0x14000, v212
	s_barrier
	s_nop 3
	ds_read_b128 v[98:101], v0
	ds_read_b128 v[196:199], v0 offset:1024
	ds_read_b128 v[200:203], v0 offset:2048
	ds_read_b128 v[204:207], v0 offset:3072
	s_barrier
; #define LDA(dst, b, h) for (int m = 0; m < 4; ++m) for (int k = 0; k < 2; ++k) \
;     dst[m][k] = *reinterpret_cast<const bf16x8*>((char*)SA(b, h) + a_thr + (m * 2 + k) * 1024)
; #define LDB(dst, b, h) for (int n = 0; n < 2; ++n) for (int k = 0; k < 2; ++k) \
;     dst[n][k] = *reinterpret_cast<const bf16x8*>((char*)SB(b, h) + b_thr + (n * 2 + k) * 1024)
; #define MMA(ai, bj, At, Btf) do { __builtin_amdgcn_s_setprio(1); \
;     for (int m = 0; m < 4; ++m) for (int n = 0; n < 2; ++n) for (int k = 0; k < 2; ++k) \
;       acc[ai][bj][m][n] = __builtin_amdgcn_mfma_f32_16x16x32_bf16(Btf[n][k], At[m][k], acc[ai][bj][m][n], 0, 0, 0); \
;     __builtin_amdgcn_s_setprio(0); } while (0)
; #define WAIT_V(n) asm volatile("s_waitcnt vmcnt(" #n ")" ::: "memory")
; #define WAIT_L(n) asm volatile("s_waitcnt lgkmcnt(" #n ")" ::: "memory")
; #define BAR __builtin_amdgcn_s_barrier()
; template <bool OVL, bool PANEL = false, class Epi>
; __device__ __forceinline__ void gemm_phase(const bf16_t* __restrict__ A, long lda, const bf16_t* __restrict__ Bt, long ldb, int nM, int nN, int K,
;                                            const Epi& epi, bf16_t* shm, int w0) {
;     ...
;       LDB(B1, 0, 1); BAR; WAIT_L(0); MMA(0, 1, At, B1); BAR;
;       LDA(At, 0, 1); WAIT_V(4); BAR; WAIT_L(0); MMA(1, 0, At, B0); MMA(1, 1, At, B1); BAR; }
;     { LDB(B0, 1, 0); LDA(At, 1, 0); WAIT_V(2); BAR; WAIT_L(0); MMA(0, 0, At, B0); BAR;
	s_waitcnt lgkmcnt(0)
	s_setprio 1
	s_waitcnt lgkmcnt(0)
	v_mfma_f32_16x16x32_bf16 v[94:97], v[98:101], v[164:167], v[94:97]
	v_mfma_f32_16x16x32_bf16 v[86:89], v[98:101], v[172:175], v[86:89]
	v_mfma_f32_16x16x32_bf16 v[82:85], v[200:203], v[172:175], v[82:85]
	v_mfma_f32_16x16x32_bf16 v[78:81], v[98:101], v[180:183], v[78:81]
	v_mfma_f32_16x16x32_bf16 v[74:77], v[200:203], v[180:183], v[74:77]
	v_mfma_f32_16x16x32_bf16 v[94:97], v[196:199], v[168:171], v[94:97]
	v_mfma_f32_16x16x32_bf16 v[90:93], v[200:203], v[164:167], v[90:93]
	v_mfma_f32_16x16x32_bf16 v[86:89], v[196:199], v[176:179], v[86:89]
	v_mfma_f32_16x16x32_bf16 v[82:85], v[204:207], v[176:179], v[82:85]
	v_mfma_f32_16x16x32_bf16 v[78:81], v[196:199], v[184:187], v[78:81]
	v_mfma_f32_16x16x32_bf16 v[74:77], v[204:207], v[184:187], v[74:77]
	v_mfma_f32_16x16x32_bf16 v[70:73], v[98:101], v[188:191], v[70:73]
	v_mfma_f32_16x16x32_bf16 v[66:69], v[200:203], v[188:191], v[66:69]
	v_mfma_f32_16x16x32_bf16 v[164:167], v[204:207], v[168:171], v[90:93]
	v_mfma_f32_16x16x32_bf16 v[168:171], v[196:199], v[192:195], v[70:73]
	v_mfma_f32_16x16x32_bf16 v[172:175], v[204:207], v[192:195], v[66:69]
	s_setprio 0
	s_barrier
	s_nop 2
	ds_read_b128 v[66:69], v143 offset:16384
	ds_read_b128 v[70:73], v143 offset:17408
	ds_read_b128 v[90:93], v143 offset:18432
	ds_read_b128 v[176:179], v143 offset:19456
	ds_read_b128 v[180:183], v143 offset:20480
	ds_read_b128 v[184:187], v143 offset:21504
	ds_read_b128 v[188:191], v143 offset:22528
	ds_read_b128 v[192:195], v143 offset:23552
	s_waitcnt vmcnt(4)
	s_barrier
	s_waitcnt lgkmcnt(0)
	s_setprio 1
	s_waitcnt lgkmcnt(0)
	v_mfma_f32_16x16x32_bf16 v[62:65], v[144:147], v[66:69], v[62:65]
	v_mfma_f32_16x16x32_bf16 v[54:57], v[144:147], v[90:93], v[54:57]
	v_mfma_f32_16x16x32_bf16 v[50:53], v[156:159], v[90:93], v[50:53]
	v_mfma_f32_16x16x32_bf16 v[46:49], v[144:147], v[180:183], v[46:49]
	v_mfma_f32_16x16x32_bf16 v[42:45], v[156:159], v[180:183], v[42:45]
	v_mfma_f32_16x16x32_bf16 v[38:41], v[144:147], v[188:191], v[38:41]
	v_mfma_f32_16x16x32_bf16 v[34:37], v[156:159], v[188:191], v[34:37]
	v_mfma_f32_16x16x32_bf16 v[62:65], v[152:155], v[70:73], v[62:65]
	v_mfma_f32_16x16x32_bf16 v[58:61], v[156:159], v[66:69], v[58:61]
	v_mfma_f32_16x16x32_bf16 v[54:57], v[152:155], v[176:179], v[54:57]
	v_mfma_f32_16x16x32_bf16 v[50:53], v[160:163], v[176:179], v[50:53]
	v_mfma_f32_16x16x32_bf16 v[46:49], v[152:155], v[184:187], v[46:49]
	v_mfma_f32_16x16x32_bf16 v[42:45], v[160:163], v[184:187], v[42:45]
	v_mfma_f32_16x16x32_bf16 v[38:41], v[152:155], v[192:195], v[38:41]
	v_mfma_f32_16x16x32_bf16 v[34:37], v[160:163], v[192:195], v[34:37]
	v_mfma_f32_16x16x32_bf16 v[208:211], v[160:163], v[70:73], v[58:61]
	s_setprio 0
	s_setprio 1
	v_mfma_f32_16x16x32_bf16 v[30:33], v[98:101], v[66:69], v[30:33]
	v_mfma_f32_16x16x32_bf16 v[26:29], v[200:203], v[66:69], v[26:29]
	v_mfma_f32_16x16x32_bf16 v[22:25], v[98:101], v[90:93], v[22:25]
	v_mfma_f32_16x16x32_bf16 v[18:21], v[200:203], v[90:93], v[18:21]
	v_mfma_f32_16x16x32_bf16 v[14:17], v[98:101], v[180:183], v[14:17]
	v_mfma_f32_16x16x32_bf16 v[10:13], v[200:203], v[180:183], v[10:13]
	v_mfma_f32_16x16x32_bf16 v[6:9], v[98:101], v[188:191], v[6:9]
	v_mfma_f32_16x16x32_bf16 v[2:5], v[200:203], v[188:191], v[2:5]
	v_mfma_f32_16x16x32_bf16 v[30:33], v[196:199], v[70:73], v[30:33]
	v_mfma_f32_16x16x32_bf16 v[26:29], v[204:207], v[70:73], v[26:29]
	v_mfma_f32_16x16x32_bf16 v[22:25], v[196:199], v[176:179], v[22:25]
	v_mfma_f32_16x16x32_bf16 v[18:21], v[204:207], v[176:179], v[18:21]
	v_mfma_f32_16x16x32_bf16 v[14:17], v[196:199], v[184:187], v[14:17]
	v_mfma_f32_16x16x32_bf16 v[10:13], v[204:207], v[184:187], v[10:13]
	v_mfma_f32_16x16x32_bf16 v[6:9], v[196:199], v[192:195], v[6:9]
	v_mfma_f32_16x16x32_bf16 v[2:5], v[204:207], v[192:195], v[2:5]
	s_setprio 0
	v_add_u32_e32 v0, 0x18000, v212
	s_barrier
	ds_read_b128 v[144:147], v0
	ds_read_b128 v[152:155], v0 offset:1024
	ds_read_b128 v[156:159], v0 offset:2048
	ds_read_b128 v[160:163], v0 offset:3072
	ds_read_b128 v[58:61], v143 offset:32768
	ds_read_b128 v[66:69], v143 offset:33792
	ds_read_b128 v[70:73], v143 offset:34816
	ds_read_b128 v[176:179], v143 offset:35840
	ds_read_b128 v[180:183], v143 offset:36864
	ds_read_b128 v[184:187], v143 offset:37888
	ds_read_b128 v[188:191], v143 offset:38912
	ds_read_b128 v[192:195], v143 offset:39936
	s_waitcnt vmcnt(2)
	s_barrier
; #define LDA(dst, b, h) for (int m = 0; m < 4; ++m) for (int k = 0; k < 2; ++k) \
;     dst[m][k] = *reinterpret_cast<const bf16x8*>((char*)SA(b, h) + a_thr + (m * 2 + k) * 1024)
; #define LDB(dst, b, h) for (int n = 0; n < 2; ++n) for (int k = 0; k < 2; ++k) \
;     dst[n][k] = *reinterpret_cast<const bf16x8*>((char*)SB(b, h) + b_thr + (n * 2 + k) * 1024)
; #define MMA(ai, bj, At, Btf) do { __builtin_amdgcn_s_setprio(1); \
;     for (int m = 0; m < 4; ++m) for (int n = 0; n < 2; ++n) for (int k = 0; k < 2; ++k) \
;       acc[ai][bj][m][n] = __builtin_amdgcn_mfma_f32_16x16x32_bf16(Btf[n][k], At[m][k], acc[ai][bj][m][n], 0, 0, 0); \
;     __builtin_amdgcn_s_setprio(0); } while (0)
; #define WAIT_V(n) asm volatile("s_waitcnt vmcnt(" #n ")" ::: "memory")
; #define WAIT_L(n) asm volatile("s_waitcnt lgkmcnt(" #n ")" ::: "memory")
; #define BAR __builtin_amdgcn_s_barrier()
; template <bool OVL, bool PANEL = false, class Epi>
; __device__ __forceinline__ void gemm_phase(const bf16_t* __restrict__ A, long lda, const bf16_t* __restrict__ Bt, long ldb, int nM, int nN, int K,
;                                            const Epi& epi, bf16_t* shm, int w0) {
;     ...
;     { LDB(B0, 1, 0); LDA(At, 1, 0); WAIT_V(2); BAR; WAIT_L(0); MMA(0, 0, At, B0); BAR;
;       LDB(B1, 1, 1); WAIT_V(0); BAR; WAIT_L(0); MMA(0, 1, At, B1); BAR;
;       LDA(At, 1, 1); BAR; WAIT_L(0); MMA(1, 0, At, B0); MMA(1, 1, At, B1); BAR; }
;     if (wr == 0) BAR;
	s_waitcnt lgkmcnt(0)
	s_setprio 1
	s_waitcnt lgkmcnt(0)
	v_mfma_f32_16x16x32_bf16 v[90:93], v[144:147], v[58:61], v[126:129]
	v_mfma_f32_16x16x32_bf16 v[126:129], v[152:155], v[66:69], v[90:93]
	v_mfma_f32_16x16x32_bf16 v[90:93], v[156:159], v[58:61], v[122:125]
	v_mfma_f32_16x16x32_bf16 v[122:125], v[160:163], v[66:69], v[90:93]
	v_mfma_f32_16x16x32_bf16 v[90:93], v[144:147], v[70:73], v[118:121]
	v_mfma_f32_16x16x32_bf16 v[118:121], v[152:155], v[176:179], v[90:93]
	v_mfma_f32_16x16x32_bf16 v[90:93], v[156:159], v[70:73], v[114:117]
	v_mfma_f32_16x16x32_bf16 v[114:117], v[160:163], v[176:179], v[90:93]
	v_mfma_f32_16x16x32_bf16 v[90:93], v[144:147], v[180:183], v[110:113]
	v_mfma_f32_16x16x32_bf16 v[110:113], v[152:155], v[184:187], v[90:93]
	v_mfma_f32_16x16x32_bf16 v[90:93], v[156:159], v[180:183], v[106:109]
	v_mfma_f32_16x16x32_bf16 v[106:109], v[160:163], v[184:187], v[90:93]
	v_mfma_f32_16x16x32_bf16 v[90:93], v[144:147], v[188:191], v[102:105]
	v_mfma_f32_16x16x32_bf16 v[98:101], v[152:155], v[192:195], v[90:93]
	v_mfma_f32_16x16x32_bf16 v[90:93], v[156:159], v[188:191], v[148:151]
	v_mfma_f32_16x16x32_bf16 v[90:93], v[160:163], v[192:195], v[90:93]
	s_setprio 0
	v_add_u32_e32 v0, 0x1c000, v212
	s_barrier
	ds_read_b128 v[148:151], v0
	ds_read_b128 v[196:199], v0 offset:1024
	ds_read_b128 v[200:203], v0 offset:2048
	ds_read_b128 v[204:207], v0 offset:3072
	s_waitcnt vmcnt(0)
	s_barrier
	s_waitcnt lgkmcnt(0)
	s_setprio 1
	s_waitcnt lgkmcnt(0)
	v_mfma_f32_16x16x32_bf16 v[94:97], v[148:151], v[58:61], v[94:97]
	v_mfma_f32_16x16x32_bf16 v[58:61], v[200:203], v[58:61], v[164:167]
	v_mfma_f32_16x16x32_bf16 v[102:105], v[196:199], v[66:69], v[94:97]
	v_mfma_f32_16x16x32_bf16 v[94:97], v[204:207], v[66:69], v[58:61]
	v_mfma_f32_16x16x32_bf16 v[58:61], v[148:151], v[70:73], v[86:89]
	v_mfma_f32_16x16x32_bf16 v[86:89], v[196:199], v[176:179], v[58:61]
	v_mfma_f32_16x16x32_bf16 v[58:61], v[200:203], v[70:73], v[82:85]
	v_mfma_f32_16x16x32_bf16 v[82:85], v[204:207], v[176:179], v[58:61]
	v_mfma_f32_16x16x32_bf16 v[58:61], v[148:151], v[180:183], v[78:81]
	v_mfma_f32_16x16x32_bf16 v[78:81], v[196:199], v[184:187], v[58:61]
	v_mfma_f32_16x16x32_bf16 v[58:61], v[200:203], v[180:183], v[74:77]
	v_mfma_f32_16x16x32_bf16 v[70:73], v[204:207], v[184:187], v[58:61]
	v_mfma_f32_16x16x32_bf16 v[58:61], v[148:151], v[188:191], v[168:171]
	v_mfma_f32_16x16x32_bf16 v[66:69], v[196:199], v[192:195], v[58:61]
	v_mfma_f32_16x16x32_bf16 v[58:61], v[200:203], v[188:191], v[172:175]
	v_mfma_f32_16x16x32_bf16 v[58:61], v[204:207], v[192:195], v[58:61]
	s_setprio 0
	s_barrier
	ds_read_b128 v[164:167], v143 offset:49152
	ds_read_b128 v[168:171], v143 offset:50176
	ds_read_b128 v[172:175], v143 offset:51200
	ds_read_b128 v[176:179], v143 offset:52224
	ds_read_b128 v[180:183], v143 offset:53248
	ds_read_b128 v[184:187], v143 offset:54272
	ds_read_b128 v[188:191], v143 offset:55296
	ds_read_b128 v[192:195], v143 offset:56320
	s_barrier
	s_waitcnt lgkmcnt(0)
	s_setprio 1
	s_waitcnt lgkmcnt(0)
	v_mfma_f32_16x16x32_bf16 v[62:65], v[144:147], v[164:167], v[62:65]
	v_mfma_f32_16x16x32_bf16 v[74:77], v[152:155], v[168:171], v[62:65]
	v_mfma_f32_16x16x32_bf16 v[62:65], v[156:159], v[164:167], v[208:211]
	v_mfma_f32_16x16x32_bf16 v[54:57], v[144:147], v[172:175], v[54:57]
	v_mfma_f32_16x16x32_bf16 v[50:53], v[156:159], v[172:175], v[50:53]
	v_mfma_f32_16x16x32_bf16 v[46:49], v[144:147], v[180:183], v[46:49]
	v_mfma_f32_16x16x32_bf16 v[42:45], v[156:159], v[180:183], v[42:45]
	v_mfma_f32_16x16x32_bf16 v[38:41], v[144:147], v[188:191], v[38:41]
	v_mfma_f32_16x16x32_bf16 v[34:37], v[156:159], v[188:191], v[34:37]
	v_mfma_f32_16x16x32_bf16 v[62:65], v[160:163], v[168:171], v[62:65]
	v_mfma_f32_16x16x32_bf16 v[54:57], v[152:155], v[176:179], v[54:57]
	v_mfma_f32_16x16x32_bf16 v[50:53], v[160:163], v[176:179], v[50:53]
	v_mfma_f32_16x16x32_bf16 v[46:49], v[152:155], v[184:187], v[46:49]
	v_mfma_f32_16x16x32_bf16 v[42:45], v[160:163], v[184:187], v[42:45]
	v_mfma_f32_16x16x32_bf16 v[38:41], v[152:155], v[192:195], v[38:41]
	v_mfma_f32_16x16x32_bf16 v[34:37], v[160:163], v[192:195], v[34:37]
	s_setprio 0
	s_setprio 1
	v_mfma_f32_16x16x32_bf16 v[30:33], v[148:151], v[164:167], v[30:33]
	v_mfma_f32_16x16x32_bf16 v[26:29], v[200:203], v[164:167], v[26:29]
	v_mfma_f32_16x16x32_bf16 v[22:25], v[148:151], v[172:175], v[22:25]
	v_mfma_f32_16x16x32_bf16 v[18:21], v[200:203], v[172:175], v[18:21]
	v_mfma_f32_16x16x32_bf16 v[14:17], v[148:151], v[180:183], v[14:17]
	v_mfma_f32_16x16x32_bf16 v[10:13], v[200:203], v[180:183], v[10:13]
	v_mfma_f32_16x16x32_bf16 v[6:9], v[148:151], v[188:191], v[6:9]
	v_mfma_f32_16x16x32_bf16 v[2:5], v[200:203], v[188:191], v[2:5]
	v_mfma_f32_16x16x32_bf16 v[30:33], v[196:199], v[168:171], v[30:33]
	v_mfma_f32_16x16x32_bf16 v[26:29], v[204:207], v[168:171], v[26:29]
	v_mfma_f32_16x16x32_bf16 v[22:25], v[196:199], v[176:179], v[22:25]
	v_mfma_f32_16x16x32_bf16 v[18:21], v[204:207], v[176:179], v[18:21]
	v_mfma_f32_16x16x32_bf16 v[14:17], v[196:199], v[184:187], v[14:17]
	v_mfma_f32_16x16x32_bf16 v[10:13], v[204:207], v[184:187], v[10:13]
	v_mfma_f32_16x16x32_bf16 v[6:9], v[196:199], v[192:195], v[6:9]
	v_mfma_f32_16x16x32_bf16 v[2:5], v[204:207], v[192:195], v[2:5]
	s_setprio 0
	s_barrier
	s_and_saveexec_b64 s[0:1], s[6:7]
	s_cbranch_execz .LBB0_413
	s_barrier

; #define LDA(dst, b, h) for (int m = 0; m < 4; ++m) for (int k = 0; k < 2; ++k) \
;     dst[m][k] = *reinterpret_cast<const bf16x8*>((char*)SA(b, h) + a_thr + (m * 2 + k) * 1024)
; #define LDB(dst, b, h) for (int n = 0; n < 2; ++n) for (int k = 0; k < 2; ++k) \
;     dst[n][k] = *reinterpret_cast<const bf16x8*>((char*)SB(b, h) + b_thr + (n * 2 + k) * 1024)
; #define MMA(ai, bj, At, Btf) do { __builtin_amdgcn_s_setprio(1); \
;     for (int m = 0; m < 4; ++m) for (int n = 0; n < 2; ++n) for (int k = 0; k < 2; ++k) \
;       acc[ai][bj][m][n] = __builtin_amdgcn_mfma_f32_16x16x32_bf16(Btf[n][k], At[m][k], acc[ai][bj][m][n], 0, 0, 0); \
;     __builtin_amdgcn_s_setprio(0); } while (0)
; #define WAIT_V(n) asm volatile("s_waitcnt vmcnt(" #n ")" ::: "memory")
; #define WAIT_L(n) asm volatile("s_waitcnt lgkmcnt(" #n ")" ::: "memory")
; #define BAR __builtin_amdgcn_s_barrier()
; #define SCHED __builtin_amdgcn_sched_barrier(0)
; template <bool OVL, bool PANEL = false, class Epi>
; __device__ __forceinline__ void gemm_phase(const bf16_t* __restrict__ A, long lda, const bf16_t* __restrict__ Bt, long ldb, int nM, int nN, int K,
;                                            const Epi& epi, bf16_t* shm, int w0) {
;     ...
;       LDB(B0, 0, 0); SCHED; LDA(At, 0, 0); STAGE(SA(1, 1), A, lda, aoff, brow + HALF, t + 1);
;       WAIT_L(8); BAR; WAIT_L(0); MMA(0, 0, At, B0); BAR; SCHED;
;       LDB(B1, 0, 1); STAGE(SB(0, 0), Bt, ldb, boff, bcol, t + 2);
;       BAR; WAIT_L(0); MMA(0, 1, At, B1); BAR;
;       LDA(At, 0, 1); STAGE(SA(0, 0), A, lda, aoff, brow, t + 2);
;       BAR; WAIT_L(0); MMA(1, 0, At, B0); BAR; SCHED;
;       STAGE(SB(0, 1), Bt, ldb, boff, bcol + HALF, t + 2);
;       WAIT_V(6); BAR; MMA(1, 1, At, B1); BAR;
.LBB0_472:
	ds_read_b128 v[138:141], v206
	ds_read_b128 v[142:145], v206 offset:1024
	ds_read_b128 v[146:149], v206 offset:2048
	ds_read_b128 v[150:153], v206 offset:3072
	s_add_u32 vcc_lo, s8, s80
	s_addc_u32 vcc_hi, s9, s81
	ds_read_b128 v[154:157], v241
	ds_read_b128 v[158:161], v241 offset:1024
	ds_read_b128 v[162:165], v241 offset:2048
	ds_read_b128 v[166:169], v241 offset:3072
	ds_read_b128 v[170:173], v241 offset:4096
	ds_read_b128 v[174:177], v241 offset:5120
	ds_read_b128 v[178:181], v241 offset:6144
	ds_read_b128 v[182:185], v241 offset:7168
	s_mov_b32 m0, s16
	s_add_u32 s98, vcc_lo, s12
	s_addc_u32 s99, vcc_hi, s13
	global_load_lds_dwordx4 v221, s[98:99]
	s_mov_b32 m0, s32
	s_add_u32 s98, vcc_lo, s36
	s_addc_u32 s99, vcc_hi, s37
	global_load_lds_dwordx4 v221, s[98:99]
	s_waitcnt lgkmcnt(8)
	s_waitcnt vmcnt(10)
	s_barrier
	s_waitcnt lgkmcnt(0)
	s_waitcnt lgkmcnt(0)
	v_mfma_f32_16x16x32_bf16 v[126:129], v[138:141], v[154:157], v[126:129]
	v_mfma_f32_16x16x32_bf16 v[122:125], v[146:149], v[154:157], v[122:125]
	v_mfma_f32_16x16x32_bf16 v[118:121], v[138:141], v[162:165], v[118:121]
	v_mfma_f32_16x16x32_bf16 v[114:117], v[146:149], v[162:165], v[114:117]
	v_mfma_f32_16x16x32_bf16 v[110:113], v[138:141], v[170:173], v[110:113]
	v_mfma_f32_16x16x32_bf16 v[106:109], v[146:149], v[170:173], v[106:109]
	v_mfma_f32_16x16x32_bf16 v[102:105], v[138:141], v[178:181], v[102:105]
	v_mfma_f32_16x16x32_bf16 v[98:101], v[146:149], v[178:181], v[98:101]
	v_mfma_f32_16x16x32_bf16 v[126:129], v[142:145], v[158:161], v[126:129]
	v_mfma_f32_16x16x32_bf16 v[122:125], v[150:153], v[158:161], v[122:125]
	v_mfma_f32_16x16x32_bf16 v[118:121], v[142:145], v[166:169], v[118:121]
	v_mfma_f32_16x16x32_bf16 v[114:117], v[150:153], v[166:169], v[114:117]
	v_mfma_f32_16x16x32_bf16 v[110:113], v[142:145], v[174:177], v[110:113]
	v_mfma_f32_16x16x32_bf16 v[106:109], v[150:153], v[174:177], v[106:109]
	v_mfma_f32_16x16x32_bf16 v[102:105], v[142:145], v[182:185], v[102:105]
	v_mfma_f32_16x16x32_bf16 v[98:101], v[150:153], v[182:185], v[98:101]
	s_barrier
	s_add_u32 s0, s6, s80
	ds_read_b128 v[186:189], v207
	ds_read_b128 v[190:193], v207 offset:1024
	ds_read_b128 v[194:197], v207 offset:2048
	ds_read_b128 v[198:201], v207 offset:3072
	s_addc_u32 s1, s7, s81
	s_mov_b32 m0, s44
	s_add_u32 s98, s0, s34
	s_addc_u32 s99, s1, s35
	global_load_lds_dwordx4 v221, s[98:99]
	s_mov_b32 m0, s45
	s_add_u32 s98, s0, s64
	s_addc_u32 s99, s1, s65
	global_load_lds_dwordx4 v221, s[98:99]
	s_waitcnt vmcnt(10)
	s_barrier
	s_waitcnt lgkmcnt(0)
	s_waitcnt lgkmcnt(0)
	v_mfma_f32_16x16x32_bf16 v[94:97], v[186:189], v[154:157], v[94:97]
	v_mfma_f32_16x16x32_bf16 v[90:93], v[194:197], v[154:157], v[90:93]
	v_mfma_f32_16x16x32_bf16 v[86:89], v[186:189], v[162:165], v[86:89]
	v_mfma_f32_16x16x32_bf16 v[82:85], v[194:197], v[162:165], v[82:85]
	v_mfma_f32_16x16x32_bf16 v[78:81], v[186:189], v[170:173], v[78:81]
	v_mfma_f32_16x16x32_bf16 v[74:77], v[194:197], v[170:173], v[74:77]
	v_mfma_f32_16x16x32_bf16 v[70:73], v[186:189], v[178:181], v[70:73]
	v_mfma_f32_16x16x32_bf16 v[66:69], v[194:197], v[178:181], v[66:69]
	v_mfma_f32_16x16x32_bf16 v[94:97], v[190:193], v[158:161], v[94:97]
	v_mfma_f32_16x16x32_bf16 v[90:93], v[198:201], v[158:161], v[90:93]
	v_mfma_f32_16x16x32_bf16 v[86:89], v[190:193], v[166:169], v[86:89]
	v_mfma_f32_16x16x32_bf16 v[82:85], v[198:201], v[166:169], v[82:85]
	v_mfma_f32_16x16x32_bf16 v[78:81], v[190:193], v[174:177], v[78:81]
	v_mfma_f32_16x16x32_bf16 v[74:77], v[198:201], v[174:177], v[74:77]
	v_mfma_f32_16x16x32_bf16 v[70:73], v[190:193], v[182:185], v[70:73]
	v_mfma_f32_16x16x32_bf16 v[66:69], v[198:201], v[182:185], v[66:69]
	s_barrier
	ds_read_b128 v[154:157], v241 offset:16384
	ds_read_b128 v[158:161], v241 offset:17408
	ds_read_b128 v[162:165], v241 offset:18432
	ds_read_b128 v[166:169], v241 offset:19456
	ds_read_b128 v[170:173], v241 offset:20480
	ds_read_b128 v[174:177], v241 offset:21504
	ds_read_b128 v[178:181], v241 offset:22528
	ds_read_b128 v[182:185], v241 offset:23552
	s_mov_b32 m0, s46
	s_add_u32 s98, vcc_lo, s34
	s_addc_u32 s99, vcc_hi, s35
	global_load_lds_dwordx4 v221, s[98:99]
	s_mov_b32 m0, s47
	s_add_u32 s98, vcc_lo, s64
	s_addc_u32 s99, vcc_hi, s65
	global_load_lds_dwordx4 v221, s[98:99]
	s_barrier
	s_waitcnt lgkmcnt(0)
	s_waitcnt lgkmcnt(0)
	v_mfma_f32_16x16x32_bf16 v[62:65], v[138:141], v[154:157], v[62:65]
	v_mfma_f32_16x16x32_bf16 v[58:61], v[146:149], v[154:157], v[58:61]
	v_mfma_f32_16x16x32_bf16 v[54:57], v[138:141], v[162:165], v[54:57]
	v_mfma_f32_16x16x32_bf16 v[50:53], v[146:149], v[162:165], v[50:53]
	v_mfma_f32_16x16x32_bf16 v[46:49], v[138:141], v[170:173], v[46:49]
	v_mfma_f32_16x16x32_bf16 v[42:45], v[146:149], v[170:173], v[42:45]
	v_mfma_f32_16x16x32_bf16 v[38:41], v[138:141], v[178:181], v[38:41]
	v_mfma_f32_16x16x32_bf16 v[34:37], v[146:149], v[178:181], v[34:37]
	v_mfma_f32_16x16x32_bf16 v[62:65], v[142:145], v[158:161], v[62:65]
	v_mfma_f32_16x16x32_bf16 v[58:61], v[150:153], v[158:161], v[58:61]
	v_mfma_f32_16x16x32_bf16 v[54:57], v[142:145], v[166:169], v[54:57]
	v_mfma_f32_16x16x32_bf16 v[50:53], v[150:153], v[166:169], v[50:53]
	v_mfma_f32_16x16x32_bf16 v[46:49], v[142:145], v[174:177], v[46:49]
	v_mfma_f32_16x16x32_bf16 v[42:45], v[150:153], v[174:177], v[42:45]
	v_mfma_f32_16x16x32_bf16 v[38:41], v[142:145], v[182:185], v[38:41]
	v_mfma_f32_16x16x32_bf16 v[34:37], v[150:153], v[182:185], v[34:37]
	s_barrier
	s_mov_b32 m0, s48
	s_add_u32 s98, s0, s68
	s_addc_u32 s99, s1, s69
	global_load_lds_dwordx4 v221, s[98:99]
	s_mov_b32 m0, s49
	s_add_u32 s98, s0, s70
	s_addc_u32 s99, s1, s71
	global_load_lds_dwordx4 v221, s[98:99]
	s_waitcnt vmcnt(10)
	s_barrier
; #define LDA(dst, b, h) for (int m = 0; m < 4; ++m) for (int k = 0; k < 2; ++k) \
;     dst[m][k] = *reinterpret_cast<const bf16x8*>((char*)SA(b, h) + a_thr + (m * 2 + k) * 1024)
; #define LDB(dst, b, h) for (int n = 0; n < 2; ++n) for (int k = 0; k < 2; ++k) \
;     dst[n][k] = *reinterpret_cast<const bf16x8*>((char*)SB(b, h) + b_thr + (n * 2 + k) * 1024)
; #define MMA(ai, bj, At, Btf) do { __builtin_amdgcn_s_setprio(1); \
;     for (int m = 0; m < 4; ++m) for (int n = 0; n < 2; ++n) for (int k = 0; k < 2; ++k) \
;       acc[ai][bj][m][n] = __builtin_amdgcn_mfma_f32_16x16x32_bf16(Btf[n][k], At[m][k], acc[ai][bj][m][n], 0, 0, 0); \
;     __builtin_amdgcn_s_setprio(0); } while (0)
; #define WAIT_V(n) asm volatile("s_waitcnt vmcnt(" #n ")" ::: "memory")
; #define WAIT_L(n) asm volatile("s_waitcnt lgkmcnt(" #n ")" ::: "memory")
; #define BAR __builtin_amdgcn_s_barrier()
; #define SCHED __builtin_amdgcn_sched_barrier(0)
; template <bool OVL, bool PANEL = false, class Epi>
; __device__ __forceinline__ void gemm_phase(const bf16_t* __restrict__ A, long lda, const bf16_t* __restrict__ Bt, long ldb, int nM, int nN, int K,
;                                            const Epi& epi, bf16_t* shm, int w0) {
;     ...
;       WAIT_V(6); BAR; MMA(1, 1, At, B1); BAR;
;       LDB(B0, 1, 0); SCHED; LDA(At, 1, 0); STAGE(SA(0, 1), A, lda, aoff, brow + HALF, t + 2);
;       WAIT_L(8); BAR; WAIT_L(0); MMA(0, 0, At, B0); BAR; SCHED;
;       LDB(B1, 1, 1); STAGE(SB(1, 0), Bt, ldb, boff, bcol, t + 3);
;       BAR; WAIT_L(0); MMA(0, 1, At, B1); BAR;
;       LDA(At, 1, 1); STAGE(SA(1, 0), A, lda, aoff, brow, t + 3);
	v_mfma_f32_16x16x32_bf16 v[30:33], v[186:189], v[154:157], v[30:33]
	v_mfma_f32_16x16x32_bf16 v[26:29], v[194:197], v[154:157], v[26:29]
	v_mfma_f32_16x16x32_bf16 v[22:25], v[186:189], v[162:165], v[22:25]
	v_mfma_f32_16x16x32_bf16 v[18:21], v[194:197], v[162:165], v[18:21]
	v_mfma_f32_16x16x32_bf16 v[14:17], v[186:189], v[170:173], v[14:17]
	v_mfma_f32_16x16x32_bf16 v[10:13], v[194:197], v[170:173], v[10:13]
	v_mfma_f32_16x16x32_bf16 v[6:9], v[186:189], v[178:181], v[6:9]
	v_mfma_f32_16x16x32_bf16 v[2:5], v[194:197], v[178:181], v[2:5]
	v_mfma_f32_16x16x32_bf16 v[30:33], v[190:193], v[158:161], v[30:33]
	v_mfma_f32_16x16x32_bf16 v[26:29], v[198:201], v[158:161], v[26:29]
	v_mfma_f32_16x16x32_bf16 v[22:25], v[190:193], v[166:169], v[22:25]
	v_mfma_f32_16x16x32_bf16 v[18:21], v[198:201], v[166:169], v[18:21]
	v_mfma_f32_16x16x32_bf16 v[14:17], v[190:193], v[174:177], v[14:17]
	v_mfma_f32_16x16x32_bf16 v[10:13], v[198:201], v[174:177], v[10:13]
	v_mfma_f32_16x16x32_bf16 v[6:9], v[190:193], v[182:185], v[6:9]
	v_mfma_f32_16x16x32_bf16 v[2:5], v[198:201], v[182:185], v[2:5]
	s_barrier
	ds_read_b128 v[138:141], v208
	ds_read_b128 v[142:145], v208 offset:1024
	ds_read_b128 v[146:149], v208 offset:2048
	ds_read_b128 v[150:153], v208 offset:3072
	ds_read_b128 v[154:157], v241 offset:32768
	ds_read_b128 v[158:161], v241 offset:33792
	ds_read_b128 v[162:165], v241 offset:34816
	ds_read_b128 v[166:169], v241 offset:35840
	ds_read_b128 v[170:173], v241 offset:36864
	ds_read_b128 v[174:177], v241 offset:37888
	ds_read_b128 v[178:181], v241 offset:38912
	ds_read_b128 v[182:185], v241 offset:39936
	s_mov_b32 m0, s50
	s_add_u32 s98, vcc_lo, s68
	s_addc_u32 s99, vcc_hi, s69
	global_load_lds_dwordx4 v221, s[98:99]
	s_mov_b32 m0, s51
	s_add_u32 s98, vcc_lo, s70
	s_addc_u32 s99, vcc_hi, s71
	global_load_lds_dwordx4 v221, s[98:99]
	s_waitcnt lgkmcnt(8)
	s_waitcnt vmcnt(10)
	s_barrier
	s_waitcnt lgkmcnt(0)
	s_waitcnt lgkmcnt(0)
	v_mfma_f32_16x16x32_bf16 v[126:129], v[138:141], v[154:157], v[126:129]
	v_mfma_f32_16x16x32_bf16 v[122:125], v[146:149], v[154:157], v[122:125]
	v_mfma_f32_16x16x32_bf16 v[118:121], v[138:141], v[162:165], v[118:121]
	v_mfma_f32_16x16x32_bf16 v[114:117], v[146:149], v[162:165], v[114:117]
	v_mfma_f32_16x16x32_bf16 v[110:113], v[138:141], v[170:173], v[110:113]
	v_mfma_f32_16x16x32_bf16 v[106:109], v[146:149], v[170:173], v[106:109]
	v_mfma_f32_16x16x32_bf16 v[102:105], v[138:141], v[178:181], v[102:105]
	v_mfma_f32_16x16x32_bf16 v[98:101], v[146:149], v[178:181], v[98:101]
	v_mfma_f32_16x16x32_bf16 v[126:129], v[142:145], v[158:161], v[126:129]
	v_mfma_f32_16x16x32_bf16 v[122:125], v[150:153], v[158:161], v[122:125]
	v_mfma_f32_16x16x32_bf16 v[118:121], v[142:145], v[166:169], v[118:121]
	v_mfma_f32_16x16x32_bf16 v[114:117], v[150:153], v[166:169], v[114:117]
	v_mfma_f32_16x16x32_bf16 v[110:113], v[142:145], v[174:177], v[110:113]
	v_mfma_f32_16x16x32_bf16 v[106:109], v[150:153], v[174:177], v[106:109]
	v_mfma_f32_16x16x32_bf16 v[102:105], v[142:145], v[182:185], v[102:105]
	v_mfma_f32_16x16x32_bf16 v[98:101], v[150:153], v[182:185], v[98:101]
	s_barrier
	ds_read_b128 v[186:189], v209
	ds_read_b128 v[190:193], v209 offset:1024
	ds_read_b128 v[194:197], v209 offset:2048
	ds_read_b128 v[198:201], v209 offset:3072
	s_mov_b32 m0, s52
	s_add_u32 s98, s0, s94
	s_addc_u32 s99, s1, s95
	global_load_lds_dwordx4 v221, s[98:99]
	s_mov_b32 m0, s53
	s_add_u32 s98, s0, s72
	s_addc_u32 s99, s1, s73
	global_load_lds_dwordx4 v221, s[98:99]
	s_waitcnt vmcnt(10)
	s_barrier
	s_waitcnt lgkmcnt(0)
	s_waitcnt lgkmcnt(0)
	v_mfma_f32_16x16x32_bf16 v[94:97], v[186:189], v[154:157], v[94:97]
	v_mfma_f32_16x16x32_bf16 v[90:93], v[194:197], v[154:157], v[90:93]
	v_mfma_f32_16x16x32_bf16 v[86:89], v[186:189], v[162:165], v[86:89]
	v_mfma_f32_16x16x32_bf16 v[82:85], v[194:197], v[162:165], v[82:85]
	v_mfma_f32_16x16x32_bf16 v[78:81], v[186:189], v[170:173], v[78:81]
	v_mfma_f32_16x16x32_bf16 v[74:77], v[194:197], v[170:173], v[74:77]
	v_mfma_f32_16x16x32_bf16 v[70:73], v[186:189], v[178:181], v[70:73]
	v_mfma_f32_16x16x32_bf16 v[66:69], v[194:197], v[178:181], v[66:69]
	v_mfma_f32_16x16x32_bf16 v[94:97], v[190:193], v[158:161], v[94:97]
	v_mfma_f32_16x16x32_bf16 v[90:93], v[198:201], v[158:161], v[90:93]
	v_mfma_f32_16x16x32_bf16 v[86:89], v[190:193], v[166:169], v[86:89]
	v_mfma_f32_16x16x32_bf16 v[82:85], v[198:201], v[166:169], v[82:85]
	v_mfma_f32_16x16x32_bf16 v[78:81], v[190:193], v[174:177], v[78:81]
	v_mfma_f32_16x16x32_bf16 v[74:77], v[198:201], v[174:177], v[74:77]
	v_mfma_f32_16x16x32_bf16 v[70:73], v[190:193], v[182:185], v[70:73]
	v_mfma_f32_16x16x32_bf16 v[66:69], v[198:201], v[182:185], v[66:69]
	s_barrier
	ds_read_b128 v[154:157], v241 offset:49152
	ds_read_b128 v[158:161], v241 offset:50176
	ds_read_b128 v[162:165], v241 offset:51200
	ds_read_b128 v[166:169], v241 offset:52224
	ds_read_b128 v[170:173], v241 offset:53248
	ds_read_b128 v[174:177], v241 offset:54272
	ds_read_b128 v[178:181], v241 offset:55296
	ds_read_b128 v[182:185], v241 offset:56320
	s_mov_b32 m0, s54
	s_add_u32 s98, vcc_lo, s94
	s_addc_u32 s99, vcc_hi, s95
	global_load_lds_dwordx4 v221, s[98:99]
	s_mov_b32 m0, s55
	s_add_u32 s98, vcc_lo, s72
	s_addc_u32 s99, vcc_hi, s73
	global_load_lds_dwordx4 v221, s[98:99]
	s_barrier
; #define LDA(dst, b, h) for (int m = 0; m < 4; ++m) for (int k = 0; k < 2; ++k) \
;     dst[m][k] = *reinterpret_cast<const bf16x8*>((char*)SA(b, h) + a_thr + (m * 2 + k) * 1024)
; #define LDB(dst, b, h) for (int n = 0; n < 2; ++n) for (int k = 0; k < 2; ++k) \
;     dst[n][k] = *reinterpret_cast<const bf16x8*>((char*)SB(b, h) + b_thr + (n * 2 + k) * 1024)
; #define MMA(ai, bj, At, Btf) do { __builtin_amdgcn_s_setprio(1); \
;     for (int m = 0; m < 4; ++m) for (int n = 0; n < 2; ++n) for (int k = 0; k < 2; ++k) \
;       acc[ai][bj][m][n] = __builtin_amdgcn_mfma_f32_16x16x32_bf16(Btf[n][k], At[m][k], acc[ai][bj][m][n], 0, 0, 0); \
;     __builtin_amdgcn_s_setprio(0); } while (0)
; #define WAIT_V(n) asm volatile("s_waitcnt vmcnt(" #n ")" ::: "memory")
; #define WAIT_L(n) asm volatile("s_waitcnt lgkmcnt(" #n ")" ::: "memory")
; #define BAR __builtin_amdgcn_s_barrier()
; #define SCHED __builtin_amdgcn_sched_barrier(0)
; template <bool OVL, bool PANEL = false, class Epi>
; __device__ __forceinline__ void gemm_phase(const bf16_t* __restrict__ A, long lda, const bf16_t* __restrict__ Bt, long ldb, int nM, int nN, int K,
;                                            const Epi& epi, bf16_t* shm, int w0) {
;     ...
;       BAR; WAIT_L(0); MMA(1, 0, At, B0); BAR; SCHED;
;       STAGE(SB(1, 1), Bt, ldb, boff, bcol + HALF, t + 3);
;       WAIT_V(6); BAR; MMA(1, 1, At, B1); BAR;
;     }
;     { LDB(B0, 0, 0); LDA(At, 0, 0); STAGE(SA(1, 1), A, lda, aoff, brow + HALF, nt - 1);
;       BAR; WAIT_L(0); MMA(0, 0, At, B0); BAR;
;       LDB(B1, 0, 1); BAR; WAIT_L(0); MMA(0, 1, At, B1); BAR;
	s_waitcnt lgkmcnt(0)
	s_waitcnt lgkmcnt(0)
	v_mfma_f32_16x16x32_bf16 v[62:65], v[138:141], v[154:157], v[62:65]
	v_mfma_f32_16x16x32_bf16 v[58:61], v[146:149], v[154:157], v[58:61]
	v_mfma_f32_16x16x32_bf16 v[54:57], v[138:141], v[162:165], v[54:57]
	v_mfma_f32_16x16x32_bf16 v[50:53], v[146:149], v[162:165], v[50:53]
	v_mfma_f32_16x16x32_bf16 v[46:49], v[138:141], v[170:173], v[46:49]
	v_mfma_f32_16x16x32_bf16 v[42:45], v[146:149], v[170:173], v[42:45]
	v_mfma_f32_16x16x32_bf16 v[38:41], v[138:141], v[178:181], v[38:41]
	v_mfma_f32_16x16x32_bf16 v[34:37], v[146:149], v[178:181], v[34:37]
	v_mfma_f32_16x16x32_bf16 v[62:65], v[142:145], v[158:161], v[62:65]
	v_mfma_f32_16x16x32_bf16 v[58:61], v[150:153], v[158:161], v[58:61]
	v_mfma_f32_16x16x32_bf16 v[54:57], v[142:145], v[166:169], v[54:57]
	v_mfma_f32_16x16x32_bf16 v[50:53], v[150:153], v[166:169], v[50:53]
	v_mfma_f32_16x16x32_bf16 v[46:49], v[142:145], v[174:177], v[46:49]
	v_mfma_f32_16x16x32_bf16 v[42:45], v[150:153], v[174:177], v[42:45]
	v_mfma_f32_16x16x32_bf16 v[38:41], v[142:145], v[182:185], v[38:41]
	v_mfma_f32_16x16x32_bf16 v[34:37], v[150:153], v[182:185], v[34:37]
	s_barrier
	s_mov_b32 m0, s56
	s_add_u32 s98, s0, s14
	s_addc_u32 s99, s1, s15
	global_load_lds_dwordx4 v221, s[98:99]
	s_mov_b32 m0, s57
	s_add_u32 s98, s0, s18
	s_addc_u32 s99, s1, s19
	global_load_lds_dwordx4 v221, s[98:99]
	s_waitcnt vmcnt(10)
	s_barrier
	v_mfma_f32_16x16x32_bf16 v[30:33], v[186:189], v[154:157], v[30:33]
	v_mfma_f32_16x16x32_bf16 v[26:29], v[194:197], v[154:157], v[26:29]
	v_mfma_f32_16x16x32_bf16 v[22:25], v[186:189], v[162:165], v[22:25]
	v_mfma_f32_16x16x32_bf16 v[18:21], v[194:197], v[162:165], v[18:21]
	v_mfma_f32_16x16x32_bf16 v[14:17], v[186:189], v[170:173], v[14:17]
	v_mfma_f32_16x16x32_bf16 v[10:13], v[194:197], v[170:173], v[10:13]
	v_mfma_f32_16x16x32_bf16 v[6:9], v[186:189], v[178:181], v[6:9]
	v_mfma_f32_16x16x32_bf16 v[2:5], v[194:197], v[178:181], v[2:5]
	v_mfma_f32_16x16x32_bf16 v[30:33], v[190:193], v[158:161], v[30:33]
	v_mfma_f32_16x16x32_bf16 v[26:29], v[198:201], v[158:161], v[26:29]
	v_mfma_f32_16x16x32_bf16 v[22:25], v[190:193], v[166:169], v[22:25]
	v_mfma_f32_16x16x32_bf16 v[18:21], v[198:201], v[166:169], v[18:21]
	v_mfma_f32_16x16x32_bf16 v[14:17], v[190:193], v[174:177], v[14:17]
	v_mfma_f32_16x16x32_bf16 v[10:13], v[198:201], v[174:177], v[10:13]
	v_mfma_f32_16x16x32_bf16 v[6:9], v[190:193], v[182:185], v[6:9]
	v_mfma_f32_16x16x32_bf16 v[2:5], v[198:201], v[182:185], v[2:5]
	s_add_i32 s2, s2, 2
	s_add_u32 s80, s80, 0x100
	s_addc_u32 s81, s81, 0
	s_cmp_gt_u32 s2, 11
	s_barrier
	s_cbranch_scc0 .LBB0_472
	s_waitcnt vmcnt(6)
	s_or_b32 s0, s82, 0x80
	s_ashr_i32 s1, s0, 31
	v_readlane_b32 s44, v252, 20
	s_lshl_b64 s[0:1], s[0:1], 11
	v_readlane_b32 s50, v252, 26
	v_add_u32_e32 v206, 16, v240
	v_readlane_b32 s51, v252, 27
	s_add_u32 s0, s50, s0
	v_add_u32_e32 v0, 0x10000, v206
	s_addc_u32 s1, s51, s1
	ds_read_b128 v[130:133], v0
	ds_read_b128 v[138:141], v0 offset:1024
	ds_read_b128 v[142:145], v0 offset:2048
	ds_read_b128 v[146:149], v0 offset:3072
	ds_read_b128 v[150:153], v241
	ds_read_b128 v[154:157], v241 offset:1024
	ds_read_b128 v[158:161], v241 offset:2048
	ds_read_b128 v[162:165], v241 offset:3072
	ds_read_b128 v[166:169], v241 offset:4096
	ds_read_b128 v[170:173], v241 offset:5120
	ds_read_b128 v[174:177], v241 offset:6144
	ds_read_b128 v[178:181], v241 offset:7168
	v_mov_b32_e32 v0, v221
	v_readlane_b32 s45, v252, 21
	v_lshl_add_u64 v[134:135], s[0:1], 0, v[0:1]
	s_mov_b64 s[0:1], 0x780
	v_lshl_add_u64 v[182:183], v[134:135], 0, s[0:1]
	v_readfirstlane_b32 s0, v136
	s_mov_b32 m0, s0
	s_mov_b64 s[0:1], 0x20780
	v_lshl_add_u64 v[134:135], v[134:135], 0, s[0:1]
	v_readfirstlane_b32 s0, v137
	global_load_lds_dwordx4 v[182:183], off
	s_mov_b32 m0, s0
	v_readlane_b32 s46, v252, 22
	global_load_lds_dwordx4 v[134:135], off
	s_barrier
	s_waitcnt lgkmcnt(0)
	v_readlane_b32 s47, v252, 23
	v_readlane_b32 s48, v252, 24
	v_readlane_b32 s49, v252, 25
	v_readlane_b32 s52, v252, 28
	v_readlane_b32 s53, v252, 29
	v_readlane_b32 s54, v252, 30
	v_readlane_b32 s55, v252, 31
	v_readlane_b32 s56, v252, 32
	v_readlane_b32 s57, v252, 33
	v_readlane_b32 s58, v252, 34
	v_readlane_b32 s59, v252, 35
	s_setprio 1
	s_waitcnt lgkmcnt(0)
	v_mfma_f32_16x16x32_bf16 v[126:129], v[130:133], v[150:153], v[126:129]
	v_mfma_f32_16x16x32_bf16 v[122:125], v[142:145], v[150:153], v[122:125]
	v_mfma_f32_16x16x32_bf16 v[118:121], v[130:133], v[158:161], v[118:121]
	v_mfma_f32_16x16x32_bf16 v[114:117], v[142:145], v[158:161], v[114:117]
	v_mfma_f32_16x16x32_bf16 v[106:109], v[142:145], v[166:169], v[106:109]
	v_mfma_f32_16x16x32_bf16 v[102:105], v[130:133], v[174:177], v[102:105]
	v_mfma_f32_16x16x32_bf16 v[98:101], v[142:145], v[174:177], v[98:101]
	v_mfma_f32_16x16x32_bf16 v[126:129], v[138:141], v[154:157], v[126:129]
	v_mfma_f32_16x16x32_bf16 v[122:125], v[146:149], v[154:157], v[122:125]
	v_mfma_f32_16x16x32_bf16 v[118:121], v[138:141], v[162:165], v[118:121]
	v_mfma_f32_16x16x32_bf16 v[114:117], v[146:149], v[162:165], v[114:117]
	v_mfma_f32_16x16x32_bf16 v[110:113], v[130:133], v[166:169], v[110:113]
	v_mfma_f32_16x16x32_bf16 v[106:109], v[146:149], v[170:173], v[106:109]
	v_mfma_f32_16x16x32_bf16 v[102:105], v[138:141], v[178:181], v[102:105]
	v_mfma_f32_16x16x32_bf16 v[98:101], v[146:149], v[178:181], v[98:101]
	v_mfma_f32_16x16x32_bf16 v[134:137], v[138:141], v[170:173], v[110:113]
	s_setprio 0
	v_add_u32_e32 v0, 0x14000, v206
	s_barrier
	s_nop 0
	ds_read_b128 v[110:113], v0
	ds_read_b128 v[182:185], v0 offset:1024
	ds_read_b128 v[186:189], v0 offset:2048
	ds_read_b128 v[190:193], v0 offset:3072
	s_barrier
; #define LDA(dst, b, h) for (int m = 0; m < 4; ++m) for (int k = 0; k < 2; ++k) \
;     dst[m][k] = *reinterpret_cast<const bf16x8*>((char*)SA(b, h) + a_thr + (m * 2 + k) * 1024)
; #define LDB(dst, b, h) for (int n = 0; n < 2; ++n) for (int k = 0; k < 2; ++k) \
;     dst[n][k] = *reinterpret_cast<const bf16x8*>((char*)SB(b, h) + b_thr + (n * 2 + k) * 1024)
; #define MMA(ai, bj, At, Btf) do { __builtin_amdgcn_s_setprio(1); \
;     for (int m = 0; m < 4; ++m) for (int n = 0; n < 2; ++n) for (int k = 0; k < 2; ++k) \
;       acc[ai][bj][m][n] = __builtin_amdgcn_mfma_f32_16x16x32_bf16(Btf[n][k], At[m][k], acc[ai][bj][m][n], 0, 0, 0); \
;     __builtin_amdgcn_s_setprio(0); } while (0)
; #define WAIT_V(n) asm volatile("s_waitcnt vmcnt(" #n ")" ::: "memory")
; #define WAIT_L(n) asm volatile("s_waitcnt lgkmcnt(" #n ")" ::: "memory")
; #define BAR __builtin_amdgcn_s_barrier()
; template <bool OVL, bool PANEL = false, class Epi>
; __device__ __forceinline__ void gemm_phase(const bf16_t* __restrict__ A, long lda, const bf16_t* __restrict__ Bt, long ldb, int nM, int nN, int K,
;                                            const Epi& epi, bf16_t* shm, int w0) {
;     ...
;       LDB(B1, 0, 1); BAR; WAIT_L(0); MMA(0, 1, At, B1); BAR;
;       LDA(At, 0, 1); WAIT_V(4); BAR; WAIT_L(0); MMA(1, 0, At, B0); MMA(1, 1, At, B1); BAR; }
;     { LDB(B0, 1, 0); LDA(At, 1, 0); WAIT_V(2); BAR; WAIT_L(0); MMA(0, 0, At, B0); BAR;
	s_waitcnt lgkmcnt(0)
	s_setprio 1
	s_waitcnt lgkmcnt(0)
	v_mfma_f32_16x16x32_bf16 v[90:93], v[186:189], v[150:153], v[90:93]
	v_mfma_f32_16x16x32_bf16 v[74:77], v[186:189], v[166:169], v[74:77]
	v_mfma_f32_16x16x32_bf16 v[70:73], v[110:113], v[174:177], v[70:73]
	v_mfma_f32_16x16x32_bf16 v[66:69], v[186:189], v[174:177], v[66:69]
	v_mfma_f32_16x16x32_bf16 v[94:97], v[110:113], v[150:153], v[94:97]
	v_mfma_f32_16x16x32_bf16 v[90:93], v[190:193], v[154:157], v[90:93]
	v_mfma_f32_16x16x32_bf16 v[86:89], v[110:113], v[158:161], v[86:89]
	v_mfma_f32_16x16x32_bf16 v[82:85], v[186:189], v[158:161], v[82:85]
	v_mfma_f32_16x16x32_bf16 v[78:81], v[110:113], v[166:169], v[78:81]
	v_mfma_f32_16x16x32_bf16 v[74:77], v[190:193], v[170:173], v[74:77]
	v_mfma_f32_16x16x32_bf16 v[70:73], v[182:185], v[178:181], v[70:73]
	v_mfma_f32_16x16x32_bf16 v[66:69], v[190:193], v[178:181], v[66:69]
	v_mfma_f32_16x16x32_bf16 v[194:197], v[182:185], v[154:157], v[94:97]
	v_mfma_f32_16x16x32_bf16 v[150:153], v[182:185], v[162:165], v[86:89]
	v_mfma_f32_16x16x32_bf16 v[154:157], v[190:193], v[162:165], v[82:85]
	v_mfma_f32_16x16x32_bf16 v[158:161], v[182:185], v[170:173], v[78:81]
	s_setprio 0
	s_barrier
	s_nop 0
	ds_read_b128 v[78:81], v241 offset:16384
	ds_read_b128 v[82:85], v241 offset:17408
	ds_read_b128 v[86:89], v241 offset:18432
	ds_read_b128 v[94:97], v241 offset:19456
	ds_read_b128 v[162:165], v241 offset:20480
	ds_read_b128 v[166:169], v241 offset:21504
	ds_read_b128 v[170:173], v241 offset:22528
	ds_read_b128 v[174:177], v241 offset:23552
	s_waitcnt vmcnt(4)
	s_barrier
	s_waitcnt lgkmcnt(0)
	s_setprio 1
	s_waitcnt lgkmcnt(0)
	v_mfma_f32_16x16x32_bf16 v[62:65], v[130:133], v[78:81], v[62:65]
	v_mfma_f32_16x16x32_bf16 v[58:61], v[142:145], v[78:81], v[58:61]
	v_mfma_f32_16x16x32_bf16 v[54:57], v[130:133], v[86:89], v[54:57]
	v_mfma_f32_16x16x32_bf16 v[50:53], v[142:145], v[86:89], v[50:53]
	v_mfma_f32_16x16x32_bf16 v[46:49], v[130:133], v[162:165], v[46:49]
	v_mfma_f32_16x16x32_bf16 v[42:45], v[142:145], v[162:165], v[42:45]
	v_mfma_f32_16x16x32_bf16 v[34:37], v[142:145], v[170:173], v[34:37]
	v_mfma_f32_16x16x32_bf16 v[62:65], v[138:141], v[82:85], v[62:65]
	v_mfma_f32_16x16x32_bf16 v[58:61], v[146:149], v[82:85], v[58:61]
	v_mfma_f32_16x16x32_bf16 v[54:57], v[138:141], v[94:97], v[54:57]
	v_mfma_f32_16x16x32_bf16 v[50:53], v[146:149], v[94:97], v[50:53]
	v_mfma_f32_16x16x32_bf16 v[46:49], v[138:141], v[166:169], v[46:49]
	v_mfma_f32_16x16x32_bf16 v[42:45], v[146:149], v[166:169], v[42:45]
	v_mfma_f32_16x16x32_bf16 v[38:41], v[130:133], v[170:173], v[38:41]
	v_mfma_f32_16x16x32_bf16 v[34:37], v[146:149], v[174:177], v[34:37]
	v_mfma_f32_16x16x32_bf16 v[130:133], v[138:141], v[174:177], v[38:41]
	s_setprio 0
	s_setprio 1
	v_mfma_f32_16x16x32_bf16 v[30:33], v[110:113], v[78:81], v[30:33]
	v_mfma_f32_16x16x32_bf16 v[26:29], v[186:189], v[78:81], v[26:29]
	v_mfma_f32_16x16x32_bf16 v[22:25], v[110:113], v[86:89], v[22:25]
	v_mfma_f32_16x16x32_bf16 v[18:21], v[186:189], v[86:89], v[18:21]
	v_mfma_f32_16x16x32_bf16 v[14:17], v[110:113], v[162:165], v[14:17]
	v_mfma_f32_16x16x32_bf16 v[10:13], v[186:189], v[162:165], v[10:13]
	v_mfma_f32_16x16x32_bf16 v[6:9], v[110:113], v[170:173], v[6:9]
	v_mfma_f32_16x16x32_bf16 v[2:5], v[186:189], v[170:173], v[2:5]
	v_mfma_f32_16x16x32_bf16 v[138:141], v[182:185], v[82:85], v[30:33]
	v_mfma_f32_16x16x32_bf16 v[142:145], v[190:193], v[82:85], v[26:29]
	v_mfma_f32_16x16x32_bf16 v[146:149], v[182:185], v[94:97], v[22:25]
	v_mfma_f32_16x16x32_bf16 v[178:181], v[190:193], v[94:97], v[18:21]
	v_mfma_f32_16x16x32_bf16 v[198:201], v[182:185], v[166:169], v[14:17]
	v_mfma_f32_16x16x32_bf16 v[162:165], v[190:193], v[166:169], v[10:13]
	v_mfma_f32_16x16x32_bf16 v[166:169], v[182:185], v[174:177], v[6:9]
	v_mfma_f32_16x16x32_bf16 v[170:173], v[190:193], v[174:177], v[2:5]
	s_setprio 0
	v_add_u32_e32 v0, 0x18000, v206
	s_barrier
	ds_read_b128 v[174:177], v0
	ds_read_b128 v[182:185], v0 offset:1024
	ds_read_b128 v[186:189], v0 offset:2048
	ds_read_b128 v[190:193], v0 offset:3072
	ds_read_b128 v[6:9], v241 offset:32768
	ds_read_b128 v[14:17], v241 offset:33792
	ds_read_b128 v[18:21], v241 offset:34816
	ds_read_b128 v[22:25], v241 offset:35840
	ds_read_b128 v[26:29], v241 offset:36864
	ds_read_b128 v[30:33], v241 offset:37888
	ds_read_b128 v[38:41], v241 offset:38912
	ds_read_b128 v[202:205], v241 offset:39936
	s_waitcnt vmcnt(2)
	s_barrier
; #define LDA(dst, b, h) for (int m = 0; m < 4; ++m) for (int k = 0; k < 2; ++k) \
;     dst[m][k] = *reinterpret_cast<const bf16x8*>((char*)SA(b, h) + a_thr + (m * 2 + k) * 1024)
; #define LDB(dst, b, h) for (int n = 0; n < 2; ++n) for (int k = 0; k < 2; ++k) \
;     dst[n][k] = *reinterpret_cast<const bf16x8*>((char*)SB(b, h) + b_thr + (n * 2 + k) * 1024)
; #define MMA(ai, bj, At, Btf) do { __builtin_amdgcn_s_setprio(1); \
;     for (int m = 0; m < 4; ++m) for (int n = 0; n < 2; ++n) for (int k = 0; k < 2; ++k) \
;       acc[ai][bj][m][n] = __builtin_amdgcn_mfma_f32_16x16x32_bf16(Btf[n][k], At[m][k], acc[ai][bj][m][n], 0, 0, 0); \
;     __builtin_amdgcn_s_setprio(0); } while (0)
; #define WAIT_V(n) asm volatile("s_waitcnt vmcnt(" #n ")" ::: "memory")
; #define WAIT_L(n) asm volatile("s_waitcnt lgkmcnt(" #n ")" ::: "memory")
; #define BAR __builtin_amdgcn_s_barrier()
; template <bool OVL, bool PANEL = false, class Epi>
; __device__ __forceinline__ void gemm_phase(const bf16_t* __restrict__ A, long lda, const bf16_t* __restrict__ Bt, long ldb, int nM, int nN, int K,
;                                            const Epi& epi, bf16_t* shm, int w0) {
;     ...
;     { LDB(B0, 1, 0); LDA(At, 1, 0); WAIT_V(2); BAR; WAIT_L(0); MMA(0, 0, At, B0); BAR;
;       LDB(B1, 1, 1); WAIT_V(0); BAR; WAIT_L(0); MMA(0, 1, At, B1); BAR;
;       LDA(At, 1, 1); BAR; WAIT_L(0); MMA(1, 0, At, B0); MMA(1, 1, At, B1); BAR; }
;     if (wr == 0) BAR;
	s_waitcnt lgkmcnt(0)
	s_setprio 1
	s_waitcnt lgkmcnt(0)
	v_mfma_f32_16x16x32_bf16 v[2:5], v[174:177], v[6:9], v[126:129]
	v_mfma_f32_16x16x32_bf16 v[126:129], v[182:185], v[14:17], v[2:5]
	v_mfma_f32_16x16x32_bf16 v[2:5], v[186:189], v[6:9], v[122:125]
	v_mfma_f32_16x16x32_bf16 v[82:85], v[190:193], v[14:17], v[2:5]
	v_mfma_f32_16x16x32_bf16 v[2:5], v[174:177], v[18:21], v[118:121]
	v_mfma_f32_16x16x32_bf16 v[110:113], v[182:185], v[22:25], v[2:5]
	v_mfma_f32_16x16x32_bf16 v[2:5], v[186:189], v[18:21], v[114:117]
	v_mfma_f32_16x16x32_bf16 v[86:89], v[190:193], v[22:25], v[2:5]
	v_mfma_f32_16x16x32_bf16 v[2:5], v[174:177], v[26:29], v[134:137]
	v_mfma_f32_16x16x32_bf16 v[94:97], v[182:185], v[30:33], v[2:5]
	v_mfma_f32_16x16x32_bf16 v[2:5], v[186:189], v[26:29], v[106:109]
	v_mfma_f32_16x16x32_bf16 v[78:81], v[190:193], v[30:33], v[2:5]
	v_mfma_f32_16x16x32_bf16 v[2:5], v[174:177], v[38:41], v[102:105]
	v_mfma_f32_16x16x32_bf16 v[10:13], v[186:189], v[38:41], v[98:101]
	v_mfma_f32_16x16x32_bf16 v[2:5], v[182:185], v[202:205], v[2:5]
	v_mfma_f32_16x16x32_bf16 v[10:13], v[190:193], v[202:205], v[10:13]
	s_setprio 0
	v_add_u32_e32 v0, 0x1c000, v206
	s_barrier
	ds_read_b128 v[122:125], v0
	ds_read_b128 v[134:137], v0 offset:1024
	ds_read_b128 v[206:209], v0 offset:2048
	ds_read_b128 v[210:213], v0 offset:3072
	s_waitcnt vmcnt(0)
	s_barrier
	s_waitcnt lgkmcnt(0)
	s_setprio 1
	s_waitcnt lgkmcnt(0)
	v_mfma_f32_16x16x32_bf16 v[98:101], v[122:125], v[6:9], v[194:197]
	v_mfma_f32_16x16x32_bf16 v[6:9], v[206:209], v[6:9], v[90:93]
	v_mfma_f32_16x16x32_bf16 v[114:117], v[210:213], v[14:17], v[6:9]
	v_mfma_f32_16x16x32_bf16 v[6:9], v[122:125], v[18:21], v[150:153]
	v_mfma_f32_16x16x32_bf16 v[102:105], v[134:137], v[22:25], v[6:9]
	v_mfma_f32_16x16x32_bf16 v[6:9], v[206:209], v[18:21], v[154:157]
	v_mfma_f32_16x16x32_bf16 v[118:121], v[210:213], v[22:25], v[6:9]
	v_mfma_f32_16x16x32_bf16 v[6:9], v[122:125], v[26:29], v[158:161]
	v_mfma_f32_16x16x32_bf16 v[90:93], v[134:137], v[30:33], v[6:9]
	v_mfma_f32_16x16x32_bf16 v[6:9], v[206:209], v[26:29], v[74:77]
	v_mfma_f32_16x16x32_bf16 v[106:109], v[210:213], v[30:33], v[6:9]
	v_mfma_f32_16x16x32_bf16 v[6:9], v[122:125], v[38:41], v[70:73]
	v_mfma_f32_16x16x32_bf16 v[22:25], v[134:137], v[202:205], v[6:9]
	v_mfma_f32_16x16x32_bf16 v[6:9], v[206:209], v[38:41], v[66:69]
	v_mfma_f32_16x16x32_bf16 v[98:101], v[134:137], v[14:17], v[98:101]
	v_mfma_f32_16x16x32_bf16 v[38:41], v[210:213], v[202:205], v[6:9]
	s_setprio 0
	s_barrier
	ds_read_b128 v[70:73], v241 offset:49152
	ds_read_b128 v[74:77], v241 offset:50176
	ds_read_b128 v[150:153], v241 offset:51200
	ds_read_b128 v[154:157], v241 offset:52224
	ds_read_b128 v[158:161], v241 offset:53248
	ds_read_b128 v[194:197], v241 offset:54272
	ds_read_b128 v[202:205], v241 offset:55296
	ds_read_b128 v[214:217], v241 offset:56320
	s_barrier
	s_waitcnt lgkmcnt(0)
	s_setprio 1
	s_waitcnt lgkmcnt(0)
	v_mfma_f32_16x16x32_bf16 v[14:17], v[186:189], v[70:73], v[58:61]
	v_mfma_f32_16x16x32_bf16 v[42:45], v[186:189], v[158:161], v[42:45]
	v_mfma_f32_16x16x32_bf16 v[6:9], v[174:177], v[70:73], v[62:65]
	v_mfma_f32_16x16x32_bf16 v[18:21], v[190:193], v[74:77], v[14:17]
	v_mfma_f32_16x16x32_bf16 v[14:17], v[174:177], v[150:153], v[54:57]
	v_mfma_f32_16x16x32_bf16 v[26:29], v[186:189], v[150:153], v[50:53]
	v_mfma_f32_16x16x32_bf16 v[30:33], v[174:177], v[158:161], v[46:49]
	v_mfma_f32_16x16x32_bf16 v[46:49], v[190:193], v[194:197], v[42:45]
	v_mfma_f32_16x16x32_bf16 v[42:45], v[174:177], v[202:205], v[130:133]
	v_mfma_f32_16x16x32_bf16 v[34:37], v[186:189], v[202:205], v[34:37]
	v_mfma_f32_16x16x32_bf16 v[6:9], v[182:185], v[74:77], v[6:9]
	v_mfma_f32_16x16x32_bf16 v[14:17], v[182:185], v[154:157], v[14:17]
	v_mfma_f32_16x16x32_bf16 v[26:29], v[190:193], v[154:157], v[26:29]
	v_mfma_f32_16x16x32_bf16 v[30:33], v[182:185], v[194:197], v[30:33]
	v_mfma_f32_16x16x32_bf16 v[54:57], v[182:185], v[214:217], v[42:45]
	v_mfma_f32_16x16x32_bf16 v[66:69], v[190:193], v[214:217], v[34:37]
	s_setprio 0
	s_setprio 1
	v_mfma_f32_16x16x32_bf16 v[34:37], v[122:125], v[70:73], v[138:141]
	v_mfma_f32_16x16x32_bf16 v[42:45], v[206:209], v[70:73], v[142:145]
	v_mfma_f32_16x16x32_bf16 v[34:37], v[134:137], v[74:77], v[34:37]
	v_mfma_f32_16x16x32_bf16 v[50:53], v[210:213], v[74:77], v[42:45]
	v_mfma_f32_16x16x32_bf16 v[42:45], v[122:125], v[150:153], v[146:149]
	v_mfma_f32_16x16x32_bf16 v[58:61], v[206:209], v[150:153], v[178:181]
	v_mfma_f32_16x16x32_bf16 v[62:65], v[122:125], v[158:161], v[198:201]
	v_mfma_f32_16x16x32_bf16 v[70:73], v[206:209], v[158:161], v[162:165]
	v_mfma_f32_16x16x32_bf16 v[74:77], v[122:125], v[202:205], v[166:169]
	v_mfma_f32_16x16x32_bf16 v[122:125], v[206:209], v[202:205], v[170:173]
	v_mfma_f32_16x16x32_bf16 v[42:45], v[134:137], v[154:157], v[42:45]
	v_mfma_f32_16x16x32_bf16 v[58:61], v[210:213], v[154:157], v[58:61]
	v_mfma_f32_16x16x32_bf16 v[62:65], v[134:137], v[194:197], v[62:65]
	v_mfma_f32_16x16x32_bf16 v[70:73], v[210:213], v[194:197], v[70:73]
	v_mfma_f32_16x16x32_bf16 v[74:77], v[134:137], v[214:217], v[74:77]
	v_mfma_f32_16x16x32_bf16 v[122:125], v[210:213], v[214:217], v[122:125]
	s_setprio 0
	s_barrier
	s_and_saveexec_b64 s[0:1], s[90:91]
	s_cbranch_execz .LBB0_475
	s_barrier

; #define LDA(dst, b, h) for (int m = 0; m < 4; ++m) for (int k = 0; k < 2; ++k) \
;     dst[m][k] = *reinterpret_cast<const bf16x8*>((char*)SA(b, h) + a_thr + (m * 2 + k) * 1024)
; #define LDB(dst, b, h) for (int n = 0; n < 2; ++n) for (int k = 0; k < 2; ++k) \
;     dst[n][k] = *reinterpret_cast<const bf16x8*>((char*)SB(b, h) + b_thr + (n * 2 + k) * 1024)
; #define MMA(ai, bj, At, Btf) do { __builtin_amdgcn_s_setprio(1); \
;     for (int m = 0; m < 4; ++m) for (int n = 0; n < 2; ++n) for (int k = 0; k < 2; ++k) \
;       acc[ai][bj][m][n] = __builtin_amdgcn_mfma_f32_16x16x32_bf16(Btf[n][k], At[m][k], acc[ai][bj][m][n], 0, 0, 0); \
;     __builtin_amdgcn_s_setprio(0); } while (0)
; #define WAIT_V(n) asm volatile("s_waitcnt vmcnt(" #n ")" ::: "memory")
; #define WAIT_L(n) asm volatile("s_waitcnt lgkmcnt(" #n ")" ::: "memory")
; #define BAR __builtin_amdgcn_s_barrier()
; #define SCHED __builtin_amdgcn_sched_barrier(0)
; template <bool OVL, bool PANEL = false, class Epi>
; __device__ __forceinline__ void gemm_phase(const bf16_t* __restrict__ A, long lda, const bf16_t* __restrict__ Bt, long ldb, int nM, int nN, int K,
;                                            const Epi& epi, bf16_t* shm, int w0) {
;     ...
;       LDB(B0, 0, 0); SCHED; LDA(At, 0, 0); STAGE(SA(1, 1), A, lda, aoff, brow + HALF, t + 1);
;       WAIT_L(8); BAR; WAIT_L(0); MMA(0, 0, At, B0); BAR; SCHED;
;       LDB(B1, 0, 1); STAGE(SB(0, 0), Bt, ldb, boff, bcol, t + 2);
;       BAR; WAIT_L(0); MMA(0, 1, At, B1); BAR;
;       LDA(At, 0, 1); STAGE(SA(0, 0), A, lda, aoff, brow, t + 2);
;       BAR; WAIT_L(0); MMA(1, 0, At, B0); BAR; SCHED;
;       STAGE(SB(0, 1), Bt, ldb, boff, bcol + HALF, t + 2);
;       WAIT_V(6); BAR; MMA(1, 1, At, B1); BAR;
.LBB0_1053:
	ds_read_b128 v[152:155], v184
	ds_read_b128 v[156:159], v184 offset:1024
	ds_read_b128 v[160:163], v184 offset:2048
	ds_read_b128 v[164:167], v184 offset:3072
	s_add_u32 s40, s10, s14
	s_addc_u32 s41, s11, s15
	ds_read_b128 v[168:171], v147
	ds_read_b128 v[172:175], v147 offset:1024
	ds_read_b128 v[176:179], v147 offset:2048
	ds_read_b128 v[194:197], v147 offset:3072
	ds_read_b128 v[198:201], v147 offset:4096
	ds_read_b128 v[202:205], v147 offset:5120
	ds_read_b128 v[206:209], v147 offset:6144
	ds_read_b128 v[210:213], v147 offset:7168
	s_mov_b32 m0, s22
	s_add_u32 s98, s40, s16
	s_addc_u32 s99, s41, s17
	global_load_lds_dwordx4 v135, s[98:99]
	s_mov_b32 m0, s23
	s_add_u32 s98, s40, s36
	s_addc_u32 s99, s41, s37
	global_load_lds_dwordx4 v135, s[98:99]
	s_waitcnt lgkmcnt(8)
	s_waitcnt vmcnt(10)
	s_barrier
	s_waitcnt lgkmcnt(0)
	s_waitcnt lgkmcnt(0)
	v_mfma_f32_16x16x32_bf16 v[126:129], v[152:155], v[168:171], v[126:129]
	v_mfma_f32_16x16x32_bf16 v[122:125], v[160:163], v[168:171], v[122:125]
	v_mfma_f32_16x16x32_bf16 v[118:121], v[152:155], v[176:179], v[118:121]
	v_mfma_f32_16x16x32_bf16 v[114:117], v[160:163], v[176:179], v[114:117]
	v_mfma_f32_16x16x32_bf16 v[110:113], v[152:155], v[198:201], v[110:113]
	v_mfma_f32_16x16x32_bf16 v[106:109], v[160:163], v[198:201], v[106:109]
	v_mfma_f32_16x16x32_bf16 v[102:105], v[152:155], v[206:209], v[102:105]
	v_mfma_f32_16x16x32_bf16 v[98:101], v[160:163], v[206:209], v[98:101]
	v_mfma_f32_16x16x32_bf16 v[126:129], v[156:159], v[172:175], v[126:129]
	v_mfma_f32_16x16x32_bf16 v[122:125], v[164:167], v[172:175], v[122:125]
	v_mfma_f32_16x16x32_bf16 v[118:121], v[156:159], v[194:197], v[118:121]
	v_mfma_f32_16x16x32_bf16 v[114:117], v[164:167], v[194:197], v[114:117]
	v_mfma_f32_16x16x32_bf16 v[110:113], v[156:159], v[202:205], v[110:113]
	v_mfma_f32_16x16x32_bf16 v[106:109], v[164:167], v[202:205], v[106:109]
	v_mfma_f32_16x16x32_bf16 v[102:105], v[156:159], v[210:213], v[102:105]
	v_mfma_f32_16x16x32_bf16 v[98:101], v[164:167], v[210:213], v[98:101]
	s_barrier
	s_add_u32 s42, s8, s14
	ds_read_b128 v[214:217], v185
	ds_read_b128 v[218:221], v185 offset:1024
	ds_read_b128 v[234:237], v185 offset:2048
	ds_read_b128 v[238:241], v185 offset:3072
	s_addc_u32 s43, s9, s15
	s_mov_b32 m0, s24
	s_add_u32 s98, s42, s34
	s_addc_u32 s99, s43, s35
	global_load_lds_dwordx4 v135, s[98:99]
	s_mov_b32 m0, s25
	s_add_u32 s98, s42, s64
	s_addc_u32 s99, s43, s65
	global_load_lds_dwordx4 v135, s[98:99]
	s_waitcnt vmcnt(10)
	s_barrier
	s_waitcnt lgkmcnt(0)
	s_waitcnt lgkmcnt(0)
	v_mfma_f32_16x16x32_bf16 v[94:97], v[214:217], v[168:171], v[94:97]
	v_mfma_f32_16x16x32_bf16 v[90:93], v[234:237], v[168:171], v[90:93]
	v_mfma_f32_16x16x32_bf16 v[86:89], v[214:217], v[176:179], v[86:89]
	v_mfma_f32_16x16x32_bf16 v[82:85], v[234:237], v[176:179], v[82:85]
	v_mfma_f32_16x16x32_bf16 v[78:81], v[214:217], v[198:201], v[78:81]
	v_mfma_f32_16x16x32_bf16 v[74:77], v[234:237], v[198:201], v[74:77]
	v_mfma_f32_16x16x32_bf16 v[70:73], v[214:217], v[206:209], v[70:73]
	v_mfma_f32_16x16x32_bf16 v[66:69], v[234:237], v[206:209], v[66:69]
	v_mfma_f32_16x16x32_bf16 v[94:97], v[218:221], v[172:175], v[94:97]
	v_mfma_f32_16x16x32_bf16 v[90:93], v[238:241], v[172:175], v[90:93]
	v_mfma_f32_16x16x32_bf16 v[86:89], v[218:221], v[194:197], v[86:89]
	v_mfma_f32_16x16x32_bf16 v[82:85], v[238:241], v[194:197], v[82:85]
	v_mfma_f32_16x16x32_bf16 v[78:81], v[218:221], v[202:205], v[78:81]
	v_mfma_f32_16x16x32_bf16 v[74:77], v[238:241], v[202:205], v[74:77]
	v_mfma_f32_16x16x32_bf16 v[70:73], v[218:221], v[210:213], v[70:73]
	v_mfma_f32_16x16x32_bf16 v[66:69], v[238:241], v[210:213], v[66:69]
	s_barrier
	ds_read_b128 v[168:171], v147 offset:16384
	ds_read_b128 v[172:175], v147 offset:17408
	ds_read_b128 v[176:179], v147 offset:18432
	ds_read_b128 v[194:197], v147 offset:19456
	ds_read_b128 v[198:201], v147 offset:20480
	ds_read_b128 v[202:205], v147 offset:21504
	ds_read_b128 v[206:209], v147 offset:22528
	ds_read_b128 v[210:213], v147 offset:23552
	s_mov_b32 m0, s26
	s_add_u32 s98, s40, s34
	s_addc_u32 s99, s41, s35
	global_load_lds_dwordx4 v135, s[98:99]
	s_mov_b32 m0, s27
	s_add_u32 s98, s40, s64
	s_addc_u32 s99, s41, s65
	global_load_lds_dwordx4 v135, s[98:99]
	s_barrier
	s_waitcnt lgkmcnt(0)
	s_waitcnt lgkmcnt(0)
	v_mfma_f32_16x16x32_bf16 v[62:65], v[152:155], v[168:171], v[62:65]
	v_mfma_f32_16x16x32_bf16 v[58:61], v[160:163], v[168:171], v[58:61]
	v_mfma_f32_16x16x32_bf16 v[54:57], v[152:155], v[176:179], v[54:57]
	v_mfma_f32_16x16x32_bf16 v[50:53], v[160:163], v[176:179], v[50:53]
	v_mfma_f32_16x16x32_bf16 v[46:49], v[152:155], v[198:201], v[46:49]
	v_mfma_f32_16x16x32_bf16 v[42:45], v[160:163], v[198:201], v[42:45]
	v_mfma_f32_16x16x32_bf16 v[38:41], v[152:155], v[206:209], v[38:41]
	v_mfma_f32_16x16x32_bf16 v[34:37], v[160:163], v[206:209], v[34:37]
	v_mfma_f32_16x16x32_bf16 v[62:65], v[156:159], v[172:175], v[62:65]
	v_mfma_f32_16x16x32_bf16 v[58:61], v[164:167], v[172:175], v[58:61]
	v_mfma_f32_16x16x32_bf16 v[54:57], v[156:159], v[194:197], v[54:57]
	v_mfma_f32_16x16x32_bf16 v[50:53], v[164:167], v[194:197], v[50:53]
	v_mfma_f32_16x16x32_bf16 v[46:49], v[156:159], v[202:205], v[46:49]
	v_mfma_f32_16x16x32_bf16 v[42:45], v[164:167], v[202:205], v[42:45]
	v_mfma_f32_16x16x32_bf16 v[38:41], v[156:159], v[210:213], v[38:41]
	v_mfma_f32_16x16x32_bf16 v[34:37], v[164:167], v[210:213], v[34:37]
	s_barrier
	s_mov_b32 m0, s28
	s_add_u32 s98, s42, s68
	s_addc_u32 s99, s43, s69
	global_load_lds_dwordx4 v135, s[98:99]
	s_mov_b32 m0, s29
	s_add_u32 s98, s42, s70
	s_addc_u32 s99, s43, s71
	global_load_lds_dwordx4 v135, s[98:99]
	s_waitcnt vmcnt(10)
	s_barrier
; #define LDA(dst, b, h) for (int m = 0; m < 4; ++m) for (int k = 0; k < 2; ++k) \
;     dst[m][k] = *reinterpret_cast<const bf16x8*>((char*)SA(b, h) + a_thr + (m * 2 + k) * 1024)
; #define LDB(dst, b, h) for (int n = 0; n < 2; ++n) for (int k = 0; k < 2; ++k) \
;     dst[n][k] = *reinterpret_cast<const bf16x8*>((char*)SB(b, h) + b_thr + (n * 2 + k) * 1024)
; #define MMA(ai, bj, At, Btf) do { __builtin_amdgcn_s_setprio(1); \
;     for (int m = 0; m < 4; ++m) for (int n = 0; n < 2; ++n) for (int k = 0; k < 2; ++k) \
;       acc[ai][bj][m][n] = __builtin_amdgcn_mfma_f32_16x16x32_bf16(Btf[n][k], At[m][k], acc[ai][bj][m][n], 0, 0, 0); \
;     __builtin_amdgcn_s_setprio(0); } while (0)
; #define WAIT_V(n) asm volatile("s_waitcnt vmcnt(" #n ")" ::: "memory")
; #define WAIT_L(n) asm volatile("s_waitcnt lgkmcnt(" #n ")" ::: "memory")
; #define BAR __builtin_amdgcn_s_barrier()
; #define SCHED __builtin_amdgcn_sched_barrier(0)
; template <bool OVL, bool PANEL = false, class Epi>
; __device__ __forceinline__ void gemm_phase(const bf16_t* __restrict__ A, long lda, const bf16_t* __restrict__ Bt, long ldb, int nM, int nN, int K,
;                                            const Epi& epi, bf16_t* shm, int w0) {
;     ...
;       WAIT_V(6); BAR; MMA(1, 1, At, B1); BAR;
;       LDB(B0, 1, 0); SCHED; LDA(At, 1, 0); STAGE(SA(0, 1), A, lda, aoff, brow + HALF, t + 2);
;       WAIT_L(8); BAR; WAIT_L(0); MMA(0, 0, At, B0); BAR; SCHED;
;       LDB(B1, 1, 1); STAGE(SB(1, 0), Bt, ldb, boff, bcol, t + 3);
;       BAR; WAIT_L(0); MMA(0, 1, At, B1); BAR;
;       LDA(At, 1, 1); STAGE(SA(1, 0), A, lda, aoff, brow, t + 3);
	v_mfma_f32_16x16x32_bf16 v[30:33], v[214:217], v[168:171], v[30:33]
	v_mfma_f32_16x16x32_bf16 v[26:29], v[234:237], v[168:171], v[26:29]
	v_mfma_f32_16x16x32_bf16 v[22:25], v[214:217], v[176:179], v[22:25]
	v_mfma_f32_16x16x32_bf16 v[18:21], v[234:237], v[176:179], v[18:21]
	v_mfma_f32_16x16x32_bf16 v[14:17], v[214:217], v[198:201], v[14:17]
	v_mfma_f32_16x16x32_bf16 v[10:13], v[234:237], v[198:201], v[10:13]
	v_mfma_f32_16x16x32_bf16 v[6:9], v[214:217], v[206:209], v[6:9]
	v_mfma_f32_16x16x32_bf16 v[2:5], v[234:237], v[206:209], v[2:5]
	v_mfma_f32_16x16x32_bf16 v[30:33], v[218:221], v[172:175], v[30:33]
	v_mfma_f32_16x16x32_bf16 v[26:29], v[238:241], v[172:175], v[26:29]
	v_mfma_f32_16x16x32_bf16 v[22:25], v[218:221], v[194:197], v[22:25]
	v_mfma_f32_16x16x32_bf16 v[18:21], v[238:241], v[194:197], v[18:21]
	v_mfma_f32_16x16x32_bf16 v[14:17], v[218:221], v[202:205], v[14:17]
	v_mfma_f32_16x16x32_bf16 v[10:13], v[238:241], v[202:205], v[10:13]
	v_mfma_f32_16x16x32_bf16 v[6:9], v[218:221], v[210:213], v[6:9]
	v_mfma_f32_16x16x32_bf16 v[2:5], v[238:241], v[210:213], v[2:5]
	s_barrier
	ds_read_b128 v[152:155], v186
	ds_read_b128 v[156:159], v186 offset:1024
	ds_read_b128 v[160:163], v186 offset:2048
	ds_read_b128 v[164:167], v186 offset:3072
	ds_read_b128 v[168:171], v147 offset:32768
	ds_read_b128 v[172:175], v147 offset:33792
	ds_read_b128 v[176:179], v147 offset:34816
	ds_read_b128 v[194:197], v147 offset:35840
	ds_read_b128 v[198:201], v147 offset:36864
	ds_read_b128 v[202:205], v147 offset:37888
	ds_read_b128 v[206:209], v147 offset:38912
	ds_read_b128 v[210:213], v147 offset:39936
	s_mov_b32 m0, s30
	s_add_u32 s98, s40, s68
	s_addc_u32 s99, s41, s69
	global_load_lds_dwordx4 v135, s[98:99]
	s_mov_b32 m0, s31
	s_add_u32 s98, s40, s70
	s_addc_u32 s99, s41, s71
	global_load_lds_dwordx4 v135, s[98:99]
	s_waitcnt lgkmcnt(8)
	s_waitcnt vmcnt(10)
	s_barrier
	s_waitcnt lgkmcnt(0)
	s_waitcnt lgkmcnt(0)
	v_mfma_f32_16x16x32_bf16 v[126:129], v[152:155], v[168:171], v[126:129]
	v_mfma_f32_16x16x32_bf16 v[122:125], v[160:163], v[168:171], v[122:125]
	v_mfma_f32_16x16x32_bf16 v[118:121], v[152:155], v[176:179], v[118:121]
	v_mfma_f32_16x16x32_bf16 v[114:117], v[160:163], v[176:179], v[114:117]
	v_mfma_f32_16x16x32_bf16 v[110:113], v[152:155], v[198:201], v[110:113]
	v_mfma_f32_16x16x32_bf16 v[106:109], v[160:163], v[198:201], v[106:109]
	v_mfma_f32_16x16x32_bf16 v[102:105], v[152:155], v[206:209], v[102:105]
	v_mfma_f32_16x16x32_bf16 v[98:101], v[160:163], v[206:209], v[98:101]
	v_mfma_f32_16x16x32_bf16 v[126:129], v[156:159], v[172:175], v[126:129]
	v_mfma_f32_16x16x32_bf16 v[122:125], v[164:167], v[172:175], v[122:125]
	v_mfma_f32_16x16x32_bf16 v[118:121], v[156:159], v[194:197], v[118:121]
	v_mfma_f32_16x16x32_bf16 v[114:117], v[164:167], v[194:197], v[114:117]
	v_mfma_f32_16x16x32_bf16 v[110:113], v[156:159], v[202:205], v[110:113]
	v_mfma_f32_16x16x32_bf16 v[106:109], v[164:167], v[202:205], v[106:109]
	v_mfma_f32_16x16x32_bf16 v[102:105], v[156:159], v[210:213], v[102:105]
	v_mfma_f32_16x16x32_bf16 v[98:101], v[164:167], v[210:213], v[98:101]
	s_barrier
	ds_read_b128 v[214:217], v187
	ds_read_b128 v[218:221], v187 offset:1024
	ds_read_b128 v[234:237], v187 offset:2048
	ds_read_b128 v[238:241], v187 offset:3072
	s_mov_b32 m0, s32
	s_add_u32 s98, s42, s94
	s_addc_u32 s99, s43, s95
	global_load_lds_dwordx4 v135, s[98:99]
	s_mov_b32 m0, s44
	s_add_u32 s98, s42, s72
	s_addc_u32 s99, s43, s73
	global_load_lds_dwordx4 v135, s[98:99]
	s_waitcnt vmcnt(10)
	s_barrier
	s_waitcnt lgkmcnt(0)
	s_waitcnt lgkmcnt(0)
	v_mfma_f32_16x16x32_bf16 v[94:97], v[214:217], v[168:171], v[94:97]
	v_mfma_f32_16x16x32_bf16 v[90:93], v[234:237], v[168:171], v[90:93]
	v_mfma_f32_16x16x32_bf16 v[86:89], v[214:217], v[176:179], v[86:89]
	v_mfma_f32_16x16x32_bf16 v[82:85], v[234:237], v[176:179], v[82:85]
	v_mfma_f32_16x16x32_bf16 v[78:81], v[214:217], v[198:201], v[78:81]
	v_mfma_f32_16x16x32_bf16 v[74:77], v[234:237], v[198:201], v[74:77]
	v_mfma_f32_16x16x32_bf16 v[70:73], v[214:217], v[206:209], v[70:73]
	v_mfma_f32_16x16x32_bf16 v[66:69], v[234:237], v[206:209], v[66:69]
	v_mfma_f32_16x16x32_bf16 v[94:97], v[218:221], v[172:175], v[94:97]
	v_mfma_f32_16x16x32_bf16 v[90:93], v[238:241], v[172:175], v[90:93]
	v_mfma_f32_16x16x32_bf16 v[86:89], v[218:221], v[194:197], v[86:89]
	v_mfma_f32_16x16x32_bf16 v[82:85], v[238:241], v[194:197], v[82:85]
	v_mfma_f32_16x16x32_bf16 v[78:81], v[218:221], v[202:205], v[78:81]
	v_mfma_f32_16x16x32_bf16 v[74:77], v[238:241], v[202:205], v[74:77]
	v_mfma_f32_16x16x32_bf16 v[70:73], v[218:221], v[210:213], v[70:73]
	v_mfma_f32_16x16x32_bf16 v[66:69], v[238:241], v[210:213], v[66:69]
	s_barrier
	ds_read_b128 v[168:171], v147 offset:49152
	ds_read_b128 v[172:175], v147 offset:50176
	ds_read_b128 v[176:179], v147 offset:51200
	ds_read_b128 v[194:197], v147 offset:52224
	ds_read_b128 v[198:201], v147 offset:53248
	ds_read_b128 v[202:205], v147 offset:54272
	ds_read_b128 v[206:209], v147 offset:55296
	ds_read_b128 v[210:213], v147 offset:56320
	s_mov_b32 m0, s45
	s_add_u32 s98, s40, s94
	s_addc_u32 s99, s41, s95
	global_load_lds_dwordx4 v135, s[98:99]
	s_mov_b32 m0, s46
	s_add_u32 s98, s40, s72
	s_addc_u32 s99, s41, s73
	global_load_lds_dwordx4 v135, s[98:99]
	s_barrier
; #define LDA(dst, b, h) for (int m = 0; m < 4; ++m) for (int k = 0; k < 2; ++k) \
;     dst[m][k] = *reinterpret_cast<const bf16x8*>((char*)SA(b, h) + a_thr + (m * 2 + k) * 1024)
; #define LDB(dst, b, h) for (int n = 0; n < 2; ++n) for (int k = 0; k < 2; ++k) \
;     dst[n][k] = *reinterpret_cast<const bf16x8*>((char*)SB(b, h) + b_thr + (n * 2 + k) * 1024)
; #define MMA(ai, bj, At, Btf) do { __builtin_amdgcn_s_setprio(1); \
;     for (int m = 0; m < 4; ++m) for (int n = 0; n < 2; ++n) for (int k = 0; k < 2; ++k) \
;       acc[ai][bj][m][n] = __builtin_amdgcn_mfma_f32_16x16x32_bf16(Btf[n][k], At[m][k], acc[ai][bj][m][n], 0, 0, 0); \
;     __builtin_amdgcn_s_setprio(0); } while (0)
; #define WAIT_V(n) asm volatile("s_waitcnt vmcnt(" #n ")" ::: "memory")
; #define WAIT_L(n) asm volatile("s_waitcnt lgkmcnt(" #n ")" ::: "memory")
; #define BAR __builtin_amdgcn_s_barrier()
; #define SCHED __builtin_amdgcn_sched_barrier(0)
; template <bool OVL, bool PANEL = false, class Epi>
; __device__ __forceinline__ void gemm_phase(const bf16_t* __restrict__ A, long lda, const bf16_t* __restrict__ Bt, long ldb, int nM, int nN, int K,
;                                            const Epi& epi, bf16_t* shm, int w0) {
;     ...
;       BAR; WAIT_L(0); MMA(1, 0, At, B0); BAR; SCHED;
;       STAGE(SB(1, 1), Bt, ldb, boff, bcol + HALF, t + 3);
;       WAIT_V(6); BAR; MMA(1, 1, At, B1); BAR;
;     }
;     { LDB(B0, 0, 0); LDA(At, 0, 0); STAGE(SA(1, 1), A, lda, aoff, brow + HALF, nt - 1);
;       BAR; WAIT_L(0); MMA(0, 0, At, B0); BAR;
;       LDB(B1, 0, 1); BAR; WAIT_L(0); MMA(0, 1, At, B1); BAR;
	s_waitcnt lgkmcnt(0)
	s_waitcnt lgkmcnt(0)
	v_mfma_f32_16x16x32_bf16 v[62:65], v[152:155], v[168:171], v[62:65]
	v_mfma_f32_16x16x32_bf16 v[58:61], v[160:163], v[168:171], v[58:61]
	v_mfma_f32_16x16x32_bf16 v[54:57], v[152:155], v[176:179], v[54:57]
	v_mfma_f32_16x16x32_bf16 v[50:53], v[160:163], v[176:179], v[50:53]
	v_mfma_f32_16x16x32_bf16 v[46:49], v[152:155], v[198:201], v[46:49]
	v_mfma_f32_16x16x32_bf16 v[42:45], v[160:163], v[198:201], v[42:45]
	v_mfma_f32_16x16x32_bf16 v[38:41], v[152:155], v[206:209], v[38:41]
	v_mfma_f32_16x16x32_bf16 v[34:37], v[160:163], v[206:209], v[34:37]
	v_mfma_f32_16x16x32_bf16 v[62:65], v[156:159], v[172:175], v[62:65]
	v_mfma_f32_16x16x32_bf16 v[58:61], v[164:167], v[172:175], v[58:61]
	v_mfma_f32_16x16x32_bf16 v[54:57], v[156:159], v[194:197], v[54:57]
	v_mfma_f32_16x16x32_bf16 v[50:53], v[164:167], v[194:197], v[50:53]
	v_mfma_f32_16x16x32_bf16 v[46:49], v[156:159], v[202:205], v[46:49]
	v_mfma_f32_16x16x32_bf16 v[42:45], v[164:167], v[202:205], v[42:45]
	v_mfma_f32_16x16x32_bf16 v[38:41], v[156:159], v[210:213], v[38:41]
	v_mfma_f32_16x16x32_bf16 v[34:37], v[164:167], v[210:213], v[34:37]
	s_barrier
	s_mov_b32 m0, s47
	s_add_u32 s98, s42, s18
	s_addc_u32 s99, s43, s19
	global_load_lds_dwordx4 v135, s[98:99]
	s_mov_b32 m0, s48
	s_add_u32 s98, s42, s20
	s_addc_u32 s99, s43, s21
	global_load_lds_dwordx4 v135, s[98:99]
	s_waitcnt vmcnt(10)
	s_barrier
	v_mfma_f32_16x16x32_bf16 v[30:33], v[214:217], v[168:171], v[30:33]
	v_mfma_f32_16x16x32_bf16 v[26:29], v[234:237], v[168:171], v[26:29]
	v_mfma_f32_16x16x32_bf16 v[22:25], v[214:217], v[176:179], v[22:25]
	v_mfma_f32_16x16x32_bf16 v[18:21], v[234:237], v[176:179], v[18:21]
	v_mfma_f32_16x16x32_bf16 v[14:17], v[214:217], v[198:201], v[14:17]
	v_mfma_f32_16x16x32_bf16 v[10:13], v[234:237], v[198:201], v[10:13]
	v_mfma_f32_16x16x32_bf16 v[6:9], v[214:217], v[206:209], v[6:9]
	v_mfma_f32_16x16x32_bf16 v[2:5], v[234:237], v[206:209], v[2:5]
	v_mfma_f32_16x16x32_bf16 v[30:33], v[218:221], v[172:175], v[30:33]
	v_mfma_f32_16x16x32_bf16 v[26:29], v[238:241], v[172:175], v[26:29]
	v_mfma_f32_16x16x32_bf16 v[22:25], v[218:221], v[194:197], v[22:25]
	v_mfma_f32_16x16x32_bf16 v[18:21], v[238:241], v[194:197], v[18:21]
	v_mfma_f32_16x16x32_bf16 v[14:17], v[218:221], v[202:205], v[14:17]
	v_mfma_f32_16x16x32_bf16 v[10:13], v[238:241], v[202:205], v[10:13]
	v_mfma_f32_16x16x32_bf16 v[6:9], v[218:221], v[210:213], v[6:9]
	v_mfma_f32_16x16x32_bf16 v[2:5], v[238:241], v[210:213], v[2:5]
	s_add_i32 s1, s1, 2
	s_add_u32 s14, s14, 0x100
	s_addc_u32 s15, s15, 0
	s_cmp_lt_u32 s1, 12
	s_barrier
	s_cbranch_scc1 .LBB0_1053
	s_waitcnt vmcnt(6)
	s_or_b32 s8, s0, 0x80
	s_ashr_i32 s9, s8, 31
	v_readlane_b32 s40, v252, 20
	s_lshl_b64 s[8:9], s[8:9], 11
	v_readlane_b32 s46, v252, 26
	v_add_u32_e32 v182, 16, v144
	v_readlane_b32 s47, v252, 27
	s_add_u32 s8, s46, s8
	v_add_u32_e32 v0, 0x10000, v182
	s_addc_u32 s9, s47, s9
	ds_read_b128 v[130:133], v0
	ds_read_b128 v[152:155], v0 offset:1024
	ds_read_b128 v[156:159], v0 offset:2048
	ds_read_b128 v[160:163], v0 offset:3072
	ds_read_b128 v[164:167], v147
	ds_read_b128 v[168:171], v147 offset:1024
	ds_read_b128 v[172:175], v147 offset:2048
	ds_read_b128 v[176:179], v147 offset:3072
	ds_read_b128 v[194:197], v147 offset:4096
	ds_read_b128 v[198:201], v147 offset:5120
	ds_read_b128 v[202:205], v147 offset:6144
	ds_read_b128 v[206:209], v147 offset:7168
	v_mov_b32_e32 v0, v135
	v_readfirstlane_b32 s1, v150
	v_lshl_add_u64 v[148:149], s[8:9], 0, v[0:1]
	s_mov_b64 s[8:9], 0x780
	v_lshl_add_u64 v[180:181], v[148:149], 0, s[8:9]
	s_mov_b32 m0, s1
	s_mov_b64 s[8:9], 0x20780
	v_readfirstlane_b32 s1, v151
	global_load_lds_dwordx4 v[180:181], off
	v_lshl_add_u64 v[148:149], v[148:149], 0, s[8:9]
	s_mov_b32 m0, s1
	v_readlane_b32 s41, v252, 21
	global_load_lds_dwordx4 v[148:149], off
	s_barrier
	s_waitcnt lgkmcnt(0)
	v_readlane_b32 s42, v252, 22
	v_readlane_b32 s43, v252, 23
	v_readlane_b32 s44, v252, 24
	v_readlane_b32 s45, v252, 25
	v_readlane_b32 s48, v252, 28
	v_readlane_b32 s49, v252, 29
	v_readlane_b32 s50, v252, 30
	v_readlane_b32 s51, v252, 31
	v_readlane_b32 s52, v252, 32
	v_readlane_b32 s53, v252, 33
	v_readlane_b32 s54, v252, 34
	v_readlane_b32 s55, v252, 35
	s_setprio 1
	s_waitcnt lgkmcnt(0)
	v_mfma_f32_16x16x32_bf16 v[126:129], v[130:133], v[164:167], v[126:129]
	v_mfma_f32_16x16x32_bf16 v[122:125], v[156:159], v[164:167], v[122:125]
	v_mfma_f32_16x16x32_bf16 v[118:121], v[130:133], v[172:175], v[118:121]
	v_mfma_f32_16x16x32_bf16 v[114:117], v[156:159], v[172:175], v[114:117]
	v_mfma_f32_16x16x32_bf16 v[110:113], v[130:133], v[194:197], v[110:113]
	v_mfma_f32_16x16x32_bf16 v[106:109], v[156:159], v[194:197], v[106:109]
	v_mfma_f32_16x16x32_bf16 v[102:105], v[130:133], v[202:205], v[102:105]
	v_mfma_f32_16x16x32_bf16 v[98:101], v[156:159], v[202:205], v[98:101]
	v_mfma_f32_16x16x32_bf16 v[126:129], v[152:155], v[168:171], v[126:129]
	v_mfma_f32_16x16x32_bf16 v[122:125], v[160:163], v[168:171], v[122:125]
	v_mfma_f32_16x16x32_bf16 v[118:121], v[152:155], v[176:179], v[118:121]
	v_mfma_f32_16x16x32_bf16 v[114:117], v[160:163], v[176:179], v[114:117]
	v_mfma_f32_16x16x32_bf16 v[110:113], v[152:155], v[198:201], v[110:113]
	v_mfma_f32_16x16x32_bf16 v[106:109], v[160:163], v[198:201], v[106:109]
	v_mfma_f32_16x16x32_bf16 v[102:105], v[152:155], v[206:209], v[102:105]
	v_mfma_f32_16x16x32_bf16 v[98:101], v[160:163], v[206:209], v[98:101]
	s_setprio 0
	v_add_u32_e32 v0, 0x14000, v182
	s_barrier
	ds_read_b128 v[148:151], v0
	ds_read_b128 v[210:213], v0 offset:1024
	ds_read_b128 v[214:217], v0 offset:2048
	ds_read_b128 v[218:221], v0 offset:3072
	s_barrier
; #define LDA(dst, b, h) for (int m = 0; m < 4; ++m) for (int k = 0; k < 2; ++k) \
;     dst[m][k] = *reinterpret_cast<const bf16x8*>((char*)SA(b, h) + a_thr + (m * 2 + k) * 1024)
; #define LDB(dst, b, h) for (int n = 0; n < 2; ++n) for (int k = 0; k < 2; ++k) \
;     dst[n][k] = *reinterpret_cast<const bf16x8*>((char*)SB(b, h) + b_thr + (n * 2 + k) * 1024)
; #define MMA(ai, bj, At, Btf) do { __builtin_amdgcn_s_setprio(1); \
;     for (int m = 0; m < 4; ++m) for (int n = 0; n < 2; ++n) for (int k = 0; k < 2; ++k) \
;       acc[ai][bj][m][n] = __builtin_amdgcn_mfma_f32_16x16x32_bf16(Btf[n][k], At[m][k], acc[ai][bj][m][n], 0, 0, 0); \
;     __builtin_amdgcn_s_setprio(0); } while (0)
; #define WAIT_V(n) asm volatile("s_waitcnt vmcnt(" #n ")" ::: "memory")
; #define WAIT_L(n) asm volatile("s_waitcnt lgkmcnt(" #n ")" ::: "memory")
; #define BAR __builtin_amdgcn_s_barrier()
; template <bool OVL, bool PANEL = false, class Epi>
; __device__ __forceinline__ void gemm_phase(const bf16_t* __restrict__ A, long lda, const bf16_t* __restrict__ Bt, long ldb, int nM, int nN, int K,
;                                            const Epi& epi, bf16_t* shm, int w0) {
;     ...
;       LDB(B1, 0, 1); BAR; WAIT_L(0); MMA(0, 1, At, B1); BAR;
;       LDA(At, 0, 1); WAIT_V(4); BAR; WAIT_L(0); MMA(1, 0, At, B0); MMA(1, 1, At, B1); BAR; }
;     { LDB(B0, 1, 0); LDA(At, 1, 0); WAIT_V(2); BAR; WAIT_L(0); MMA(0, 0, At, B0); BAR;
	s_waitcnt lgkmcnt(0)
	s_setprio 1
	s_waitcnt lgkmcnt(0)
	v_mfma_f32_16x16x32_bf16 v[94:97], v[148:151], v[164:167], v[94:97]
	v_mfma_f32_16x16x32_bf16 v[90:93], v[214:217], v[164:167], v[90:93]
	v_mfma_f32_16x16x32_bf16 v[86:89], v[148:151], v[172:175], v[86:89]
	v_mfma_f32_16x16x32_bf16 v[82:85], v[214:217], v[172:175], v[82:85]
	v_mfma_f32_16x16x32_bf16 v[78:81], v[148:151], v[194:197], v[78:81]
	v_mfma_f32_16x16x32_bf16 v[74:77], v[214:217], v[194:197], v[74:77]
	v_mfma_f32_16x16x32_bf16 v[70:73], v[148:151], v[202:205], v[70:73]
	v_mfma_f32_16x16x32_bf16 v[66:69], v[214:217], v[202:205], v[66:69]
	v_mfma_f32_16x16x32_bf16 v[94:97], v[210:213], v[168:171], v[94:97]
	v_mfma_f32_16x16x32_bf16 v[90:93], v[218:221], v[168:171], v[90:93]
	v_mfma_f32_16x16x32_bf16 v[86:89], v[210:213], v[176:179], v[86:89]
	v_mfma_f32_16x16x32_bf16 v[82:85], v[218:221], v[176:179], v[82:85]
	v_mfma_f32_16x16x32_bf16 v[78:81], v[210:213], v[198:201], v[78:81]
	v_mfma_f32_16x16x32_bf16 v[74:77], v[218:221], v[198:201], v[74:77]
	v_mfma_f32_16x16x32_bf16 v[70:73], v[210:213], v[206:209], v[70:73]
	v_mfma_f32_16x16x32_bf16 v[66:69], v[218:221], v[206:209], v[66:69]
	s_setprio 0
	s_barrier
	ds_read_b128 v[164:167], v147 offset:16384
	ds_read_b128 v[168:171], v147 offset:17408
	ds_read_b128 v[172:175], v147 offset:18432
	ds_read_b128 v[176:179], v147 offset:19456
	ds_read_b128 v[194:197], v147 offset:20480
	ds_read_b128 v[198:201], v147 offset:21504
	ds_read_b128 v[202:205], v147 offset:22528
	ds_read_b128 v[206:209], v147 offset:23552
	s_waitcnt vmcnt(4)
	s_barrier
	s_waitcnt lgkmcnt(0)
	s_setprio 1
	s_waitcnt lgkmcnt(0)
	v_mfma_f32_16x16x32_bf16 v[62:65], v[130:133], v[164:167], v[62:65]
	v_mfma_f32_16x16x32_bf16 v[58:61], v[156:159], v[164:167], v[58:61]
	v_mfma_f32_16x16x32_bf16 v[54:57], v[130:133], v[172:175], v[54:57]
	v_mfma_f32_16x16x32_bf16 v[50:53], v[156:159], v[172:175], v[50:53]
	v_mfma_f32_16x16x32_bf16 v[46:49], v[130:133], v[194:197], v[46:49]
	v_mfma_f32_16x16x32_bf16 v[42:45], v[156:159], v[194:197], v[42:45]
	v_mfma_f32_16x16x32_bf16 v[38:41], v[130:133], v[202:205], v[38:41]
	v_mfma_f32_16x16x32_bf16 v[34:37], v[156:159], v[202:205], v[34:37]
	v_mfma_f32_16x16x32_bf16 v[62:65], v[152:155], v[168:171], v[62:65]
	v_mfma_f32_16x16x32_bf16 v[58:61], v[160:163], v[168:171], v[58:61]
	v_mfma_f32_16x16x32_bf16 v[54:57], v[152:155], v[176:179], v[54:57]
	v_mfma_f32_16x16x32_bf16 v[50:53], v[160:163], v[176:179], v[50:53]
	v_mfma_f32_16x16x32_bf16 v[46:49], v[152:155], v[198:201], v[46:49]
	v_mfma_f32_16x16x32_bf16 v[42:45], v[160:163], v[198:201], v[42:45]
	v_mfma_f32_16x16x32_bf16 v[38:41], v[152:155], v[206:209], v[38:41]
	v_mfma_f32_16x16x32_bf16 v[34:37], v[160:163], v[206:209], v[34:37]
	s_setprio 0
	s_setprio 1
	v_mfma_f32_16x16x32_bf16 v[30:33], v[148:151], v[164:167], v[30:33]
	v_mfma_f32_16x16x32_bf16 v[26:29], v[214:217], v[164:167], v[26:29]
	v_mfma_f32_16x16x32_bf16 v[22:25], v[148:151], v[172:175], v[22:25]
	v_mfma_f32_16x16x32_bf16 v[18:21], v[214:217], v[172:175], v[18:21]
	v_mfma_f32_16x16x32_bf16 v[14:17], v[148:151], v[194:197], v[14:17]
	v_mfma_f32_16x16x32_bf16 v[10:13], v[214:217], v[194:197], v[10:13]
	v_mfma_f32_16x16x32_bf16 v[6:9], v[148:151], v[202:205], v[6:9]
	v_mfma_f32_16x16x32_bf16 v[2:5], v[214:217], v[202:205], v[2:5]
	v_mfma_f32_16x16x32_bf16 v[30:33], v[210:213], v[168:171], v[30:33]
	v_mfma_f32_16x16x32_bf16 v[26:29], v[218:221], v[168:171], v[26:29]
	v_mfma_f32_16x16x32_bf16 v[22:25], v[210:213], v[176:179], v[22:25]
	v_mfma_f32_16x16x32_bf16 v[18:21], v[218:221], v[176:179], v[18:21]
	v_mfma_f32_16x16x32_bf16 v[14:17], v[210:213], v[198:201], v[14:17]
	v_mfma_f32_16x16x32_bf16 v[10:13], v[218:221], v[198:201], v[10:13]
	v_mfma_f32_16x16x32_bf16 v[6:9], v[210:213], v[206:209], v[6:9]
	v_mfma_f32_16x16x32_bf16 v[2:5], v[218:221], v[206:209], v[2:5]
	s_setprio 0
	v_add_u32_e32 v0, 0x18000, v182
	s_barrier
	ds_read_b128 v[130:133], v0
	ds_read_b128 v[148:151], v0 offset:1024
	ds_read_b128 v[152:155], v0 offset:2048
	ds_read_b128 v[156:159], v0 offset:3072
	ds_read_b128 v[160:163], v147 offset:32768
	ds_read_b128 v[164:167], v147 offset:33792
	ds_read_b128 v[168:171], v147 offset:34816
	ds_read_b128 v[172:175], v147 offset:35840
	ds_read_b128 v[176:179], v147 offset:36864
	ds_read_b128 v[194:197], v147 offset:37888
	ds_read_b128 v[198:201], v147 offset:38912
	ds_read_b128 v[202:205], v147 offset:39936
	s_waitcnt vmcnt(2)
	s_barrier
; #define LDA(dst, b, h) for (int m = 0; m < 4; ++m) for (int k = 0; k < 2; ++k) \
;     dst[m][k] = *reinterpret_cast<const bf16x8*>((char*)SA(b, h) + a_thr + (m * 2 + k) * 1024)
; #define LDB(dst, b, h) for (int n = 0; n < 2; ++n) for (int k = 0; k < 2; ++k) \
;     dst[n][k] = *reinterpret_cast<const bf16x8*>((char*)SB(b, h) + b_thr + (n * 2 + k) * 1024)
; #define MMA(ai, bj, At, Btf) do { __builtin_amdgcn_s_setprio(1); \
;     for (int m = 0; m < 4; ++m) for (int n = 0; n < 2; ++n) for (int k = 0; k < 2; ++k) \
;       acc[ai][bj][m][n] = __builtin_amdgcn_mfma_f32_16x16x32_bf16(Btf[n][k], At[m][k], acc[ai][bj][m][n], 0, 0, 0); \
;     __builtin_amdgcn_s_setprio(0); } while (0)
; #define WAIT_V(n) asm volatile("s_waitcnt vmcnt(" #n ")" ::: "memory")
; #define WAIT_L(n) asm volatile("s_waitcnt lgkmcnt(" #n ")" ::: "memory")
; #define BAR __builtin_amdgcn_s_barrier()
; template <bool OVL, bool PANEL = false, class Epi>
; __device__ __forceinline__ void gemm_phase(const bf16_t* __restrict__ A, long lda, const bf16_t* __restrict__ Bt, long ldb, int nM, int nN, int K,
;                                            const Epi& epi, bf16_t* shm, int w0) {
;     ...
;     { LDB(B0, 1, 0); LDA(At, 1, 0); WAIT_V(2); BAR; WAIT_L(0); MMA(0, 0, At, B0); BAR;
;       LDB(B1, 1, 1); WAIT_V(0); BAR; WAIT_L(0); MMA(0, 1, At, B1); BAR;
;       LDA(At, 1, 1); BAR; WAIT_L(0); MMA(1, 0, At, B0); MMA(1, 1, At, B1); BAR; }
;     if (wr == 0) BAR;
	s_waitcnt lgkmcnt(0)
	s_setprio 1
	s_waitcnt lgkmcnt(0)
	v_mfma_f32_16x16x32_bf16 v[126:129], v[130:133], v[160:163], v[126:129]
	v_mfma_f32_16x16x32_bf16 v[122:125], v[152:155], v[160:163], v[122:125]
	v_mfma_f32_16x16x32_bf16 v[118:121], v[130:133], v[168:171], v[118:121]
	v_mfma_f32_16x16x32_bf16 v[114:117], v[152:155], v[168:171], v[114:117]
	v_mfma_f32_16x16x32_bf16 v[110:113], v[130:133], v[176:179], v[110:113]
	v_mfma_f32_16x16x32_bf16 v[106:109], v[152:155], v[176:179], v[106:109]
	v_mfma_f32_16x16x32_bf16 v[102:105], v[130:133], v[198:201], v[102:105]
	v_mfma_f32_16x16x32_bf16 v[98:101], v[152:155], v[198:201], v[98:101]
	v_mfma_f32_16x16x32_bf16 v[126:129], v[148:151], v[164:167], v[126:129]
	v_mfma_f32_16x16x32_bf16 v[122:125], v[156:159], v[164:167], v[122:125]
	v_mfma_f32_16x16x32_bf16 v[118:121], v[148:151], v[172:175], v[118:121]
	v_mfma_f32_16x16x32_bf16 v[114:117], v[156:159], v[172:175], v[114:117]
	v_mfma_f32_16x16x32_bf16 v[110:113], v[148:151], v[194:197], v[110:113]
	v_mfma_f32_16x16x32_bf16 v[106:109], v[156:159], v[194:197], v[106:109]
	v_mfma_f32_16x16x32_bf16 v[102:105], v[148:151], v[202:205], v[102:105]
	v_mfma_f32_16x16x32_bf16 v[98:101], v[156:159], v[202:205], v[98:101]
	s_setprio 0
	v_add_u32_e32 v0, 0x1c000, v182
	s_barrier
	ds_read_b128 v[206:209], v0
	ds_read_b128 v[210:213], v0 offset:1024
	ds_read_b128 v[214:217], v0 offset:2048
	ds_read_b128 v[218:221], v0 offset:3072
	s_waitcnt vmcnt(0)
	s_barrier
	s_waitcnt lgkmcnt(0)
	s_setprio 1
	s_waitcnt lgkmcnt(0)
	v_mfma_f32_16x16x32_bf16 v[94:97], v[206:209], v[160:163], v[94:97]
	v_mfma_f32_16x16x32_bf16 v[90:93], v[214:217], v[160:163], v[90:93]
	v_mfma_f32_16x16x32_bf16 v[86:89], v[206:209], v[168:171], v[86:89]
	v_mfma_f32_16x16x32_bf16 v[82:85], v[214:217], v[168:171], v[82:85]
	v_mfma_f32_16x16x32_bf16 v[78:81], v[206:209], v[176:179], v[78:81]
	v_mfma_f32_16x16x32_bf16 v[74:77], v[214:217], v[176:179], v[74:77]
	v_mfma_f32_16x16x32_bf16 v[70:73], v[206:209], v[198:201], v[70:73]
	v_mfma_f32_16x16x32_bf16 v[66:69], v[214:217], v[198:201], v[66:69]
	v_mfma_f32_16x16x32_bf16 v[94:97], v[210:213], v[164:167], v[94:97]
	v_mfma_f32_16x16x32_bf16 v[90:93], v[218:221], v[164:167], v[90:93]
	v_mfma_f32_16x16x32_bf16 v[86:89], v[210:213], v[172:175], v[86:89]
	v_mfma_f32_16x16x32_bf16 v[82:85], v[218:221], v[172:175], v[82:85]
	v_mfma_f32_16x16x32_bf16 v[78:81], v[210:213], v[194:197], v[78:81]
	v_mfma_f32_16x16x32_bf16 v[74:77], v[218:221], v[194:197], v[74:77]
	v_mfma_f32_16x16x32_bf16 v[70:73], v[210:213], v[202:205], v[70:73]
	v_mfma_f32_16x16x32_bf16 v[66:69], v[218:221], v[202:205], v[66:69]
	s_setprio 0
	s_barrier
	ds_read_b128 v[160:163], v147 offset:49152
	ds_read_b128 v[164:167], v147 offset:50176
	ds_read_b128 v[168:171], v147 offset:51200
	ds_read_b128 v[172:175], v147 offset:52224
	ds_read_b128 v[176:179], v147 offset:53248
	ds_read_b128 v[194:197], v147 offset:54272
	ds_read_b128 v[198:201], v147 offset:55296
	ds_read_b128 v[202:205], v147 offset:56320
	s_barrier
	s_waitcnt lgkmcnt(0)
	s_setprio 1
	s_waitcnt lgkmcnt(0)
	v_mfma_f32_16x16x32_bf16 v[62:65], v[130:133], v[160:163], v[62:65]
	v_mfma_f32_16x16x32_bf16 v[58:61], v[152:155], v[160:163], v[58:61]
	v_mfma_f32_16x16x32_bf16 v[54:57], v[130:133], v[168:171], v[54:57]
	v_mfma_f32_16x16x32_bf16 v[50:53], v[152:155], v[168:171], v[50:53]
	v_mfma_f32_16x16x32_bf16 v[46:49], v[130:133], v[176:179], v[46:49]
	v_mfma_f32_16x16x32_bf16 v[42:45], v[152:155], v[176:179], v[42:45]
	v_mfma_f32_16x16x32_bf16 v[38:41], v[130:133], v[198:201], v[38:41]
	v_mfma_f32_16x16x32_bf16 v[34:37], v[152:155], v[198:201], v[34:37]
	v_mfma_f32_16x16x32_bf16 v[62:65], v[148:151], v[164:167], v[62:65]
	v_mfma_f32_16x16x32_bf16 v[58:61], v[156:159], v[164:167], v[58:61]
	v_mfma_f32_16x16x32_bf16 v[54:57], v[148:151], v[172:175], v[54:57]
	v_mfma_f32_16x16x32_bf16 v[50:53], v[156:159], v[172:175], v[50:53]
	v_mfma_f32_16x16x32_bf16 v[46:49], v[148:151], v[194:197], v[46:49]
	v_mfma_f32_16x16x32_bf16 v[42:45], v[156:159], v[194:197], v[42:45]
	v_mfma_f32_16x16x32_bf16 v[38:41], v[148:151], v[202:205], v[38:41]
	v_mfma_f32_16x16x32_bf16 v[34:37], v[156:159], v[202:205], v[34:37]
	s_setprio 0
	s_setprio 1
	v_mfma_f32_16x16x32_bf16 v[30:33], v[206:209], v[160:163], v[30:33]
	v_mfma_f32_16x16x32_bf16 v[26:29], v[214:217], v[160:163], v[26:29]
	v_mfma_f32_16x16x32_bf16 v[22:25], v[206:209], v[168:171], v[22:25]
	v_mfma_f32_16x16x32_bf16 v[18:21], v[214:217], v[168:171], v[18:21]
	v_mfma_f32_16x16x32_bf16 v[14:17], v[206:209], v[176:179], v[14:17]
	v_mfma_f32_16x16x32_bf16 v[10:13], v[214:217], v[176:179], v[10:13]
	v_mfma_f32_16x16x32_bf16 v[6:9], v[206:209], v[198:201], v[6:9]
	v_mfma_f32_16x16x32_bf16 v[2:5], v[214:217], v[198:201], v[2:5]
	v_mfma_f32_16x16x32_bf16 v[30:33], v[210:213], v[164:167], v[30:33]
	v_mfma_f32_16x16x32_bf16 v[26:29], v[218:221], v[164:167], v[26:29]
	v_mfma_f32_16x16x32_bf16 v[22:25], v[210:213], v[172:175], v[22:25]
	v_mfma_f32_16x16x32_bf16 v[18:21], v[218:221], v[172:175], v[18:21]
	v_mfma_f32_16x16x32_bf16 v[14:17], v[210:213], v[194:197], v[14:17]
	v_mfma_f32_16x16x32_bf16 v[10:13], v[218:221], v[194:197], v[10:13]
	v_mfma_f32_16x16x32_bf16 v[6:9], v[210:213], v[202:205], v[6:9]
	v_mfma_f32_16x16x32_bf16 v[2:5], v[218:221], v[202:205], v[2:5]
	s_setprio 0
	s_barrier
	s_and_saveexec_b64 s[8:9], s[6:7]
	s_cbranch_execz .LBB0_1056
	s_barrier
